# v18 + residual-add epilogues: the per-row sum over the four lane groups by v_permlane16_swap / v_permlane32_swap instead of two ds_bpermute round trips per step (5 down / out-proj phases)
# speedup vs baseline: 1.0077x; 1.0006x over previous
; #define PG8_STAGE(bufoff, gbase, voff) do { _Pragma("unroll") for (int _i = 0; _i < 2; ++_i) \
;         __builtin_amdgcn_global_load_lds((const unsigned*)((const char*)(gbase) + (voff)[_i]), (PG8_LAS unsigned*)(lds + (bufoff) + ldsw + _i * 8192), 16, 0, 0); } while (0)
; #define PG8_LDA(dst, b, h) do { _Pragma("unroll") for (int m = 0; m < 4; ++m) _Pragma("unroll") for (int k = 0; k < 2; ++k) dst[m][k] = *(const PG8_LAS bf16x8*)(lds + PG8_SA(b, h) + aoff + m * 2048 + k * 1024); } while (0)
; #define PG8_LDB(dst, b, h) do { _Pragma("unroll") for (int n = 0; n < 2; ++n) _Pragma("unroll") for (int k = 0; k < 2; ++k) dst[n][k] = *(const PG8_LAS bf16x8*)(lds + PG8_SB(b, h) + boff + n * 2048 + k * 1024); } while (0)
; #define PG8_MMA(ai, bj, At, Bt) do { __builtin_amdgcn_s_setprio(1); _Pragma("unroll") for (int m = 0; m < 4; ++m) _Pragma("unroll") for (int n = 0; n < 2; ++n) _Pragma("unroll") for (int k = 0; k < 2; ++k) \
;         acc[ai][bj][m][n] = mma16<F16>(Bt[n][k], At[m][k], acc[ai][bj][m][n]); __builtin_amdgcn_s_setprio(0); } while (0)
; #define PG8_WAIT_V(n) asm volatile("s_waitcnt vmcnt(" #n ")" ::: "memory")
; #define PG8_WAIT_L(n) asm volatile("s_waitcnt lgkmcnt(" #n ")" ::: "memory")
; #define PG8_BAR __builtin_amdgcn_s_barrier()
; #define PG8_SCHED __builtin_amdgcn_sched_barrier(0)
; template <class Epi, class Sched, bool ALIGN_EPI = false, bool SP2 = false, bool F16 = false, bool TOKPERM = false>
; __device__ __forceinline__ void gemm_phase(PG8_LAS unsigned char* lds, const Gemm g, const Sched& S, const Epi& E, int wv) {
;     ...
;             PG8_LDB(B0, 0, 0); PG8_LDB(B1, 0, 1); PG8_SCHED; PG8_LDA(At, 0, 0); PG8_STAGE(PG8_SA(1, 1), a1 + hstep, voffA);
;             PG8_WAIT_V(8); PG8_WAIT_L(0); PG8_BAR; PG8_MMA(0, 0, At, B0); PG8_MMA(0, 1, At, B1); PG8_BAR; PG8_SCHED;
;             PG8_LDA(At, 0, 1); PG8_STAGE(PG8_SB(0, 0), b2, voffB); PG8_STAGE(PG8_SB(0, 1), b2 + hstep, voffB); PG8_STAGE(PG8_SA(0, 0), a2, voffA);
;             PG8_WAIT_V(8); PG8_WAIT_L(0); PG8_BAR; PG8_MMA(1, 0, At, B0); PG8_MMA(1, 1, At, B1); PG8_BAR; PG8_SCHED;
.LBB0_297:
	ds_read_b128 v[166:169], v149
	ds_read_b128 v[170:173], v150
	ds_read_b128 v[174:177], v151
	ds_read_b128 v[178:181], v152
	ds_read_b128 v[182:185], v153
	ds_read_b128 v[186:189], v154
	ds_read_b128 v[190:193], v155
	ds_read_b128 v[194:197], v156
	s_add_u32 s18, s16, 0x100
	s_addc_u32 s19, s17, 0
	s_cmp_eq_u32 s70, 40
	s_cselect_b32 s51, s9, s19
	s_cselect_b32 s50, s8, s18
	s_cselect_b32 s49, s11, s69
	s_cselect_b32 s48, s10, s68
	s_mov_b32 m0, s61
	v_lshl_add_u64 v[232:233], s[16:17], 0, v[138:139]
	ds_read_b128 v[198:201], v147
	ds_read_b128 v[202:205], v147 offset:1024
	ds_read_b128 v[206:209], v147 offset:2048
	ds_read_b128 v[210:213], v147 offset:3072
	ds_read_b128 v[214:217], v147 offset:4096
	ds_read_b128 v[218:221], v147 offset:5120
	ds_read_b128 v[222:225], v147 offset:6144
	ds_read_b128 v[228:231], v147 offset:7168
	global_load_lds_dwordx4 v[232:233], off
	v_lshl_add_u64 v[232:233], s[16:17], 0, v[140:141]
	s_mov_b32 m0, s62
	s_nop 0
	global_load_lds_dwordx4 v[232:233], off
	s_waitcnt vmcnt(8)
	s_waitcnt lgkmcnt(0)
	s_barrier
	s_setprio 1
	s_waitcnt lgkmcnt(0)
	v_mfma_f32_16x16x32_bf16 v[124:127], v[166:169], v[198:201], v[124:127]
	v_mfma_f32_16x16x32_bf16 v[120:123], v[174:177], v[198:201], v[120:123]
	v_mfma_f32_16x16x32_bf16 v[108:111], v[166:169], v[206:209], v[108:111]
	v_mfma_f32_16x16x32_bf16 v[104:107], v[174:177], v[206:209], v[104:107]
	v_mfma_f32_16x16x32_bf16 v[92:95], v[166:169], v[214:217], v[92:95]
	v_mfma_f32_16x16x32_bf16 v[88:91], v[174:177], v[214:217], v[88:91]
	v_mfma_f32_16x16x32_bf16 v[76:79], v[166:169], v[222:225], v[76:79]
	v_mfma_f32_16x16x32_bf16 v[72:75], v[174:177], v[222:225], v[72:75]
	v_mfma_f32_16x16x32_bf16 v[124:127], v[170:173], v[202:205], v[124:127]
	v_mfma_f32_16x16x32_bf16 v[120:123], v[178:181], v[202:205], v[120:123]
	v_mfma_f32_16x16x32_bf16 v[108:111], v[170:173], v[210:213], v[108:111]
	v_mfma_f32_16x16x32_bf16 v[104:107], v[178:181], v[210:213], v[104:107]
	v_mfma_f32_16x16x32_bf16 v[92:95], v[170:173], v[218:221], v[92:95]
	v_mfma_f32_16x16x32_bf16 v[88:91], v[178:181], v[218:221], v[88:91]
	v_mfma_f32_16x16x32_bf16 v[76:79], v[170:173], v[228:231], v[76:79]
	v_mfma_f32_16x16x32_bf16 v[72:75], v[178:181], v[228:231], v[72:75]
	s_setprio 0
	s_setprio 1
	v_mfma_f32_16x16x32_bf16 v[116:119], v[182:185], v[198:201], v[116:119]
	v_mfma_f32_16x16x32_bf16 v[112:115], v[190:193], v[198:201], v[112:115]
	v_mfma_f32_16x16x32_bf16 v[100:103], v[182:185], v[206:209], v[100:103]
	v_mfma_f32_16x16x32_bf16 v[96:99], v[190:193], v[206:209], v[96:99]
	v_mfma_f32_16x16x32_bf16 v[84:87], v[182:185], v[214:217], v[84:87]
	v_mfma_f32_16x16x32_bf16 v[80:83], v[190:193], v[214:217], v[80:83]
	v_mfma_f32_16x16x32_bf16 v[68:71], v[182:185], v[222:225], v[68:71]
	v_mfma_f32_16x16x32_bf16 v[64:67], v[190:193], v[222:225], v[64:67]
	v_mfma_f32_16x16x32_bf16 v[116:119], v[186:189], v[202:205], v[116:119]
	v_mfma_f32_16x16x32_bf16 v[112:115], v[194:197], v[202:205], v[112:115]
	v_mfma_f32_16x16x32_bf16 v[100:103], v[186:189], v[210:213], v[100:103]
	v_mfma_f32_16x16x32_bf16 v[96:99], v[194:197], v[210:213], v[96:99]
	v_mfma_f32_16x16x32_bf16 v[84:87], v[186:189], v[218:221], v[84:87]
	v_mfma_f32_16x16x32_bf16 v[80:83], v[194:197], v[218:221], v[80:83]
	v_mfma_f32_16x16x32_bf16 v[68:71], v[186:189], v[228:231], v[68:71]
	v_mfma_f32_16x16x32_bf16 v[64:67], v[194:197], v[228:231], v[64:67]
	s_setprio 0
	s_barrier
	s_mov_b32 m0, s3
	v_lshl_add_u64 v[232:233], s[48:49], 0, v[130:131]
	s_add_u32 s16, s48, 0xb0000
	ds_read_b128 v[198:201], v147 offset:16384
	ds_read_b128 v[202:205], v147 offset:17408
	ds_read_b128 v[206:209], v147 offset:18432
	ds_read_b128 v[210:213], v147 offset:19456
	ds_read_b128 v[214:217], v147 offset:20480
	ds_read_b128 v[218:221], v147 offset:21504
	ds_read_b128 v[222:225], v147 offset:22528
	ds_read_b128 v[228:231], v147 offset:23552
	global_load_lds_dwordx4 v[232:233], off
	v_lshl_add_u64 v[234:235], s[48:49], 0, v[134:135]
	s_mov_b32 m0, s21
	s_addc_u32 s17, s49, 0
	global_load_lds_dwordx4 v[234:235], off
	v_lshl_add_u64 v[236:237], s[16:17], 0, v[130:131]
	s_mov_b32 m0, s22
	v_lshl_add_u64 v[238:239], s[50:51], 0, v[132:133]
	global_load_lds_dwordx4 v[236:237], off
	v_lshl_add_u64 v[236:237], s[16:17], 0, v[134:135]
	s_mov_b32 m0, s23
	s_nop 0
	global_load_lds_dwordx4 v[236:237], off
	v_lshl_add_u64 v[236:237], s[50:51], 0, v[128:129]
	s_mov_b32 m0, s2
	s_nop 0
	global_load_lds_dwordx4 v[236:237], off
	s_mov_b32 m0, s33
	s_nop 0
	global_load_lds_dwordx4 v[238:239], off
	s_waitcnt vmcnt(8)
	s_waitcnt lgkmcnt(0)
	s_barrier
; #define PG8_STAGE(bufoff, gbase, voff) do { _Pragma("unroll") for (int _i = 0; _i < 2; ++_i) \
;         __builtin_amdgcn_global_load_lds((const unsigned*)((const char*)(gbase) + (voff)[_i]), (PG8_LAS unsigned*)(lds + (bufoff) + ldsw + _i * 8192), 16, 0, 0); } while (0)
; #define PG8_LDA(dst, b, h) do { _Pragma("unroll") for (int m = 0; m < 4; ++m) _Pragma("unroll") for (int k = 0; k < 2; ++k) dst[m][k] = *(const PG8_LAS bf16x8*)(lds + PG8_SA(b, h) + aoff + m * 2048 + k * 1024); } while (0)
; #define PG8_LDB(dst, b, h) do { _Pragma("unroll") for (int n = 0; n < 2; ++n) _Pragma("unroll") for (int k = 0; k < 2; ++k) dst[n][k] = *(const PG8_LAS bf16x8*)(lds + PG8_SB(b, h) + boff + n * 2048 + k * 1024); } while (0)
; #define PG8_MMA(ai, bj, At, Bt) do { __builtin_amdgcn_s_setprio(1); _Pragma("unroll") for (int m = 0; m < 4; ++m) _Pragma("unroll") for (int n = 0; n < 2; ++n) _Pragma("unroll") for (int k = 0; k < 2; ++k) \
;         acc[ai][bj][m][n] = mma16<F16>(Bt[n][k], At[m][k], acc[ai][bj][m][n]); __builtin_amdgcn_s_setprio(0); } while (0)
; #define PG8_WAIT_V(n) asm volatile("s_waitcnt vmcnt(" #n ")" ::: "memory")
; #define PG8_WAIT_L(n) asm volatile("s_waitcnt lgkmcnt(" #n ")" ::: "memory")
; #define PG8_BAR __builtin_amdgcn_s_barrier()
; #define PG8_SCHED __builtin_amdgcn_sched_barrier(0)
; template <class Epi, class Sched, bool ALIGN_EPI = false, bool SP2 = false, bool F16 = false, bool TOKPERM = false>
; __device__ __forceinline__ void gemm_phase(PG8_LAS unsigned char* lds, const Gemm g, const Sched& S, const Epi& E, int wv) {
;     ...
;             PG8_WAIT_V(8); PG8_WAIT_L(0); PG8_BAR; PG8_MMA(1, 0, At, B0); PG8_MMA(1, 1, At, B1); PG8_BAR; PG8_SCHED;
;             PG8_LDB(B0, 1, 0); PG8_LDB(B1, 1, 1); PG8_SCHED; PG8_LDA(At, 1, 0); PG8_STAGE(PG8_SA(0, 1), a2 + hstep, voffA);
;             PG8_WAIT_V(8); PG8_WAIT_L(0); PG8_BAR; PG8_MMA(0, 0, At, B0); PG8_MMA(0, 1, At, B1); PG8_BAR; PG8_SCHED;
	s_setprio 1
	s_waitcnt lgkmcnt(0)
	v_mfma_f32_16x16x32_bf16 v[60:63], v[166:169], v[198:201], v[60:63]
	v_mfma_f32_16x16x32_bf16 v[56:59], v[174:177], v[198:201], v[56:59]
	v_mfma_f32_16x16x32_bf16 v[44:47], v[166:169], v[206:209], v[44:47]
	v_mfma_f32_16x16x32_bf16 v[40:43], v[174:177], v[206:209], v[40:43]
	v_mfma_f32_16x16x32_bf16 v[28:31], v[166:169], v[214:217], v[28:31]
	v_mfma_f32_16x16x32_bf16 v[24:27], v[174:177], v[214:217], v[24:27]
	v_mfma_f32_16x16x32_bf16 v[12:15], v[166:169], v[222:225], v[12:15]
	v_mfma_f32_16x16x32_bf16 v[8:11], v[174:177], v[222:225], v[8:11]
	v_mfma_f32_16x16x32_bf16 v[60:63], v[170:173], v[202:205], v[60:63]
	v_mfma_f32_16x16x32_bf16 v[56:59], v[178:181], v[202:205], v[56:59]
	v_mfma_f32_16x16x32_bf16 v[44:47], v[170:173], v[210:213], v[44:47]
	v_mfma_f32_16x16x32_bf16 v[40:43], v[178:181], v[210:213], v[40:43]
	v_mfma_f32_16x16x32_bf16 v[28:31], v[170:173], v[218:221], v[28:31]
	v_mfma_f32_16x16x32_bf16 v[24:27], v[178:181], v[218:221], v[24:27]
	v_mfma_f32_16x16x32_bf16 v[12:15], v[170:173], v[228:231], v[12:15]
	v_mfma_f32_16x16x32_bf16 v[8:11], v[178:181], v[228:231], v[8:11]
	s_setprio 0
	s_setprio 1
	v_mfma_f32_16x16x32_bf16 v[52:55], v[182:185], v[198:201], v[52:55]
	v_mfma_f32_16x16x32_bf16 v[48:51], v[190:193], v[198:201], v[48:51]
	v_mfma_f32_16x16x32_bf16 v[36:39], v[182:185], v[206:209], v[36:39]
	v_mfma_f32_16x16x32_bf16 v[32:35], v[190:193], v[206:209], v[32:35]
	v_mfma_f32_16x16x32_bf16 v[20:23], v[182:185], v[214:217], v[20:23]
	v_mfma_f32_16x16x32_bf16 v[16:19], v[190:193], v[214:217], v[16:19]
	v_mfma_f32_16x16x32_bf16 v[4:7], v[182:185], v[222:225], v[4:7]
	v_mfma_f32_16x16x32_bf16 v[0:3], v[190:193], v[222:225], v[0:3]
	v_mfma_f32_16x16x32_bf16 v[52:55], v[186:189], v[202:205], v[52:55]
	v_mfma_f32_16x16x32_bf16 v[48:51], v[194:197], v[202:205], v[48:51]
	v_mfma_f32_16x16x32_bf16 v[36:39], v[186:189], v[210:213], v[36:39]
	v_mfma_f32_16x16x32_bf16 v[32:35], v[194:197], v[210:213], v[32:35]
	v_mfma_f32_16x16x32_bf16 v[20:23], v[186:189], v[218:221], v[20:23]
	v_mfma_f32_16x16x32_bf16 v[16:19], v[194:197], v[218:221], v[16:19]
	v_mfma_f32_16x16x32_bf16 v[4:7], v[186:189], v[228:231], v[4:7]
	v_mfma_f32_16x16x32_bf16 v[0:3], v[194:197], v[228:231], v[0:3]
	s_setprio 0
	s_barrier
	ds_read_b128 v[166:169], v157
	ds_read_b128 v[170:173], v158
	ds_read_b128 v[174:177], v159
	ds_read_b128 v[178:181], v160
	ds_read_b128 v[182:185], v161
	ds_read_b128 v[186:189], v162
	ds_read_b128 v[190:193], v163
	ds_read_b128 v[194:197], v164
	s_add_u32 s16, s50, 0xb0000
	s_addc_u32 s17, s51, 0
	s_mov_b32 m0, s36
	v_lshl_add_u64 v[240:241], s[16:17], 0, v[128:129]
	ds_read_b128 v[198:201], v147 offset:32768
	ds_read_b128 v[202:205], v147 offset:33792
	ds_read_b128 v[206:209], v147 offset:34816
	ds_read_b128 v[210:213], v147 offset:35840
	ds_read_b128 v[214:217], v147 offset:36864
	ds_read_b128 v[218:221], v147 offset:37888
	ds_read_b128 v[222:225], v147 offset:38912
	ds_read_b128 v[228:231], v147 offset:39936
	global_load_lds_dwordx4 v[240:241], off
	v_lshl_add_u64 v[240:241], s[16:17], 0, v[132:133]
	s_mov_b32 m0, s37
	s_nop 0
	global_load_lds_dwordx4 v[240:241], off
	s_waitcnt vmcnt(8)
	s_waitcnt lgkmcnt(0)
	s_barrier
	s_setprio 1
	s_waitcnt lgkmcnt(0)
	v_mfma_f32_16x16x32_bf16 v[124:127], v[166:169], v[198:201], v[124:127]
	v_mfma_f32_16x16x32_bf16 v[120:123], v[174:177], v[198:201], v[120:123]
	v_mfma_f32_16x16x32_bf16 v[108:111], v[166:169], v[206:209], v[108:111]
	v_mfma_f32_16x16x32_bf16 v[104:107], v[174:177], v[206:209], v[104:107]
	v_mfma_f32_16x16x32_bf16 v[92:95], v[166:169], v[214:217], v[92:95]
	v_mfma_f32_16x16x32_bf16 v[88:91], v[174:177], v[214:217], v[88:91]
	v_mfma_f32_16x16x32_bf16 v[76:79], v[166:169], v[222:225], v[76:79]
	v_mfma_f32_16x16x32_bf16 v[72:75], v[174:177], v[222:225], v[72:75]
	v_mfma_f32_16x16x32_bf16 v[124:127], v[170:173], v[202:205], v[124:127]
	v_mfma_f32_16x16x32_bf16 v[120:123], v[178:181], v[202:205], v[120:123]
	v_mfma_f32_16x16x32_bf16 v[108:111], v[170:173], v[210:213], v[108:111]
	v_mfma_f32_16x16x32_bf16 v[104:107], v[178:181], v[210:213], v[104:107]
	v_mfma_f32_16x16x32_bf16 v[92:95], v[170:173], v[218:221], v[92:95]
	v_mfma_f32_16x16x32_bf16 v[88:91], v[178:181], v[218:221], v[88:91]
	v_mfma_f32_16x16x32_bf16 v[76:79], v[170:173], v[228:231], v[76:79]
	v_mfma_f32_16x16x32_bf16 v[72:75], v[178:181], v[228:231], v[72:75]
	s_setprio 0
	s_setprio 1
	v_mfma_f32_16x16x32_bf16 v[116:119], v[182:185], v[198:201], v[116:119]
	v_mfma_f32_16x16x32_bf16 v[112:115], v[190:193], v[198:201], v[112:115]
	v_mfma_f32_16x16x32_bf16 v[100:103], v[182:185], v[206:209], v[100:103]
	v_mfma_f32_16x16x32_bf16 v[96:99], v[190:193], v[206:209], v[96:99]
	v_mfma_f32_16x16x32_bf16 v[84:87], v[182:185], v[214:217], v[84:87]
	v_mfma_f32_16x16x32_bf16 v[80:83], v[190:193], v[214:217], v[80:83]
	v_mfma_f32_16x16x32_bf16 v[68:71], v[182:185], v[222:225], v[68:71]
	v_mfma_f32_16x16x32_bf16 v[64:67], v[190:193], v[222:225], v[64:67]
	v_mfma_f32_16x16x32_bf16 v[116:119], v[186:189], v[202:205], v[116:119]
	v_mfma_f32_16x16x32_bf16 v[112:115], v[194:197], v[202:205], v[112:115]
	v_mfma_f32_16x16x32_bf16 v[100:103], v[186:189], v[210:213], v[100:103]
	v_mfma_f32_16x16x32_bf16 v[96:99], v[194:197], v[210:213], v[96:99]
	v_mfma_f32_16x16x32_bf16 v[84:87], v[186:189], v[218:221], v[84:87]
	v_mfma_f32_16x16x32_bf16 v[80:83], v[194:197], v[218:221], v[80:83]
	v_mfma_f32_16x16x32_bf16 v[68:71], v[186:189], v[228:231], v[68:71]
	v_mfma_f32_16x16x32_bf16 v[64:67], v[194:197], v[228:231], v[64:67]
	s_setprio 0
	s_barrier
; #define PG8_STAGE(bufoff, gbase, voff) do { _Pragma("unroll") for (int _i = 0; _i < 2; ++_i) \
;         __builtin_amdgcn_global_load_lds((const unsigned*)((const char*)(gbase) + (voff)[_i]), (PG8_LAS unsigned*)(lds + (bufoff) + ldsw + _i * 8192), 16, 0, 0); } while (0)
; #define PG8_LDA(dst, b, h) do { _Pragma("unroll") for (int m = 0; m < 4; ++m) _Pragma("unroll") for (int k = 0; k < 2; ++k) dst[m][k] = *(const PG8_LAS bf16x8*)(lds + PG8_SA(b, h) + aoff + m * 2048 + k * 1024); } while (0)
; #define PG8_MMA(ai, bj, At, Bt) do { __builtin_amdgcn_s_setprio(1); _Pragma("unroll") for (int m = 0; m < 4; ++m) _Pragma("unroll") for (int n = 0; n < 2; ++n) _Pragma("unroll") for (int k = 0; k < 2; ++k) \
;         acc[ai][bj][m][n] = mma16<F16>(Bt[n][k], At[m][k], acc[ai][bj][m][n]); __builtin_amdgcn_s_setprio(0); } while (0)
; #define PG8_WAIT_V(n) asm volatile("s_waitcnt vmcnt(" #n ")" ::: "memory")
; #define PG8_WAIT_L(n) asm volatile("s_waitcnt lgkmcnt(" #n ")" ::: "memory")
; #define PG8_BAR __builtin_amdgcn_s_barrier()
; #define PG8_SCHED __builtin_amdgcn_sched_barrier(0)
; template <class Epi, class Sched, bool ALIGN_EPI = false, bool SP2 = false, bool F16 = false, bool TOKPERM = false>
; __device__ __forceinline__ void gemm_phase(PG8_LAS unsigned char* lds, const Gemm g, const Sched& S, const Epi& E, int wv) {
;     ...
;             PG8_LDA(At, 1, 1); PG8_STAGE(PG8_SB(1, 0), b3, voffB); PG8_STAGE(PG8_SB(1, 1), b3 + hstep, voffB); PG8_STAGE(PG8_SA(1, 0), a3, voffA);
;             PG8_WAIT_V(8); PG8_WAIT_L(0); PG8_BAR; PG8_MMA(1, 0, At, B0); PG8_MMA(1, 1, At, B1); PG8_BAR; PG8_SCHED;
;   __device__ __forceinline__ void operator()(const pg8::f32x4 (&acc)[2][2][4][2], const pg8::Unit& u, int wr, int wc, int fr, int fq) const {
;     ...
;     const int row0 = u.pm * 256 + wr * 64 + fr + z, colb = u.pn * 256 + wc * 32 + 8 * fq + z;
; #pragma unroll
;     for (int ai = 0; ai < 2; ++ai)
; #pragma unroll
;       for (int m = 0; m < 4; ++m) {
;         const int tok = row0 + ai * 128 + m * 16; float ss = 0.f;
; #pragma unroll
;         for (int bj = 0; bj < 2; ++bj) {
;           const unsigned off = (unsigned)tok * DM + colb + 128 * bj;
;           f8_t n = __builtin_convertvector(*(const h8_t*)(x16 + off), f8_t);
	s_mov_b32 m0, s45
	v_lshl_add_u64 v[232:233], v[232:233], 0, s[12:13]
	s_add_u32 s16, s48, 0xb0080
	ds_read_b128 v[198:201], v147 offset:49152
	ds_read_b128 v[202:205], v147 offset:50176
	ds_read_b128 v[206:209], v147 offset:51200
	ds_read_b128 v[210:213], v147 offset:52224
	ds_read_b128 v[214:217], v147 offset:53248
	ds_read_b128 v[218:221], v147 offset:54272
	ds_read_b128 v[222:225], v147 offset:55296
	ds_read_b128 v[228:231], v147 offset:56320
	global_load_lds_dwordx4 v[232:233], off
	v_lshl_add_u64 v[232:233], v[234:235], 0, s[12:13]
	s_mov_b32 m0, s52
	s_addc_u32 s17, s49, 0
	global_load_lds_dwordx4 v[232:233], off
	v_lshl_add_u64 v[232:233], s[16:17], 0, v[130:131]
	s_mov_b32 m0, s55
	s_nop 0
	global_load_lds_dwordx4 v[232:233], off
	v_lshl_add_u64 v[232:233], s[16:17], 0, v[134:135]
	s_mov_b32 m0, s56
	s_nop 0
	global_load_lds_dwordx4 v[232:233], off
	v_lshl_add_u64 v[232:233], v[236:237], 0, s[12:13]
	s_mov_b32 m0, s53
	s_nop 0
	global_load_lds_dwordx4 v[232:233], off
	v_lshl_add_u64 v[232:233], v[238:239], 0, s[12:13]
	s_mov_b32 m0, s54
	s_nop 0
	global_load_lds_dwordx4 v[232:233], off
	s_waitcnt vmcnt(8)
	s_waitcnt lgkmcnt(0)
	s_barrier
	s_setprio 1
	s_waitcnt lgkmcnt(0)
	v_mfma_f32_16x16x32_bf16 v[60:63], v[166:169], v[198:201], v[60:63]
	v_mfma_f32_16x16x32_bf16 v[56:59], v[174:177], v[198:201], v[56:59]
	v_mfma_f32_16x16x32_bf16 v[44:47], v[166:169], v[206:209], v[44:47]
	v_mfma_f32_16x16x32_bf16 v[40:43], v[174:177], v[206:209], v[40:43]
	v_mfma_f32_16x16x32_bf16 v[28:31], v[166:169], v[214:217], v[28:31]
	v_mfma_f32_16x16x32_bf16 v[24:27], v[174:177], v[214:217], v[24:27]
	v_mfma_f32_16x16x32_bf16 v[12:15], v[166:169], v[222:225], v[12:15]
	v_mfma_f32_16x16x32_bf16 v[8:11], v[174:177], v[222:225], v[8:11]
	v_mfma_f32_16x16x32_bf16 v[60:63], v[170:173], v[202:205], v[60:63]
	v_mfma_f32_16x16x32_bf16 v[56:59], v[178:181], v[202:205], v[56:59]
	v_mfma_f32_16x16x32_bf16 v[44:47], v[170:173], v[210:213], v[44:47]
	v_mfma_f32_16x16x32_bf16 v[40:43], v[178:181], v[210:213], v[40:43]
	v_mfma_f32_16x16x32_bf16 v[28:31], v[170:173], v[218:221], v[28:31]
	v_mfma_f32_16x16x32_bf16 v[24:27], v[178:181], v[218:221], v[24:27]
	v_mfma_f32_16x16x32_bf16 v[12:15], v[170:173], v[228:231], v[12:15]
	v_mfma_f32_16x16x32_bf16 v[8:11], v[178:181], v[228:231], v[8:11]
	s_setprio 0
	s_setprio 1
	v_mfma_f32_16x16x32_bf16 v[52:55], v[182:185], v[198:201], v[52:55]
	v_mfma_f32_16x16x32_bf16 v[48:51], v[190:193], v[198:201], v[48:51]
	v_mfma_f32_16x16x32_bf16 v[36:39], v[182:185], v[206:209], v[36:39]
	v_mfma_f32_16x16x32_bf16 v[32:35], v[190:193], v[206:209], v[32:35]
	v_mfma_f32_16x16x32_bf16 v[20:23], v[182:185], v[214:217], v[20:23]
	v_mfma_f32_16x16x32_bf16 v[16:19], v[190:193], v[214:217], v[16:19]
	v_mfma_f32_16x16x32_bf16 v[4:7], v[182:185], v[222:225], v[4:7]
	v_mfma_f32_16x16x32_bf16 v[0:3], v[190:193], v[222:225], v[0:3]
	v_mfma_f32_16x16x32_bf16 v[52:55], v[186:189], v[202:205], v[52:55]
	v_mfma_f32_16x16x32_bf16 v[48:51], v[194:197], v[202:205], v[48:51]
	v_mfma_f32_16x16x32_bf16 v[36:39], v[186:189], v[210:213], v[36:39]
	v_mfma_f32_16x16x32_bf16 v[32:35], v[194:197], v[210:213], v[32:35]
	v_mfma_f32_16x16x32_bf16 v[20:23], v[186:189], v[218:221], v[20:23]
	v_mfma_f32_16x16x32_bf16 v[16:19], v[194:197], v[218:221], v[16:19]
	v_mfma_f32_16x16x32_bf16 v[4:7], v[186:189], v[228:231], v[4:7]
	v_mfma_f32_16x16x32_bf16 v[0:3], v[194:197], v[228:231], v[0:3]
	s_setprio 0
	s_barrier
	s_add_i32 s70, s70, 2
	s_add_u32 s68, s68, 0x100
	s_addc_u32 s69, s69, 0
	s_cmp_gt_u32 s70, 41
	s_mov_b64 s[16:17], s[18:19]
	s_cbranch_scc0 .LBB0_297
	s_lshl_b32 s16, s66, 8
	v_lshl_or_b32 v166, s65, 8, v148
	v_mov_b32 v136, 0
	v_xor_b32_e32 v169, 32, v165
	v_add3_u32 v167, s16, v146, v136
	v_add_u32_e32 v168, v166, v136
	v_lshl_add_u32 v136, v167, 10, v168
	v_lshl_add_u64 v[178:179], v[136:137], 1, s[40:41]
	v_add_u32_e32 v136, 0x80, v136
	global_load_dwordx4 v[170:173], v[178:179], off
	v_lshl_add_u64 v[180:181], v[136:137], 1, s[40:41]
	global_load_dwordx4 v[174:177], v[180:181], off
	v_add_u32_e32 v136, 16, v167
	v_lshl_add_u32 v136, v136, 10, v168
	v_lshl_add_u64 v[224:225], v[136:137], 1, s[40:41]
	v_add_u32_e32 v136, 0x80, v136
	global_load_dwordx4 v[192:195], v[224:225], off
	v_lshl_add_u64 v[248:249], v[136:137], 1, s[40:41]
	global_load_dwordx4 v[196:199], v[248:249], off
	v_add_u32_e32 v136, 32, v167
	v_lshl_add_u32 v136, v136, 10, v168
	v_lshl_add_u64 v[224:225], v[136:137], 1, s[40:41]
	v_add_u32_e32 v136, 0x80, v136
	global_load_dwordx4 v[200:203], v[224:225], off
	v_lshl_add_u64 v[248:249], v[136:137], 1, s[40:41]
	global_load_dwordx4 v[204:207], v[248:249], off
	v_add_u32_e32 v136, 48, v167
	v_lshl_add_u32 v136, v136, 10, v168
	v_lshl_add_u64 v[224:225], v[136:137], 1, s[40:41]
	v_add_u32_e32 v136, 0x80, v136
	global_load_dwordx4 v[208:211], v[224:225], off
	v_lshl_add_u64 v[248:249], v[136:137], 1, s[40:41]
	global_load_dwordx4 v[212:215], v[248:249], off
	v_add_u32_e32 v136, 0x80, v167
	v_lshl_add_u32 v136, v136, 10, v168
	v_lshl_add_u64 v[224:225], v[136:137], 1, s[40:41]
	v_add_u32_e32 v136, 0x80, v136
	global_load_dwordx4 v[216:219], v[224:225], off
	v_lshl_add_u64 v[248:249], v[136:137], 1, s[40:41]
	global_load_dwordx4 v[220:223], v[248:249], off
	v_add_u32_e32 v136, 0x90, v167
	v_lshl_add_u32 v136, v136, 10, v168
	v_lshl_add_u64 v[224:225], v[136:137], 1, s[40:41]
	v_add_u32_e32 v136, 0x80, v136
	global_load_dwordx4 v[228:231], v[224:225], off
	v_lshl_add_u64 v[248:249], v[136:137], 1, s[40:41]
	global_load_dwordx4 v[244:247], v[248:249], off
	v_and_b32_e32 v166, 64, v165
	v_xor_b32_e32 v136, 16, v165
	v_add_u32_e32 v166, 64, v166
	v_cmp_lt_i32_e32 vcc, v136, v166
	s_lshl_b32 s16, s65, 2
	s_or_b32 s18, s16, s44
	v_cndmask_b32_e32 v136, v165, v136, vcc
	v_cmp_lt_i32_e32 vcc, v169, v166
	v_lshlrev_b32_e32 v166, 2, v136
	s_waitcnt vmcnt(10)
;   __device__ __forceinline__ void operator()(const pg8::f32x4 (&acc)[2][2][4][2], const pg8::Unit& u, int wr, int wc, int fr, int fq) const {
;     ...
;         const int tok = row0 + ai * 128 + m * 16; float ss = 0.f;
; #pragma unroll
;         for (int bj = 0; bj < 2; ++bj) {
;           const unsigned off = (unsigned)tok * DM + colb + 128 * bj;
;           f8_t n = __builtin_convertvector(*(const h8_t*)(x16 + off), f8_t);
; #pragma unroll
;           for (int c = 0; c < 4; ++c) { n[c] += sc * acc[ai][bj][m][0][c]; n[4 + c] += sc * acc[ai][bj][m][1][c]; }
;           if (aux) {
;             *(h8_t*)(x16 + off) = __builtin_convertvector(n, h8_t);
;             ss += ((n[0] * n[0] + n[1] * n[1]) + (n[2] * n[2] + n[3] * n[3])) + ((n[4] * n[4] + n[5] * n[5]) + (n[6] * n[6] + n[7] * n[7]));
;           } else {
;             *(f32x4*)(xout + off) = (f32x4){n[0], n[1], n[2], n[3]}; *(f32x4*)(xout + off + 4) = (f32x4){n[4], n[5], n[6], n[7]};
;           }
;         }
;         if (aux) { ss += __shfl_xor(ss, 16); ss += __shfl_xor(ss, 32); if (fq == 0) ssq[(unsigned)tok * 16 + u.pn * 4 + wc] = ss; }
	v_cvt_f32_f16_e32 v182, v173
	v_cvt_f32_f16_sdwa v183, v173 dst_sel:DWORD dst_unused:UNUSED_PAD src0_sel:WORD_1
	v_cvt_f32_f16_e32 v184, v171
	v_cvt_f32_f16_sdwa v185, v171 dst_sel:DWORD dst_unused:UNUSED_PAD src0_sel:WORD_1
	v_cvt_f32_f16_e32 v186, v172
	v_cvt_f32_f16_sdwa v187, v172 dst_sel:DWORD dst_unused:UNUSED_PAD src0_sel:WORD_1
	v_cvt_f32_f16_e32 v172, v170
	v_cvt_f32_f16_sdwa v173, v170 dst_sel:DWORD dst_unused:UNUSED_PAD src0_sel:WORD_1
	v_cvt_f32_f16_e32 v170, v177
	v_cvt_f32_f16_sdwa v171, v177 dst_sel:DWORD dst_unused:UNUSED_PAD src0_sel:WORD_1
	v_cvt_f32_f16_e32 v188, v175
	v_cvt_f32_f16_sdwa v189, v175 dst_sel:DWORD dst_unused:UNUSED_PAD src0_sel:WORD_1
	v_cvt_f32_f16_e32 v190, v176
	v_cvt_f32_f16_sdwa v191, v176 dst_sel:DWORD dst_unused:UNUSED_PAD src0_sel:WORD_1
	v_cvt_f32_f16_e32 v176, v174
	v_cvt_f32_f16_sdwa v177, v174 dst_sel:DWORD dst_unused:UNUSED_PAD src0_sel:WORD_1
	v_pk_fma_f32 v[124:125], v[124:125], 0.5, v[172:173] op_sel_hi:[1,0,1]
	v_pk_fma_f32 v[172:173], v[120:121], 0.5, v[186:187] op_sel_hi:[1,0,1]
	v_pk_fma_f32 v[126:127], v[126:127], 0.5, v[184:185] op_sel_hi:[1,0,1]
	v_pk_fma_f32 v[122:123], v[122:123], 0.5, v[182:183] op_sel_hi:[1,0,1]
	v_cvt_pk_f16_f32 v120, v172, v173
	v_cvt_pk_f16_f32 v121, v122, v123
	v_pk_mul_f32 v[174:175], v[124:125], v[124:125]
	v_pk_mul_f32 v[182:183], v[126:127], v[126:127]
	v_pk_mul_f32 v[172:173], v[172:173], v[172:173]
	v_pk_mul_f32 v[122:123], v[122:123], v[122:123]
	v_pk_fma_f32 v[176:177], v[116:117], 0.5, v[176:177] op_sel_hi:[1,0,1]
	v_pk_fma_f32 v[116:117], v[112:113], 0.5, v[190:191] op_sel_hi:[1,0,1]
	v_pk_fma_f32 v[184:185], v[118:119], 0.5, v[188:189] op_sel_hi:[1,0,1]
	v_pk_fma_f32 v[112:113], v[114:115], 0.5, v[170:171] op_sel_hi:[1,0,1]
	v_pk_mul_f32 v[114:115], v[176:177], v[176:177]
	v_pk_mul_f32 v[118:119], v[184:185], v[184:185]
	v_pk_mul_f32 v[170:171], v[116:117], v[116:117]
	v_pk_mul_f32 v[186:187], v[112:113], v[112:113]
	v_add_f32_e32 v122, v122, v123
	v_add_f32_e32 v123, v172, v173
	v_add_f32_e32 v136, v182, v183
	v_add_f32_e32 v172, v174, v175
	v_add_f32_e32 v122, v123, v122
	v_add_f32_e32 v123, v172, v136
	v_add_f32_e32 v136, v186, v187
	v_add_f32_e32 v170, v170, v171
	v_add_f32_e32 v118, v118, v119
	v_add_f32_e32 v114, v114, v115
	v_add_f32_e32 v119, v170, v136
	v_add_f32_e32 v114, v114, v118
	v_add_f32_e32 v115, v123, v122
	v_add_f32_e32 v114, v114, v119
	v_add_f32_e32 v114, v115, v114
	v_mov_b32_e32 v115, v114
	s_nop 1
	v_permlane16_swap_b32_e32 v114, v115
	v_cndmask_b32_e32 v169, v165, v169, vcc
	v_cvt_pk_f16_f32 v119, v126, v127
	v_cvt_pk_f16_f32 v118, v124, v125
	global_store_dwordx4 v[178:179], v[118:121], off
	s_nop 1
	v_cvt_pk_f16_f32 v119, v112, v113
	s_waitcnt lgkmcnt(0)
	v_add_f32_e32 v113, v114, v115
	v_lshlrev_b32_e32 v112, 2, v169
	v_mov_b32_e32 v114, v113
	s_nop 1
	v_permlane32_swap_b32_e32 v113, v114
	v_cvt_pk_f16_f32 v118, v116, v117
	v_cvt_pk_f16_f32 v117, v184, v185
	v_cvt_pk_f16_f32 v116, v176, v177
	global_store_dwordx4 v[180:181], v[116:119], off
	s_and_saveexec_b64 s[16:17], s[4:5]
	s_cbranch_execz .LBB0_300
	v_lshl_add_u32 v136, v167, 4, s18
	s_waitcnt lgkmcnt(0)
	v_add_f32_e32 v113, v113, v114
	v_lshl_add_u64 v[114:115], v[136:137], 2, s[42:43]
	global_store_dword v[114:115], v113, off
.LBB0_300:
	s_or_b64 exec, exec, s[16:17]
	v_add_u32_e32 v113, 16, v167
	v_lshl_add_u32 v136, v113, 10, v168
	v_lshl_add_u64 v[122:123], v[136:137], 1, s[40:41]
	v_add_u32_e32 v136, 0x80, v136
	v_lshl_add_u64 v[124:125], v[136:137], 1, s[40:41]
	s_waitcnt lgkmcnt(0)
	s_waitcnt vmcnt(10)
	v_cvt_f32_f16_e32 v126, v195
	v_cvt_f32_f16_sdwa v127, v195 dst_sel:DWORD dst_unused:UNUSED_PAD src0_sel:WORD_1
	v_cvt_f32_f16_e32 v170, v193
	v_cvt_f32_f16_sdwa v171, v193 dst_sel:DWORD dst_unused:UNUSED_PAD src0_sel:WORD_1
	v_cvt_f32_f16_e32 v172, v194
	v_cvt_f32_f16_sdwa v173, v194 dst_sel:DWORD dst_unused:UNUSED_PAD src0_sel:WORD_1
	v_cvt_f32_f16_e32 v116, v192
	v_cvt_f32_f16_sdwa v117, v192 dst_sel:DWORD dst_unused:UNUSED_PAD src0_sel:WORD_1
	v_cvt_f32_f16_e32 v114, v199
	v_cvt_f32_f16_sdwa v115, v199 dst_sel:DWORD dst_unused:UNUSED_PAD src0_sel:WORD_1
	v_cvt_f32_f16_e32 v174, v197
	v_cvt_f32_f16_sdwa v175, v197 dst_sel:DWORD dst_unused:UNUSED_PAD src0_sel:WORD_1
	v_cvt_f32_f16_e32 v176, v198
	v_cvt_f32_f16_sdwa v177, v198 dst_sel:DWORD dst_unused:UNUSED_PAD src0_sel:WORD_1
	v_cvt_f32_f16_e32 v120, v196
	v_cvt_f32_f16_sdwa v121, v196 dst_sel:DWORD dst_unused:UNUSED_PAD src0_sel:WORD_1
	v_pk_fma_f32 v[108:109], v[108:109], 0.5, v[116:117] op_sel_hi:[1,0,1]
	v_pk_fma_f32 v[116:117], v[104:105], 0.5, v[172:173] op_sel_hi:[1,0,1]
	v_pk_fma_f32 v[110:111], v[110:111], 0.5, v[170:171] op_sel_hi:[1,0,1]
	v_pk_fma_f32 v[106:107], v[106:107], 0.5, v[126:127] op_sel_hi:[1,0,1]
	v_pk_fma_f32 v[120:121], v[100:101], 0.5, v[120:121] op_sel_hi:[1,0,1]
	v_pk_fma_f32 v[170:171], v[96:97], 0.5, v[176:177] op_sel_hi:[1,0,1]
	v_pk_fma_f32 v[172:173], v[102:103], 0.5, v[174:175] op_sel_hi:[1,0,1]
	v_pk_fma_f32 v[96:97], v[98:99], 0.5, v[114:115] op_sel_hi:[1,0,1]
	v_cvt_pk_f16_f32 v105, v106, v107
	v_cvt_pk_f16_f32 v104, v116, v117
	v_pk_mul_f32 v[118:119], v[108:109], v[108:109]
	v_pk_mul_f32 v[126:127], v[110:111], v[110:111]
	v_pk_mul_f32 v[116:117], v[116:117], v[116:117]
	v_pk_mul_f32 v[106:107], v[106:107], v[106:107]
	v_pk_mul_f32 v[98:99], v[120:121], v[120:121]
	v_pk_mul_f32 v[100:101], v[172:173], v[172:173]
	v_pk_mul_f32 v[102:103], v[170:171], v[170:171]
	v_pk_mul_f32 v[114:115], v[96:97], v[96:97]
	v_add_f32_e32 v106, v106, v107
	v_add_f32_e32 v107, v116, v117
	v_add_f32_e32 v116, v126, v127
	v_add_f32_e32 v117, v118, v119
	v_add_f32_e32 v114, v114, v115
	v_add_f32_e32 v102, v102, v103
	v_add_f32_e32 v100, v100, v101
	v_add_f32_e32 v98, v98, v99
	v_add_f32_e32 v106, v107, v106
	v_add_f32_e32 v107, v117, v116
	v_add_f32_e32 v101, v102, v114
	v_add_f32_e32 v98, v98, v100
	v_add_f32_e32 v99, v107, v106
	v_add_f32_e32 v98, v98, v101
	v_add_f32_e32 v98, v99, v98
	v_mov_b32_e32 v99, v98
	s_nop 1
	v_permlane16_swap_b32_e32 v98, v99
	v_cvt_pk_f16_f32 v101, v96, v97
	v_cvt_pk_f16_f32 v103, v110, v111
	v_cvt_pk_f16_f32 v102, v108, v109
	v_cvt_pk_f16_f32 v100, v170, v171
	s_waitcnt lgkmcnt(0)
	v_add_f32_e32 v96, v98, v99
	v_mov_b32_e32 v97, v96
	s_nop 1
	v_permlane32_swap_b32_e32 v96, v97
	v_cvt_pk_f16_f32 v99, v172, v173
	v_cvt_pk_f16_f32 v98, v120, v121
	global_store_dwordx4 v[122:123], v[102:105], off
	global_store_dwordx4 v[124:125], v[98:101], off
	s_and_saveexec_b64 s[16:17], s[4:5]
	s_cbranch_execz .LBB0_302
	v_lshl_add_u32 v136, v113, 4, s18
	s_waitcnt lgkmcnt(0)
	v_add_f32_e32 v98, v96, v97
	v_lshl_add_u64 v[96:97], v[136:137], 2, s[42:43]
	global_store_dword v[96:97], v98, off
;   __device__ __forceinline__ void operator()(const pg8::f32x4 (&acc)[2][2][4][2], const pg8::Unit& u, int wr, int wc, int fr, int fq) const {
;     ...
;         const int tok = row0 + ai * 128 + m * 16; float ss = 0.f;
; #pragma unroll
;         for (int bj = 0; bj < 2; ++bj) {
;           const unsigned off = (unsigned)tok * DM + colb + 128 * bj;
;           f8_t n = __builtin_convertvector(*(const h8_t*)(x16 + off), f8_t);
; #pragma unroll
;           for (int c = 0; c < 4; ++c) { n[c] += sc * acc[ai][bj][m][0][c]; n[4 + c] += sc * acc[ai][bj][m][1][c]; }
;           if (aux) {
;             *(h8_t*)(x16 + off) = __builtin_convertvector(n, h8_t);
;             ss += ((n[0] * n[0] + n[1] * n[1]) + (n[2] * n[2] + n[3] * n[3])) + ((n[4] * n[4] + n[5] * n[5]) + (n[6] * n[6] + n[7] * n[7]));
;           } else {
;             *(f32x4*)(xout + off) = (f32x4){n[0], n[1], n[2], n[3]}; *(f32x4*)(xout + off + 4) = (f32x4){n[4], n[5], n[6], n[7]};
;           }
;         }
;         if (aux) { ss += __shfl_xor(ss, 16); ss += __shfl_xor(ss, 32); if (fq == 0) ssq[(unsigned)tok * 16 + u.pn * 4 + wc] = ss; }
.LBB0_302:
	s_or_b64 exec, exec, s[16:17]
	v_add_u32_e32 v96, 32, v167
	v_lshl_add_u32 v136, v96, 10, v168
	v_lshl_add_u64 v[106:107], v[136:137], 1, s[40:41]
	v_add_u32_e32 v136, 0x80, v136
	v_lshl_add_u64 v[108:109], v[136:137], 1, s[40:41]
	s_waitcnt vmcnt(10)
	v_cvt_f32_f16_e32 v110, v203
	v_cvt_f32_f16_sdwa v111, v203 dst_sel:DWORD dst_unused:UNUSED_PAD src0_sel:WORD_1
	v_cvt_f32_f16_e32 v114, v201
	v_cvt_f32_f16_sdwa v115, v201 dst_sel:DWORD dst_unused:UNUSED_PAD src0_sel:WORD_1
	v_cvt_f32_f16_e32 v116, v202
	v_cvt_f32_f16_sdwa v117, v202 dst_sel:DWORD dst_unused:UNUSED_PAD src0_sel:WORD_1
	v_cvt_f32_f16_e32 v100, v200
	v_cvt_f32_f16_sdwa v101, v200 dst_sel:DWORD dst_unused:UNUSED_PAD src0_sel:WORD_1
	v_cvt_f32_f16_e32 v98, v207
	v_cvt_f32_f16_sdwa v99, v207 dst_sel:DWORD dst_unused:UNUSED_PAD src0_sel:WORD_1
	v_cvt_f32_f16_e32 v118, v205
	v_cvt_f32_f16_sdwa v119, v205 dst_sel:DWORD dst_unused:UNUSED_PAD src0_sel:WORD_1
	v_cvt_f32_f16_e32 v120, v206
	v_cvt_f32_f16_sdwa v121, v206 dst_sel:DWORD dst_unused:UNUSED_PAD src0_sel:WORD_1
	v_cvt_f32_f16_e32 v104, v204
	v_cvt_f32_f16_sdwa v105, v204 dst_sel:DWORD dst_unused:UNUSED_PAD src0_sel:WORD_1
	v_pk_fma_f32 v[92:93], v[92:93], 0.5, v[100:101] op_sel_hi:[1,0,1]
	v_pk_fma_f32 v[100:101], v[88:89], 0.5, v[116:117] op_sel_hi:[1,0,1]
	v_pk_fma_f32 v[94:95], v[94:95], 0.5, v[114:115] op_sel_hi:[1,0,1]
	v_pk_fma_f32 v[90:91], v[90:91], 0.5, v[110:111] op_sel_hi:[1,0,1]
	v_cvt_pk_f16_f32 v88, v100, v101
	v_cvt_pk_f16_f32 v89, v90, v91
	v_pk_mul_f32 v[102:103], v[92:93], v[92:93]
	v_pk_mul_f32 v[110:111], v[94:95], v[94:95]
	v_pk_mul_f32 v[100:101], v[100:101], v[100:101]
	v_pk_mul_f32 v[90:91], v[90:91], v[90:91]
	v_pk_fma_f32 v[104:105], v[84:85], 0.5, v[104:105] op_sel_hi:[1,0,1]
	v_pk_fma_f32 v[114:115], v[80:81], 0.5, v[120:121] op_sel_hi:[1,0,1]
	v_pk_fma_f32 v[116:117], v[86:87], 0.5, v[118:119] op_sel_hi:[1,0,1]
	v_pk_fma_f32 v[80:81], v[82:83], 0.5, v[98:99] op_sel_hi:[1,0,1]
	v_pk_mul_f32 v[82:83], v[104:105], v[104:105]
	v_pk_mul_f32 v[84:85], v[116:117], v[116:117]
	v_pk_mul_f32 v[86:87], v[114:115], v[114:115]
	v_pk_mul_f32 v[98:99], v[80:81], v[80:81]
	v_add_f32_e32 v90, v90, v91
	v_add_f32_e32 v91, v100, v101
	s_waitcnt lgkmcnt(0)
	v_add_f32_e32 v97, v110, v111
	v_add_f32_e32 v100, v102, v103
	v_add_f32_e32 v90, v91, v90
	v_add_f32_e32 v91, v100, v97
	v_add_f32_e32 v97, v98, v99
	v_add_f32_e32 v86, v86, v87
	v_add_f32_e32 v84, v84, v85
	v_add_f32_e32 v82, v82, v83
	v_add_f32_e32 v85, v86, v97
	v_add_f32_e32 v82, v82, v84
	v_add_f32_e32 v83, v91, v90
	v_add_f32_e32 v82, v82, v85
	v_add_f32_e32 v82, v83, v82
	v_mov_b32_e32 v83, v82
	s_nop 1
	v_permlane16_swap_b32_e32 v82, v83
	v_cvt_pk_f16_f32 v85, v80, v81
	v_cvt_pk_f16_f32 v87, v94, v95
	v_cvt_pk_f16_f32 v86, v92, v93
	v_cvt_pk_f16_f32 v84, v114, v115
	s_waitcnt lgkmcnt(0)
	v_add_f32_e32 v80, v82, v83
	v_mov_b32_e32 v81, v80
	s_nop 1
	v_permlane32_swap_b32_e32 v80, v81
	v_cvt_pk_f16_f32 v83, v116, v117
	v_cvt_pk_f16_f32 v82, v104, v105
	global_store_dwordx4 v[106:107], v[86:89], off
	global_store_dwordx4 v[108:109], v[82:85], off
	s_and_saveexec_b64 s[16:17], s[4:5]
	s_cbranch_execz .LBB0_304
	v_lshl_add_u32 v136, v96, 4, s18
	s_waitcnt lgkmcnt(0)
	v_add_f32_e32 v82, v80, v81
	v_lshl_add_u64 v[80:81], v[136:137], 2, s[42:43]
	global_store_dword v[80:81], v82, off
.LBB0_304:
	s_or_b64 exec, exec, s[16:17]
	v_add_u32_e32 v80, 48, v167
	v_lshl_add_u32 v136, v80, 10, v168
	v_lshl_add_u64 v[90:91], v[136:137], 1, s[40:41]
	v_add_u32_e32 v136, 0x80, v136
	v_lshl_add_u64 v[92:93], v[136:137], 1, s[40:41]
	s_waitcnt vmcnt(10)
	v_cvt_f32_f16_e32 v94, v211
	v_cvt_f32_f16_sdwa v95, v211 dst_sel:DWORD dst_unused:UNUSED_PAD src0_sel:WORD_1
	v_cvt_f32_f16_e32 v96, v209
	v_cvt_f32_f16_sdwa v97, v209 dst_sel:DWORD dst_unused:UNUSED_PAD src0_sel:WORD_1
	v_cvt_f32_f16_e32 v98, v210
	v_cvt_f32_f16_sdwa v99, v210 dst_sel:DWORD dst_unused:UNUSED_PAD src0_sel:WORD_1
	v_cvt_f32_f16_e32 v84, v208
	v_cvt_f32_f16_sdwa v85, v208 dst_sel:DWORD dst_unused:UNUSED_PAD src0_sel:WORD_1
	v_cvt_f32_f16_e32 v82, v215
	v_cvt_f32_f16_sdwa v83, v215 dst_sel:DWORD dst_unused:UNUSED_PAD src0_sel:WORD_1
	v_cvt_f32_f16_e32 v100, v213
	v_cvt_f32_f16_sdwa v101, v213 dst_sel:DWORD dst_unused:UNUSED_PAD src0_sel:WORD_1
	v_cvt_f32_f16_e32 v102, v214
	v_cvt_f32_f16_sdwa v103, v214 dst_sel:DWORD dst_unused:UNUSED_PAD src0_sel:WORD_1
	v_cvt_f32_f16_e32 v88, v212
	v_cvt_f32_f16_sdwa v89, v212 dst_sel:DWORD dst_unused:UNUSED_PAD src0_sel:WORD_1
	v_pk_fma_f32 v[76:77], v[76:77], 0.5, v[84:85] op_sel_hi:[1,0,1]
	v_pk_fma_f32 v[84:85], v[72:73], 0.5, v[98:99] op_sel_hi:[1,0,1]
	v_pk_fma_f32 v[78:79], v[78:79], 0.5, v[96:97] op_sel_hi:[1,0,1]
	v_pk_fma_f32 v[74:75], v[74:75], 0.5, v[94:95] op_sel_hi:[1,0,1]
	v_cvt_pk_f16_f32 v72, v84, v85
	v_cvt_pk_f16_f32 v73, v74, v75
	v_pk_mul_f32 v[86:87], v[76:77], v[76:77]
	v_pk_mul_f32 v[94:95], v[78:79], v[78:79]
	v_pk_mul_f32 v[84:85], v[84:85], v[84:85]
	v_pk_mul_f32 v[74:75], v[74:75], v[74:75]
	v_pk_fma_f32 v[88:89], v[68:69], 0.5, v[88:89] op_sel_hi:[1,0,1]
	v_pk_fma_f32 v[96:97], v[64:65], 0.5, v[102:103] op_sel_hi:[1,0,1]
	v_pk_fma_f32 v[98:99], v[70:71], 0.5, v[100:101] op_sel_hi:[1,0,1]
	v_pk_fma_f32 v[64:65], v[66:67], 0.5, v[82:83] op_sel_hi:[1,0,1]
	v_pk_mul_f32 v[66:67], v[88:89], v[88:89]
	v_pk_mul_f32 v[68:69], v[98:99], v[98:99]
	v_pk_mul_f32 v[70:71], v[96:97], v[96:97]
	v_pk_mul_f32 v[82:83], v[64:65], v[64:65]
	v_add_f32_e32 v74, v74, v75
	v_add_f32_e32 v75, v84, v85
	s_waitcnt lgkmcnt(0)
	v_add_f32_e32 v81, v94, v95
	v_add_f32_e32 v84, v86, v87
	v_add_f32_e32 v74, v75, v74
	v_add_f32_e32 v75, v84, v81
	v_add_f32_e32 v81, v82, v83
	v_add_f32_e32 v70, v70, v71
	v_add_f32_e32 v68, v68, v69
	v_add_f32_e32 v66, v66, v67
	v_add_f32_e32 v69, v70, v81
	v_add_f32_e32 v66, v66, v68
	v_add_f32_e32 v67, v75, v74
	v_add_f32_e32 v66, v66, v69
	v_add_f32_e32 v66, v67, v66
	v_mov_b32_e32 v67, v66
	s_nop 1
	v_permlane16_swap_b32_e32 v66, v67
	v_cvt_pk_f16_f32 v69, v64, v65
	v_cvt_pk_f16_f32 v71, v78, v79
	v_cvt_pk_f16_f32 v70, v76, v77
	v_cvt_pk_f16_f32 v68, v96, v97
	s_waitcnt lgkmcnt(0)
	v_add_f32_e32 v64, v66, v67
	v_mov_b32_e32 v65, v64
	s_nop 1
	v_permlane32_swap_b32_e32 v64, v65
	v_cvt_pk_f16_f32 v67, v98, v99
	v_cvt_pk_f16_f32 v66, v88, v89
	global_store_dwordx4 v[90:91], v[70:73], off
	global_store_dwordx4 v[92:93], v[66:69], off
	s_and_saveexec_b64 s[16:17], s[4:5]
	s_cbranch_execz .LBB0_306
	v_lshl_add_u32 v136, v80, 4, s18
	s_waitcnt lgkmcnt(0)
	v_add_f32_e32 v66, v64, v65
	v_lshl_add_u64 v[64:65], v[136:137], 2, s[42:43]
	global_store_dword v[64:65], v66, off
;   __device__ __forceinline__ void operator()(const pg8::f32x4 (&acc)[2][2][4][2], const pg8::Unit& u, int wr, int wc, int fr, int fq) const {
;     ...
;         const int tok = row0 + ai * 128 + m * 16; float ss = 0.f;
; #pragma unroll
;         for (int bj = 0; bj < 2; ++bj) {
;           const unsigned off = (unsigned)tok * DM + colb + 128 * bj;
;           f8_t n = __builtin_convertvector(*(const h8_t*)(x16 + off), f8_t);
; #pragma unroll
;           for (int c = 0; c < 4; ++c) { n[c] += sc * acc[ai][bj][m][0][c]; n[4 + c] += sc * acc[ai][bj][m][1][c]; }
;           if (aux) {
;             *(h8_t*)(x16 + off) = __builtin_convertvector(n, h8_t);
;             ss += ((n[0] * n[0] + n[1] * n[1]) + (n[2] * n[2] + n[3] * n[3])) + ((n[4] * n[4] + n[5] * n[5]) + (n[6] * n[6] + n[7] * n[7]));
;           } else {
;             *(f32x4*)(xout + off) = (f32x4){n[0], n[1], n[2], n[3]}; *(f32x4*)(xout + off + 4) = (f32x4){n[4], n[5], n[6], n[7]};
;           }
;         }
;         if (aux) { ss += __shfl_xor(ss, 16); ss += __shfl_xor(ss, 32); if (fq == 0) ssq[(unsigned)tok * 16 + u.pn * 4 + wc] = ss; }
.LBB0_306:
	s_or_b64 exec, exec, s[16:17]
	v_add_u32_e32 v64, 0x80, v167
	v_lshl_add_u32 v136, v64, 10, v168
	v_lshl_add_u64 v[74:75], v[136:137], 1, s[40:41]
	v_add_u32_e32 v136, 0x80, v136
	v_lshl_add_u64 v[76:77], v[136:137], 1, s[40:41]
	s_waitcnt vmcnt(10)
	v_cvt_f32_f16_e32 v78, v219
	v_cvt_f32_f16_sdwa v79, v219 dst_sel:DWORD dst_unused:UNUSED_PAD src0_sel:WORD_1
	v_cvt_f32_f16_e32 v80, v217
	v_cvt_f32_f16_sdwa v81, v217 dst_sel:DWORD dst_unused:UNUSED_PAD src0_sel:WORD_1
	v_cvt_f32_f16_e32 v82, v218
	v_cvt_f32_f16_sdwa v83, v218 dst_sel:DWORD dst_unused:UNUSED_PAD src0_sel:WORD_1
	v_cvt_f32_f16_e32 v68, v216
	v_cvt_f32_f16_sdwa v69, v216 dst_sel:DWORD dst_unused:UNUSED_PAD src0_sel:WORD_1
	v_cvt_f32_f16_e32 v66, v223
	v_cvt_f32_f16_sdwa v67, v223 dst_sel:DWORD dst_unused:UNUSED_PAD src0_sel:WORD_1
	v_cvt_f32_f16_e32 v84, v221
	v_cvt_f32_f16_sdwa v85, v221 dst_sel:DWORD dst_unused:UNUSED_PAD src0_sel:WORD_1
	v_cvt_f32_f16_e32 v86, v222
	v_cvt_f32_f16_sdwa v87, v222 dst_sel:DWORD dst_unused:UNUSED_PAD src0_sel:WORD_1
	v_cvt_f32_f16_e32 v72, v220
	v_cvt_f32_f16_sdwa v73, v220 dst_sel:DWORD dst_unused:UNUSED_PAD src0_sel:WORD_1
	v_pk_fma_f32 v[60:61], v[60:61], 0.5, v[68:69] op_sel_hi:[1,0,1]
	v_pk_fma_f32 v[68:69], v[56:57], 0.5, v[82:83] op_sel_hi:[1,0,1]
	v_pk_fma_f32 v[62:63], v[62:63], 0.5, v[80:81] op_sel_hi:[1,0,1]
	v_pk_fma_f32 v[58:59], v[58:59], 0.5, v[78:79] op_sel_hi:[1,0,1]
	v_cvt_pk_f16_f32 v56, v68, v69
	v_cvt_pk_f16_f32 v57, v58, v59
	v_pk_mul_f32 v[70:71], v[60:61], v[60:61]
	v_pk_mul_f32 v[78:79], v[62:63], v[62:63]
	v_pk_mul_f32 v[68:69], v[68:69], v[68:69]
	v_pk_mul_f32 v[58:59], v[58:59], v[58:59]
	v_pk_fma_f32 v[72:73], v[52:53], 0.5, v[72:73] op_sel_hi:[1,0,1]
	v_pk_fma_f32 v[80:81], v[48:49], 0.5, v[86:87] op_sel_hi:[1,0,1]
	v_pk_fma_f32 v[82:83], v[54:55], 0.5, v[84:85] op_sel_hi:[1,0,1]
	v_pk_fma_f32 v[48:49], v[50:51], 0.5, v[66:67] op_sel_hi:[1,0,1]
	v_pk_mul_f32 v[50:51], v[72:73], v[72:73]
	v_pk_mul_f32 v[52:53], v[82:83], v[82:83]
	v_pk_mul_f32 v[54:55], v[80:81], v[80:81]
	v_pk_mul_f32 v[66:67], v[48:49], v[48:49]
	v_add_f32_e32 v58, v58, v59
	v_add_f32_e32 v59, v68, v69
	s_waitcnt lgkmcnt(0)
	v_add_f32_e32 v65, v78, v79
	v_add_f32_e32 v68, v70, v71
	v_add_f32_e32 v58, v59, v58
	v_add_f32_e32 v59, v68, v65
	v_add_f32_e32 v65, v66, v67
	v_add_f32_e32 v54, v54, v55
	v_add_f32_e32 v52, v52, v53
	v_add_f32_e32 v50, v50, v51
	v_add_f32_e32 v53, v54, v65
	v_add_f32_e32 v50, v50, v52
	v_add_f32_e32 v51, v59, v58
	v_add_f32_e32 v50, v50, v53
	v_add_f32_e32 v50, v51, v50
	v_mov_b32_e32 v51, v50
	s_nop 1
	v_permlane16_swap_b32_e32 v50, v51
	v_cvt_pk_f16_f32 v53, v48, v49
	v_cvt_pk_f16_f32 v55, v62, v63
	v_cvt_pk_f16_f32 v54, v60, v61
	v_cvt_pk_f16_f32 v52, v80, v81
	s_waitcnt lgkmcnt(0)
	v_add_f32_e32 v48, v50, v51
	v_mov_b32_e32 v49, v48
	s_nop 1
	v_permlane32_swap_b32_e32 v48, v49
	v_cvt_pk_f16_f32 v51, v82, v83
	v_cvt_pk_f16_f32 v50, v72, v73
	global_store_dwordx4 v[74:75], v[54:57], off
	global_store_dwordx4 v[76:77], v[50:53], off
	s_and_saveexec_b64 s[16:17], s[4:5]
	s_cbranch_execz .LBB0_308
	v_lshl_add_u32 v136, v64, 4, s18
	s_waitcnt lgkmcnt(0)
	v_add_f32_e32 v50, v48, v49
	v_lshl_add_u64 v[48:49], v[136:137], 2, s[42:43]
	global_store_dword v[48:49], v50, off
.LBB0_308:
	s_or_b64 exec, exec, s[16:17]
	v_add_u32_e32 v48, 0x90, v167
	v_lshl_add_u32 v136, v48, 10, v168
	v_lshl_add_u64 v[58:59], v[136:137], 1, s[40:41]
	v_add_u32_e32 v136, 0x80, v136
	v_lshl_add_u64 v[60:61], v[136:137], 1, s[40:41]
	s_waitcnt vmcnt(10)
	v_cvt_f32_f16_e32 v62, v231
	v_cvt_f32_f16_sdwa v63, v231 dst_sel:DWORD dst_unused:UNUSED_PAD src0_sel:WORD_1
	v_cvt_f32_f16_e32 v64, v229
	v_cvt_f32_f16_sdwa v65, v229 dst_sel:DWORD dst_unused:UNUSED_PAD src0_sel:WORD_1
	v_cvt_f32_f16_e32 v66, v230
	v_cvt_f32_f16_sdwa v67, v230 dst_sel:DWORD dst_unused:UNUSED_PAD src0_sel:WORD_1
	v_cvt_f32_f16_e32 v52, v228
	v_cvt_f32_f16_sdwa v53, v228 dst_sel:DWORD dst_unused:UNUSED_PAD src0_sel:WORD_1
	v_cvt_f32_f16_e32 v50, v247
	v_cvt_f32_f16_sdwa v51, v247 dst_sel:DWORD dst_unused:UNUSED_PAD src0_sel:WORD_1
	v_cvt_f32_f16_e32 v68, v245
	v_cvt_f32_f16_sdwa v69, v245 dst_sel:DWORD dst_unused:UNUSED_PAD src0_sel:WORD_1
	v_cvt_f32_f16_e32 v70, v246
	v_cvt_f32_f16_sdwa v71, v246 dst_sel:DWORD dst_unused:UNUSED_PAD src0_sel:WORD_1
	v_cvt_f32_f16_e32 v56, v244
	v_cvt_f32_f16_sdwa v57, v244 dst_sel:DWORD dst_unused:UNUSED_PAD src0_sel:WORD_1
	v_pk_fma_f32 v[44:45], v[44:45], 0.5, v[52:53] op_sel_hi:[1,0,1]
	v_pk_fma_f32 v[52:53], v[40:41], 0.5, v[66:67] op_sel_hi:[1,0,1]
	v_pk_fma_f32 v[46:47], v[46:47], 0.5, v[64:65] op_sel_hi:[1,0,1]
	v_pk_fma_f32 v[42:43], v[42:43], 0.5, v[62:63] op_sel_hi:[1,0,1]
	v_cvt_pk_f16_f32 v40, v52, v53
	v_cvt_pk_f16_f32 v41, v42, v43
	v_pk_mul_f32 v[54:55], v[44:45], v[44:45]
	v_pk_mul_f32 v[62:63], v[46:47], v[46:47]
	v_pk_mul_f32 v[52:53], v[52:53], v[52:53]
	v_pk_mul_f32 v[42:43], v[42:43], v[42:43]
	v_pk_fma_f32 v[56:57], v[36:37], 0.5, v[56:57] op_sel_hi:[1,0,1]
	v_pk_fma_f32 v[64:65], v[32:33], 0.5, v[70:71] op_sel_hi:[1,0,1]
	v_pk_fma_f32 v[66:67], v[38:39], 0.5, v[68:69] op_sel_hi:[1,0,1]
	v_pk_fma_f32 v[32:33], v[34:35], 0.5, v[50:51] op_sel_hi:[1,0,1]
	v_pk_mul_f32 v[34:35], v[56:57], v[56:57]
	v_pk_mul_f32 v[36:37], v[66:67], v[66:67]
	v_pk_mul_f32 v[38:39], v[64:65], v[64:65]
	v_pk_mul_f32 v[50:51], v[32:33], v[32:33]
	v_add_f32_e32 v42, v42, v43
	v_add_f32_e32 v43, v52, v53
	s_waitcnt lgkmcnt(0)
	v_add_f32_e32 v49, v62, v63
	v_add_f32_e32 v52, v54, v55
	v_add_f32_e32 v42, v43, v42
	v_add_f32_e32 v43, v52, v49
	v_add_f32_e32 v49, v50, v51
	v_add_f32_e32 v38, v38, v39
	v_add_f32_e32 v36, v36, v37
	v_add_f32_e32 v34, v34, v35
	v_add_f32_e32 v37, v38, v49
	v_add_f32_e32 v34, v34, v36
	v_add_f32_e32 v35, v43, v42
	v_add_f32_e32 v34, v34, v37
	v_add_f32_e32 v34, v35, v34
	v_mov_b32_e32 v35, v34
	s_nop 1
	v_permlane16_swap_b32_e32 v34, v35
	v_cvt_pk_f16_f32 v37, v32, v33
	v_cvt_pk_f16_f32 v39, v46, v47
	v_cvt_pk_f16_f32 v38, v44, v45
	v_cvt_pk_f16_f32 v36, v64, v65
	s_waitcnt lgkmcnt(0)
	v_add_f32_e32 v32, v34, v35
	v_mov_b32_e32 v33, v32
	s_nop 1
	v_permlane32_swap_b32_e32 v32, v33
	v_cvt_pk_f16_f32 v35, v66, v67
	v_cvt_pk_f16_f32 v34, v56, v57
	global_store_dwordx4 v[58:59], v[38:41], off
	global_store_dwordx4 v[60:61], v[34:37], off
	s_and_saveexec_b64 s[16:17], s[4:5]
	s_cbranch_execz .LBB0_310
	v_lshl_add_u32 v136, v48, 4, s18
	s_waitcnt lgkmcnt(0)
	v_add_f32_e32 v34, v32, v33
	v_lshl_add_u64 v[32:33], v[136:137], 2, s[42:43]
	global_store_dword v[32:33], v34, off
;   __device__ __forceinline__ void operator()(const pg8::f32x4 (&acc)[2][2][4][2], const pg8::Unit& u, int wr, int wc, int fr, int fq) const {
;     ...
;         const int tok = row0 + ai * 128 + m * 16; float ss = 0.f;
; #pragma unroll
;         for (int bj = 0; bj < 2; ++bj) {
;           const unsigned off = (unsigned)tok * DM + colb + 128 * bj;
;           f8_t n = __builtin_convertvector(*(const h8_t*)(x16 + off), f8_t);
; #pragma unroll
;           for (int c = 0; c < 4; ++c) { n[c] += sc * acc[ai][bj][m][0][c]; n[4 + c] += sc * acc[ai][bj][m][1][c]; }
;           if (aux) {
;             *(h8_t*)(x16 + off) = __builtin_convertvector(n, h8_t);
;             ss += ((n[0] * n[0] + n[1] * n[1]) + (n[2] * n[2] + n[3] * n[3])) + ((n[4] * n[4] + n[5] * n[5]) + (n[6] * n[6] + n[7] * n[7]));
;           } else {
;             *(f32x4*)(xout + off) = (f32x4){n[0], n[1], n[2], n[3]}; *(f32x4*)(xout + off + 4) = (f32x4){n[4], n[5], n[6], n[7]};
;           }
;         }
;         if (aux) { ss += __shfl_xor(ss, 16); ss += __shfl_xor(ss, 32); if (fq == 0) ssq[(unsigned)tok * 16 + u.pn * 4 + wc] = ss; }
;         if (m & 1) asm volatile("" ::: "memory");
.LBB0_310:
	s_or_b64 exec, exec, s[16:17]
	v_add_u32_e32 v32, 0xa0, v167
	v_lshl_add_u32 v136, v32, 10, v168
	v_lshl_add_u64 v[42:43], v[136:137], 1, s[40:41]
	v_add_u32_e32 v136, 0x80, v136
	global_load_dwordx4 v[34:37], v[42:43], off
	v_lshl_add_u64 v[44:45], v[136:137], 1, s[40:41]
	global_load_dwordx4 v[38:41], v[44:45], off
	s_waitcnt vmcnt(1)
	v_cvt_f32_f16_e32 v46, v37
	v_cvt_f32_f16_sdwa v47, v37 dst_sel:DWORD dst_unused:UNUSED_PAD src0_sel:WORD_1
	v_cvt_f32_f16_e32 v48, v35
	v_cvt_f32_f16_sdwa v49, v35 dst_sel:DWORD dst_unused:UNUSED_PAD src0_sel:WORD_1
	v_cvt_f32_f16_e32 v50, v36
	v_cvt_f32_f16_sdwa v51, v36 dst_sel:DWORD dst_unused:UNUSED_PAD src0_sel:WORD_1
	v_cvt_f32_f16_e32 v36, v34
	v_cvt_f32_f16_sdwa v37, v34 dst_sel:DWORD dst_unused:UNUSED_PAD src0_sel:WORD_1
	s_waitcnt vmcnt(0)
	v_cvt_f32_f16_e32 v34, v41
	v_cvt_f32_f16_sdwa v35, v41 dst_sel:DWORD dst_unused:UNUSED_PAD src0_sel:WORD_1
	v_cvt_f32_f16_e32 v52, v39
	v_cvt_f32_f16_sdwa v53, v39 dst_sel:DWORD dst_unused:UNUSED_PAD src0_sel:WORD_1
	v_cvt_f32_f16_e32 v54, v40
	v_cvt_f32_f16_sdwa v55, v40 dst_sel:DWORD dst_unused:UNUSED_PAD src0_sel:WORD_1
	v_cvt_f32_f16_e32 v40, v38
	v_cvt_f32_f16_sdwa v41, v38 dst_sel:DWORD dst_unused:UNUSED_PAD src0_sel:WORD_1
	v_pk_fma_f32 v[28:29], v[28:29], 0.5, v[36:37] op_sel_hi:[1,0,1]
	v_pk_fma_f32 v[36:37], v[24:25], 0.5, v[50:51] op_sel_hi:[1,0,1]
	v_pk_fma_f32 v[30:31], v[30:31], 0.5, v[48:49] op_sel_hi:[1,0,1]
	v_pk_fma_f32 v[26:27], v[26:27], 0.5, v[46:47] op_sel_hi:[1,0,1]
	v_cvt_pk_f16_f32 v24, v36, v37
	v_cvt_pk_f16_f32 v25, v26, v27
	v_pk_mul_f32 v[38:39], v[28:29], v[28:29]
	v_pk_mul_f32 v[46:47], v[30:31], v[30:31]
	v_pk_mul_f32 v[36:37], v[36:37], v[36:37]
	v_pk_mul_f32 v[26:27], v[26:27], v[26:27]
	v_pk_fma_f32 v[40:41], v[20:21], 0.5, v[40:41] op_sel_hi:[1,0,1]
	v_pk_fma_f32 v[48:49], v[16:17], 0.5, v[54:55] op_sel_hi:[1,0,1]
	v_pk_fma_f32 v[50:51], v[22:23], 0.5, v[52:53] op_sel_hi:[1,0,1]
	v_pk_fma_f32 v[16:17], v[18:19], 0.5, v[34:35] op_sel_hi:[1,0,1]
	v_pk_mul_f32 v[18:19], v[40:41], v[40:41]
	v_pk_mul_f32 v[20:21], v[50:51], v[50:51]
	v_pk_mul_f32 v[22:23], v[48:49], v[48:49]
	v_pk_mul_f32 v[34:35], v[16:17], v[16:17]
	v_add_f32_e32 v26, v26, v27
	v_add_f32_e32 v27, v36, v37
	s_waitcnt lgkmcnt(0)
	v_add_f32_e32 v33, v46, v47
	v_add_f32_e32 v36, v38, v39
	v_add_f32_e32 v26, v27, v26
	v_add_f32_e32 v27, v36, v33
	v_add_f32_e32 v33, v34, v35
	v_add_f32_e32 v22, v22, v23
	v_add_f32_e32 v20, v20, v21
	v_add_f32_e32 v18, v18, v19
	v_add_f32_e32 v21, v22, v33
	v_add_f32_e32 v18, v18, v20
	v_add_f32_e32 v19, v27, v26
	v_add_f32_e32 v18, v18, v21
	v_add_f32_e32 v18, v19, v18
	v_mov_b32_e32 v19, v18
	s_nop 1
	v_permlane16_swap_b32_e32 v18, v19
	v_cvt_pk_f16_f32 v21, v16, v17
	v_cvt_pk_f16_f32 v23, v30, v31
	v_cvt_pk_f16_f32 v22, v28, v29
	v_cvt_pk_f16_f32 v20, v48, v49
	s_waitcnt lgkmcnt(0)
	v_add_f32_e32 v16, v18, v19
	v_mov_b32_e32 v17, v16
	s_nop 1
	v_permlane32_swap_b32_e32 v16, v17
	v_cvt_pk_f16_f32 v19, v50, v51
	v_cvt_pk_f16_f32 v18, v40, v41
	global_store_dwordx4 v[42:43], v[22:25], off
	global_store_dwordx4 v[44:45], v[18:21], off
	s_and_saveexec_b64 s[16:17], s[4:5]
	s_cbranch_execz .LBB0_312
	v_lshl_add_u32 v136, v32, 4, s18
	s_waitcnt lgkmcnt(0)
	v_add_f32_e32 v18, v16, v17
	v_lshl_add_u64 v[16:17], v[136:137], 2, s[42:43]
	global_store_dword v[16:17], v18, off
.LBB0_312:
	s_or_b64 exec, exec, s[16:17]
	v_add_u32_e32 v16, 0xb0, v167
	v_lshl_add_u32 v136, v16, 10, v168
	v_lshl_add_u64 v[26:27], v[136:137], 1, s[40:41]
	v_add_u32_e32 v136, 0x80, v136
	global_load_dwordx4 v[18:21], v[26:27], off
	v_lshl_add_u64 v[28:29], v[136:137], 1, s[40:41]
	global_load_dwordx4 v[22:25], v[28:29], off
	s_waitcnt vmcnt(1)
	v_cvt_f32_f16_e32 v30, v21
	v_cvt_f32_f16_sdwa v31, v21 dst_sel:DWORD dst_unused:UNUSED_PAD src0_sel:WORD_1
	v_cvt_f32_f16_e32 v32, v19
	v_cvt_f32_f16_sdwa v33, v19 dst_sel:DWORD dst_unused:UNUSED_PAD src0_sel:WORD_1
	v_cvt_f32_f16_e32 v34, v20
	v_cvt_f32_f16_sdwa v35, v20 dst_sel:DWORD dst_unused:UNUSED_PAD src0_sel:WORD_1
	v_cvt_f32_f16_e32 v20, v18
	v_cvt_f32_f16_sdwa v21, v18 dst_sel:DWORD dst_unused:UNUSED_PAD src0_sel:WORD_1
	s_waitcnt vmcnt(0)
	v_cvt_f32_f16_e32 v18, v25
	v_cvt_f32_f16_sdwa v19, v25 dst_sel:DWORD dst_unused:UNUSED_PAD src0_sel:WORD_1
	v_cvt_f32_f16_e32 v36, v23
	v_cvt_f32_f16_sdwa v37, v23 dst_sel:DWORD dst_unused:UNUSED_PAD src0_sel:WORD_1
	v_cvt_f32_f16_e32 v38, v24
	v_cvt_f32_f16_sdwa v39, v24 dst_sel:DWORD dst_unused:UNUSED_PAD src0_sel:WORD_1
	v_cvt_f32_f16_e32 v24, v22
	v_cvt_f32_f16_sdwa v25, v22 dst_sel:DWORD dst_unused:UNUSED_PAD src0_sel:WORD_1
	v_pk_fma_f32 v[12:13], v[12:13], 0.5, v[20:21] op_sel_hi:[1,0,1]
	v_pk_fma_f32 v[20:21], v[8:9], 0.5, v[34:35] op_sel_hi:[1,0,1]
	v_pk_fma_f32 v[14:15], v[14:15], 0.5, v[32:33] op_sel_hi:[1,0,1]
	v_pk_fma_f32 v[10:11], v[10:11], 0.5, v[30:31] op_sel_hi:[1,0,1]
	v_cvt_pk_f16_f32 v8, v20, v21
	v_cvt_pk_f16_f32 v9, v10, v11
	v_pk_mul_f32 v[22:23], v[12:13], v[12:13]
	v_pk_mul_f32 v[30:31], v[14:15], v[14:15]
	v_pk_mul_f32 v[20:21], v[20:21], v[20:21]
	v_pk_mul_f32 v[10:11], v[10:11], v[10:11]
	v_pk_fma_f32 v[24:25], v[4:5], 0.5, v[24:25] op_sel_hi:[1,0,1]
	v_pk_fma_f32 v[32:33], v[0:1], 0.5, v[38:39] op_sel_hi:[1,0,1]
	v_pk_fma_f32 v[34:35], v[6:7], 0.5, v[36:37] op_sel_hi:[1,0,1]
	v_pk_fma_f32 v[0:1], v[2:3], 0.5, v[18:19] op_sel_hi:[1,0,1]
	v_pk_mul_f32 v[2:3], v[24:25], v[24:25]
	v_pk_mul_f32 v[4:5], v[34:35], v[34:35]
	v_pk_mul_f32 v[6:7], v[32:33], v[32:33]
	v_pk_mul_f32 v[18:19], v[0:1], v[0:1]
	v_add_f32_e32 v10, v10, v11
	v_add_f32_e32 v11, v20, v21
	s_waitcnt lgkmcnt(0)
	v_add_f32_e32 v17, v30, v31
	v_add_f32_e32 v20, v22, v23
	v_add_f32_e32 v10, v11, v10
	v_add_f32_e32 v11, v20, v17
	v_add_f32_e32 v17, v18, v19
	v_add_f32_e32 v6, v6, v7
	v_add_f32_e32 v4, v4, v5
	v_add_f32_e32 v2, v2, v3
	v_add_f32_e32 v5, v6, v17
	v_add_f32_e32 v2, v2, v4
	v_add_f32_e32 v3, v11, v10
	v_add_f32_e32 v2, v2, v5
	v_add_f32_e32 v2, v3, v2
	v_mov_b32_e32 v3, v2
	s_nop 1
	v_permlane16_swap_b32_e32 v2, v3
	v_cvt_pk_f16_f32 v5, v0, v1
	v_cvt_pk_f16_f32 v7, v14, v15
	v_cvt_pk_f16_f32 v6, v12, v13
	v_cvt_pk_f16_f32 v4, v32, v33
	s_waitcnt lgkmcnt(0)
	v_add_f32_e32 v0, v2, v3
	v_mov_b32_e32 v1, v0
	s_nop 1
	v_permlane32_swap_b32_e32 v0, v1
	v_cvt_pk_f16_f32 v3, v34, v35
	v_cvt_pk_f16_f32 v2, v24, v25
	global_store_dwordx4 v[26:27], v[6:9], off
	global_store_dwordx4 v[28:29], v[2:5], off
	s_and_saveexec_b64 s[16:17], s[4:5]
	s_cbranch_execz .LBB0_285
	v_lshl_add_u32 v136, v16, 4, s18
	s_waitcnt lgkmcnt(0)
	v_add_f32_e32 v2, v0, v1
	v_lshl_add_u64 v[0:1], v[136:137], 2, s[42:43]
	global_store_dword v[0:1], v2, off
	s_branch .LBB0_285

; #define PG8_STAGE(bufoff, gbase, voff) do { _Pragma("unroll") for (int _i = 0; _i < 2; ++_i) \
;         __builtin_amdgcn_global_load_lds((const unsigned*)((const char*)(gbase) + (voff)[_i]), (PG8_LAS unsigned*)(lds + (bufoff) + ldsw + _i * 8192), 16, 0, 0); } while (0)
; #define PG8_LDA(dst, b, h) do { _Pragma("unroll") for (int m = 0; m < 4; ++m) _Pragma("unroll") for (int k = 0; k < 2; ++k) dst[m][k] = *(const PG8_LAS bf16x8*)(lds + PG8_SA(b, h) + aoff + m * 2048 + k * 1024); } while (0)
; #define PG8_LDB(dst, b, h) do { _Pragma("unroll") for (int n = 0; n < 2; ++n) _Pragma("unroll") for (int k = 0; k < 2; ++k) dst[n][k] = *(const PG8_LAS bf16x8*)(lds + PG8_SB(b, h) + boff + n * 2048 + k * 1024); } while (0)
; #define PG8_MMA(ai, bj, At, Bt) do { __builtin_amdgcn_s_setprio(1); _Pragma("unroll") for (int m = 0; m < 4; ++m) _Pragma("unroll") for (int n = 0; n < 2; ++n) _Pragma("unroll") for (int k = 0; k < 2; ++k) \
;         acc[ai][bj][m][n] = mma16<F16>(Bt[n][k], At[m][k], acc[ai][bj][m][n]); __builtin_amdgcn_s_setprio(0); } while (0)
; #define PG8_WAIT_V(n) asm volatile("s_waitcnt vmcnt(" #n ")" ::: "memory")
; #define PG8_WAIT_L(n) asm volatile("s_waitcnt lgkmcnt(" #n ")" ::: "memory")
; #define PG8_BAR __builtin_amdgcn_s_barrier()
; #define PG8_SCHED __builtin_amdgcn_sched_barrier(0)
; template <class Epi, class Sched, bool ALIGN_EPI = false, bool SP2 = false, bool F16 = false, bool TOKPERM = false>
; __device__ __forceinline__ void gemm_phase(PG8_LAS unsigned char* lds, const Gemm g, const Sched& S, const Epi& E, int wv) {
;     ...
;             PG8_LDB(B0, 0, 0); PG8_LDB(B1, 0, 1); PG8_SCHED; PG8_LDA(At, 0, 0); PG8_STAGE(PG8_SA(1, 1), a1 + hstep, voffA);
;             PG8_WAIT_V(8); PG8_WAIT_L(0); PG8_BAR; PG8_MMA(0, 0, At, B0); PG8_MMA(0, 1, At, B1); PG8_BAR; PG8_SCHED;
;             PG8_LDA(At, 0, 1); PG8_STAGE(PG8_SB(0, 0), b2, voffB); PG8_STAGE(PG8_SB(0, 1), b2 + hstep, voffB); PG8_STAGE(PG8_SA(0, 0), a2, voffA);
;             PG8_WAIT_V(8); PG8_WAIT_L(0); PG8_BAR; PG8_MMA(1, 0, At, B0); PG8_MMA(1, 1, At, B1); PG8_BAR; PG8_SCHED;
.LBB0_685:
	ds_read_b128 v[166:169], v149
	ds_read_b128 v[170:173], v150
	ds_read_b128 v[174:177], v151
	ds_read_b128 v[178:181], v152
	ds_read_b128 v[182:185], v153
	ds_read_b128 v[186:189], v154
	ds_read_b128 v[190:193], v155
	ds_read_b128 v[194:197], v156
	s_add_u32 s54, s52, 0xfffc0080
	s_addc_u32 s55, s53, -1
	s_cmp_eq_u32 s69, 12
	s_cselect_b32 s57, s13, s55
	s_cselect_b32 s56, s49, s54
	s_cselect_b32 s55, s11, s68
	s_cselect_b32 s54, s66, s67
	s_mov_b32 m0, s64
	v_lshl_add_u64 v[232:233], s[52:53], 0, v[138:139]
	ds_read_b128 v[198:201], v147
	ds_read_b128 v[202:205], v147 offset:1024
	ds_read_b128 v[206:209], v147 offset:2048
	ds_read_b128 v[210:213], v147 offset:3072
	ds_read_b128 v[214:217], v147 offset:4096
	ds_read_b128 v[218:221], v147 offset:5120
	ds_read_b128 v[222:225], v147 offset:6144
	ds_read_b128 v[228:231], v147 offset:7168
	global_load_lds_dwordx4 v[232:233], off
	v_lshl_add_u64 v[232:233], s[52:53], 0, v[140:141]
	s_mov_b32 m0, s65
	s_nop 0
	global_load_lds_dwordx4 v[232:233], off
	s_waitcnt vmcnt(8)
	s_waitcnt lgkmcnt(0)
	s_barrier
	s_setprio 1
	s_waitcnt lgkmcnt(0)
	v_mfma_f32_16x16x32_bf16 v[124:127], v[166:169], v[198:201], v[124:127]
	v_mfma_f32_16x16x32_bf16 v[120:123], v[174:177], v[198:201], v[120:123]
	v_mfma_f32_16x16x32_bf16 v[108:111], v[166:169], v[206:209], v[108:111]
	v_mfma_f32_16x16x32_bf16 v[104:107], v[174:177], v[206:209], v[104:107]
	v_mfma_f32_16x16x32_bf16 v[92:95], v[166:169], v[214:217], v[92:95]
	v_mfma_f32_16x16x32_bf16 v[88:91], v[174:177], v[214:217], v[88:91]
	v_mfma_f32_16x16x32_bf16 v[76:79], v[166:169], v[222:225], v[76:79]
	v_mfma_f32_16x16x32_bf16 v[72:75], v[174:177], v[222:225], v[72:75]
	v_mfma_f32_16x16x32_bf16 v[124:127], v[170:173], v[202:205], v[124:127]
	v_mfma_f32_16x16x32_bf16 v[120:123], v[178:181], v[202:205], v[120:123]
	v_mfma_f32_16x16x32_bf16 v[108:111], v[170:173], v[210:213], v[108:111]
	v_mfma_f32_16x16x32_bf16 v[104:107], v[178:181], v[210:213], v[104:107]
	v_mfma_f32_16x16x32_bf16 v[92:95], v[170:173], v[218:221], v[92:95]
	v_mfma_f32_16x16x32_bf16 v[88:91], v[178:181], v[218:221], v[88:91]
	v_mfma_f32_16x16x32_bf16 v[76:79], v[170:173], v[228:231], v[76:79]
	v_mfma_f32_16x16x32_bf16 v[72:75], v[178:181], v[228:231], v[72:75]
	s_setprio 0
	s_setprio 1
	v_mfma_f32_16x16x32_bf16 v[116:119], v[182:185], v[198:201], v[116:119]
	v_mfma_f32_16x16x32_bf16 v[112:115], v[190:193], v[198:201], v[112:115]
	v_mfma_f32_16x16x32_bf16 v[100:103], v[182:185], v[206:209], v[100:103]
	v_mfma_f32_16x16x32_bf16 v[96:99], v[190:193], v[206:209], v[96:99]
	v_mfma_f32_16x16x32_bf16 v[84:87], v[182:185], v[214:217], v[84:87]
	v_mfma_f32_16x16x32_bf16 v[80:83], v[190:193], v[214:217], v[80:83]
	v_mfma_f32_16x16x32_bf16 v[68:71], v[182:185], v[222:225], v[68:71]
	v_mfma_f32_16x16x32_bf16 v[64:67], v[190:193], v[222:225], v[64:67]
	v_mfma_f32_16x16x32_bf16 v[116:119], v[186:189], v[202:205], v[116:119]
	v_mfma_f32_16x16x32_bf16 v[112:115], v[194:197], v[202:205], v[112:115]
	v_mfma_f32_16x16x32_bf16 v[100:103], v[186:189], v[210:213], v[100:103]
	v_mfma_f32_16x16x32_bf16 v[96:99], v[194:197], v[210:213], v[96:99]
	v_mfma_f32_16x16x32_bf16 v[84:87], v[186:189], v[218:221], v[84:87]
	v_mfma_f32_16x16x32_bf16 v[80:83], v[194:197], v[218:221], v[80:83]
	v_mfma_f32_16x16x32_bf16 v[68:71], v[186:189], v[228:231], v[68:71]
	v_mfma_f32_16x16x32_bf16 v[64:67], v[194:197], v[228:231], v[64:67]
	s_setprio 0
	s_barrier
	s_mov_b32 m0, s2
	v_lshl_add_u64 v[232:233], s[54:55], 0, v[130:131]
	s_add_u32 s70, s54, 0x40000
	ds_read_b128 v[198:201], v147 offset:16384
	ds_read_b128 v[202:205], v147 offset:17408
	ds_read_b128 v[206:209], v147 offset:18432
	ds_read_b128 v[210:213], v147 offset:19456
	ds_read_b128 v[214:217], v147 offset:20480
	ds_read_b128 v[218:221], v147 offset:21504
	ds_read_b128 v[222:225], v147 offset:22528
	ds_read_b128 v[228:231], v147 offset:23552
	global_load_lds_dwordx4 v[232:233], off
	v_lshl_add_u64 v[234:235], s[54:55], 0, v[134:135]
	s_mov_b32 m0, s3
	s_addc_u32 s71, s55, 0
	global_load_lds_dwordx4 v[234:235], off
	v_lshl_add_u64 v[236:237], s[70:71], 0, v[130:131]
	s_mov_b32 m0, s20
	v_lshl_add_u64 v[238:239], s[56:57], 0, v[132:133]
	global_load_lds_dwordx4 v[236:237], off
	v_lshl_add_u64 v[236:237], s[70:71], 0, v[134:135]
	s_mov_b32 m0, s21
	s_nop 0
	global_load_lds_dwordx4 v[236:237], off
	v_lshl_add_u64 v[236:237], s[56:57], 0, v[128:129]
	s_mov_b32 m0, s1
	s_nop 0
	global_load_lds_dwordx4 v[236:237], off
	s_mov_b32 m0, s22
	s_nop 0
	global_load_lds_dwordx4 v[238:239], off
	s_waitcnt vmcnt(8)
	s_waitcnt lgkmcnt(0)
	s_barrier
; #define PG8_STAGE(bufoff, gbase, voff) do { _Pragma("unroll") for (int _i = 0; _i < 2; ++_i) \
;         __builtin_amdgcn_global_load_lds((const unsigned*)((const char*)(gbase) + (voff)[_i]), (PG8_LAS unsigned*)(lds + (bufoff) + ldsw + _i * 8192), 16, 0, 0); } while (0)
; #define PG8_LDA(dst, b, h) do { _Pragma("unroll") for (int m = 0; m < 4; ++m) _Pragma("unroll") for (int k = 0; k < 2; ++k) dst[m][k] = *(const PG8_LAS bf16x8*)(lds + PG8_SA(b, h) + aoff + m * 2048 + k * 1024); } while (0)
; #define PG8_LDB(dst, b, h) do { _Pragma("unroll") for (int n = 0; n < 2; ++n) _Pragma("unroll") for (int k = 0; k < 2; ++k) dst[n][k] = *(const PG8_LAS bf16x8*)(lds + PG8_SB(b, h) + boff + n * 2048 + k * 1024); } while (0)
; #define PG8_MMA(ai, bj, At, Bt) do { __builtin_amdgcn_s_setprio(1); _Pragma("unroll") for (int m = 0; m < 4; ++m) _Pragma("unroll") for (int n = 0; n < 2; ++n) _Pragma("unroll") for (int k = 0; k < 2; ++k) \
;         acc[ai][bj][m][n] = mma16<F16>(Bt[n][k], At[m][k], acc[ai][bj][m][n]); __builtin_amdgcn_s_setprio(0); } while (0)
; #define PG8_WAIT_V(n) asm volatile("s_waitcnt vmcnt(" #n ")" ::: "memory")
; #define PG8_WAIT_L(n) asm volatile("s_waitcnt lgkmcnt(" #n ")" ::: "memory")
; #define PG8_BAR __builtin_amdgcn_s_barrier()
; #define PG8_SCHED __builtin_amdgcn_sched_barrier(0)
; template <class Epi, class Sched, bool ALIGN_EPI = false, bool SP2 = false, bool F16 = false, bool TOKPERM = false>
; __device__ __forceinline__ void gemm_phase(PG8_LAS unsigned char* lds, const Gemm g, const Sched& S, const Epi& E, int wv) {
;     ...
;             PG8_WAIT_V(8); PG8_WAIT_L(0); PG8_BAR; PG8_MMA(1, 0, At, B0); PG8_MMA(1, 1, At, B1); PG8_BAR; PG8_SCHED;
;             PG8_LDB(B0, 1, 0); PG8_LDB(B1, 1, 1); PG8_SCHED; PG8_LDA(At, 1, 0); PG8_STAGE(PG8_SA(0, 1), a2 + hstep, voffA);
;             PG8_WAIT_V(8); PG8_WAIT_L(0); PG8_BAR; PG8_MMA(0, 0, At, B0); PG8_MMA(0, 1, At, B1); PG8_BAR; PG8_SCHED;
	s_setprio 1
	s_waitcnt lgkmcnt(0)
	v_mfma_f32_16x16x32_bf16 v[60:63], v[166:169], v[198:201], v[60:63]
	v_mfma_f32_16x16x32_bf16 v[56:59], v[174:177], v[198:201], v[56:59]
	v_mfma_f32_16x16x32_bf16 v[44:47], v[166:169], v[206:209], v[44:47]
	v_mfma_f32_16x16x32_bf16 v[40:43], v[174:177], v[206:209], v[40:43]
	v_mfma_f32_16x16x32_bf16 v[28:31], v[166:169], v[214:217], v[28:31]
	v_mfma_f32_16x16x32_bf16 v[24:27], v[174:177], v[214:217], v[24:27]
	v_mfma_f32_16x16x32_bf16 v[12:15], v[166:169], v[222:225], v[12:15]
	v_mfma_f32_16x16x32_bf16 v[8:11], v[174:177], v[222:225], v[8:11]
	v_mfma_f32_16x16x32_bf16 v[60:63], v[170:173], v[202:205], v[60:63]
	v_mfma_f32_16x16x32_bf16 v[56:59], v[178:181], v[202:205], v[56:59]
	v_mfma_f32_16x16x32_bf16 v[44:47], v[170:173], v[210:213], v[44:47]
	v_mfma_f32_16x16x32_bf16 v[40:43], v[178:181], v[210:213], v[40:43]
	v_mfma_f32_16x16x32_bf16 v[28:31], v[170:173], v[218:221], v[28:31]
	v_mfma_f32_16x16x32_bf16 v[24:27], v[178:181], v[218:221], v[24:27]
	v_mfma_f32_16x16x32_bf16 v[12:15], v[170:173], v[228:231], v[12:15]
	v_mfma_f32_16x16x32_bf16 v[8:11], v[178:181], v[228:231], v[8:11]
	s_setprio 0
	s_setprio 1
	v_mfma_f32_16x16x32_bf16 v[52:55], v[182:185], v[198:201], v[52:55]
	v_mfma_f32_16x16x32_bf16 v[48:51], v[190:193], v[198:201], v[48:51]
	v_mfma_f32_16x16x32_bf16 v[36:39], v[182:185], v[206:209], v[36:39]
	v_mfma_f32_16x16x32_bf16 v[32:35], v[190:193], v[206:209], v[32:35]
	v_mfma_f32_16x16x32_bf16 v[20:23], v[182:185], v[214:217], v[20:23]
	v_mfma_f32_16x16x32_bf16 v[16:19], v[190:193], v[214:217], v[16:19]
	v_mfma_f32_16x16x32_bf16 v[4:7], v[182:185], v[222:225], v[4:7]
	v_mfma_f32_16x16x32_bf16 v[0:3], v[190:193], v[222:225], v[0:3]
	v_mfma_f32_16x16x32_bf16 v[52:55], v[186:189], v[202:205], v[52:55]
	v_mfma_f32_16x16x32_bf16 v[48:51], v[194:197], v[202:205], v[48:51]
	v_mfma_f32_16x16x32_bf16 v[36:39], v[186:189], v[210:213], v[36:39]
	v_mfma_f32_16x16x32_bf16 v[32:35], v[194:197], v[210:213], v[32:35]
	v_mfma_f32_16x16x32_bf16 v[20:23], v[186:189], v[218:221], v[20:23]
	v_mfma_f32_16x16x32_bf16 v[16:19], v[194:197], v[218:221], v[16:19]
	v_mfma_f32_16x16x32_bf16 v[4:7], v[186:189], v[228:231], v[4:7]
	v_mfma_f32_16x16x32_bf16 v[0:3], v[194:197], v[228:231], v[0:3]
	s_setprio 0
	s_barrier
	ds_read_b128 v[166:169], v157
	ds_read_b128 v[170:173], v158
	ds_read_b128 v[174:177], v159
	ds_read_b128 v[178:181], v160
	ds_read_b128 v[182:185], v161
	ds_read_b128 v[186:189], v162
	ds_read_b128 v[190:193], v163
	ds_read_b128 v[194:197], v164
	s_add_u32 s56, s56, 0x40000
	s_addc_u32 s57, s57, 0
	s_mov_b32 m0, s23
	v_lshl_add_u64 v[240:241], s[56:57], 0, v[128:129]
	ds_read_b128 v[198:201], v147 offset:32768
	ds_read_b128 v[202:205], v147 offset:33792
	ds_read_b128 v[206:209], v147 offset:34816
	ds_read_b128 v[210:213], v147 offset:35840
	ds_read_b128 v[214:217], v147 offset:36864
	ds_read_b128 v[218:221], v147 offset:37888
	ds_read_b128 v[222:225], v147 offset:38912
	ds_read_b128 v[228:231], v147 offset:39936
	global_load_lds_dwordx4 v[240:241], off
	v_lshl_add_u64 v[240:241], s[56:57], 0, v[132:133]
	s_mov_b32 m0, s33
	s_nop 0
	global_load_lds_dwordx4 v[240:241], off
	s_waitcnt vmcnt(8)
	s_waitcnt lgkmcnt(0)
	s_barrier
	s_setprio 1
	s_waitcnt lgkmcnt(0)
	v_mfma_f32_16x16x32_bf16 v[124:127], v[166:169], v[198:201], v[124:127]
	v_mfma_f32_16x16x32_bf16 v[120:123], v[174:177], v[198:201], v[120:123]
	v_mfma_f32_16x16x32_bf16 v[108:111], v[166:169], v[206:209], v[108:111]
	v_mfma_f32_16x16x32_bf16 v[104:107], v[174:177], v[206:209], v[104:107]
	v_mfma_f32_16x16x32_bf16 v[92:95], v[166:169], v[214:217], v[92:95]
	v_mfma_f32_16x16x32_bf16 v[88:91], v[174:177], v[214:217], v[88:91]
	v_mfma_f32_16x16x32_bf16 v[76:79], v[166:169], v[222:225], v[76:79]
	v_mfma_f32_16x16x32_bf16 v[72:75], v[174:177], v[222:225], v[72:75]
	v_mfma_f32_16x16x32_bf16 v[124:127], v[170:173], v[202:205], v[124:127]
	v_mfma_f32_16x16x32_bf16 v[120:123], v[178:181], v[202:205], v[120:123]
	v_mfma_f32_16x16x32_bf16 v[108:111], v[170:173], v[210:213], v[108:111]
	v_mfma_f32_16x16x32_bf16 v[104:107], v[178:181], v[210:213], v[104:107]
	v_mfma_f32_16x16x32_bf16 v[92:95], v[170:173], v[218:221], v[92:95]
	v_mfma_f32_16x16x32_bf16 v[88:91], v[178:181], v[218:221], v[88:91]
	v_mfma_f32_16x16x32_bf16 v[76:79], v[170:173], v[228:231], v[76:79]
	v_mfma_f32_16x16x32_bf16 v[72:75], v[178:181], v[228:231], v[72:75]
	s_setprio 0
	s_setprio 1
	v_mfma_f32_16x16x32_bf16 v[116:119], v[182:185], v[198:201], v[116:119]
	v_mfma_f32_16x16x32_bf16 v[112:115], v[190:193], v[198:201], v[112:115]
	v_mfma_f32_16x16x32_bf16 v[100:103], v[182:185], v[206:209], v[100:103]
	v_mfma_f32_16x16x32_bf16 v[96:99], v[190:193], v[206:209], v[96:99]
	v_mfma_f32_16x16x32_bf16 v[84:87], v[182:185], v[214:217], v[84:87]
	v_mfma_f32_16x16x32_bf16 v[80:83], v[190:193], v[214:217], v[80:83]
	v_mfma_f32_16x16x32_bf16 v[68:71], v[182:185], v[222:225], v[68:71]
	v_mfma_f32_16x16x32_bf16 v[64:67], v[190:193], v[222:225], v[64:67]
	v_mfma_f32_16x16x32_bf16 v[116:119], v[186:189], v[202:205], v[116:119]
	v_mfma_f32_16x16x32_bf16 v[112:115], v[194:197], v[202:205], v[112:115]
	v_mfma_f32_16x16x32_bf16 v[100:103], v[186:189], v[210:213], v[100:103]
	v_mfma_f32_16x16x32_bf16 v[96:99], v[194:197], v[210:213], v[96:99]
	v_mfma_f32_16x16x32_bf16 v[84:87], v[186:189], v[218:221], v[84:87]
	v_mfma_f32_16x16x32_bf16 v[80:83], v[194:197], v[218:221], v[80:83]
	v_mfma_f32_16x16x32_bf16 v[68:71], v[186:189], v[228:231], v[68:71]
	v_mfma_f32_16x16x32_bf16 v[64:67], v[194:197], v[228:231], v[64:67]
	s_setprio 0
	s_barrier
; #define PG8_STAGE(bufoff, gbase, voff) do { _Pragma("unroll") for (int _i = 0; _i < 2; ++_i) \
;         __builtin_amdgcn_global_load_lds((const unsigned*)((const char*)(gbase) + (voff)[_i]), (PG8_LAS unsigned*)(lds + (bufoff) + ldsw + _i * 8192), 16, 0, 0); } while (0)
; #define PG8_LDA(dst, b, h) do { _Pragma("unroll") for (int m = 0; m < 4; ++m) _Pragma("unroll") for (int k = 0; k < 2; ++k) dst[m][k] = *(const PG8_LAS bf16x8*)(lds + PG8_SA(b, h) + aoff + m * 2048 + k * 1024); } while (0)
; #define PG8_MMA(ai, bj, At, Bt) do { __builtin_amdgcn_s_setprio(1); _Pragma("unroll") for (int m = 0; m < 4; ++m) _Pragma("unroll") for (int n = 0; n < 2; ++n) _Pragma("unroll") for (int k = 0; k < 2; ++k) \
;         acc[ai][bj][m][n] = mma16<F16>(Bt[n][k], At[m][k], acc[ai][bj][m][n]); __builtin_amdgcn_s_setprio(0); } while (0)
; #define PG8_WAIT_V(n) asm volatile("s_waitcnt vmcnt(" #n ")" ::: "memory")
; #define PG8_WAIT_L(n) asm volatile("s_waitcnt lgkmcnt(" #n ")" ::: "memory")
; #define PG8_BAR __builtin_amdgcn_s_barrier()
; #define PG8_SCHED __builtin_amdgcn_sched_barrier(0)
; template <class Epi, class Sched, bool ALIGN_EPI = false, bool SP2 = false, bool F16 = false, bool TOKPERM = false>
; __device__ __forceinline__ void gemm_phase(PG8_LAS unsigned char* lds, const Gemm g, const Sched& S, const Epi& E, int wv) {
;     ...
;             PG8_LDA(At, 1, 1); PG8_STAGE(PG8_SB(1, 0), b3, voffB); PG8_STAGE(PG8_SB(1, 1), b3 + hstep, voffB); PG8_STAGE(PG8_SA(1, 0), a3, voffA);
;             PG8_WAIT_V(8); PG8_WAIT_L(0); PG8_BAR; PG8_MMA(1, 0, At, B0); PG8_MMA(1, 1, At, B1); PG8_BAR; PG8_SCHED;
;   __device__ __forceinline__ void operator()(const pg8::f32x4 (&acc)[2][2][4][2], const pg8::Unit& u, int wr, int wc, int fr, int fq) const {
;     ...
;     const int row0 = u.pm * 256 + wr * 64 + fr + z, colb = u.pn * 256 + wc * 32 + 8 * fq + z;
; #pragma unroll
;     for (int ai = 0; ai < 2; ++ai)
; #pragma unroll
;       for (int m = 0; m < 4; ++m) {
;         const int tok = row0 + ai * 128 + m * 16; float ss = 0.f;
; #pragma unroll
;         for (int bj = 0; bj < 2; ++bj) {
;           const unsigned off = (unsigned)tok * DM + colb + 128 * bj;
;           f8_t n = __builtin_convertvector(*(const h8_t*)(x16 + off), f8_t);
	s_mov_b32 m0, s37
	v_lshl_add_u64 v[232:233], v[232:233], 0, s[8:9]
	s_add_u32 s54, s54, 0x40080
	ds_read_b128 v[198:201], v147 offset:49152
	ds_read_b128 v[202:205], v147 offset:50176
	ds_read_b128 v[206:209], v147 offset:51200
	ds_read_b128 v[210:213], v147 offset:52224
	ds_read_b128 v[214:217], v147 offset:53248
	ds_read_b128 v[218:221], v147 offset:54272
	ds_read_b128 v[222:225], v147 offset:55296
	ds_read_b128 v[228:231], v147 offset:56320
	global_load_lds_dwordx4 v[232:233], off
	v_lshl_add_u64 v[232:233], v[234:235], 0, s[8:9]
	s_mov_b32 m0, s44
	s_addc_u32 s55, s55, 0
	global_load_lds_dwordx4 v[232:233], off
	v_lshl_add_u64 v[232:233], s[54:55], 0, v[130:131]
	s_mov_b32 m0, s58
	s_nop 0
	global_load_lds_dwordx4 v[232:233], off
	v_lshl_add_u64 v[232:233], s[54:55], 0, v[134:135]
	s_mov_b32 m0, s59
	s_nop 0
	global_load_lds_dwordx4 v[232:233], off
	v_lshl_add_u64 v[232:233], v[236:237], 0, s[8:9]
	s_mov_b32 m0, s45
	s_nop 0
	global_load_lds_dwordx4 v[232:233], off
	v_lshl_add_u64 v[232:233], v[238:239], 0, s[8:9]
	s_mov_b32 m0, s51
	s_nop 0
	global_load_lds_dwordx4 v[232:233], off
	s_waitcnt vmcnt(8)
	s_waitcnt lgkmcnt(0)
	s_barrier
	s_setprio 1
	s_waitcnt lgkmcnt(0)
	v_mfma_f32_16x16x32_bf16 v[60:63], v[166:169], v[198:201], v[60:63]
	v_mfma_f32_16x16x32_bf16 v[56:59], v[174:177], v[198:201], v[56:59]
	v_mfma_f32_16x16x32_bf16 v[44:47], v[166:169], v[206:209], v[44:47]
	v_mfma_f32_16x16x32_bf16 v[40:43], v[174:177], v[206:209], v[40:43]
	v_mfma_f32_16x16x32_bf16 v[28:31], v[166:169], v[214:217], v[28:31]
	v_mfma_f32_16x16x32_bf16 v[24:27], v[174:177], v[214:217], v[24:27]
	v_mfma_f32_16x16x32_bf16 v[12:15], v[166:169], v[222:225], v[12:15]
	v_mfma_f32_16x16x32_bf16 v[8:11], v[174:177], v[222:225], v[8:11]
	v_mfma_f32_16x16x32_bf16 v[60:63], v[170:173], v[202:205], v[60:63]
	v_mfma_f32_16x16x32_bf16 v[56:59], v[178:181], v[202:205], v[56:59]
	v_mfma_f32_16x16x32_bf16 v[44:47], v[170:173], v[210:213], v[44:47]
	v_mfma_f32_16x16x32_bf16 v[40:43], v[178:181], v[210:213], v[40:43]
	v_mfma_f32_16x16x32_bf16 v[28:31], v[170:173], v[218:221], v[28:31]
	v_mfma_f32_16x16x32_bf16 v[24:27], v[178:181], v[218:221], v[24:27]
	v_mfma_f32_16x16x32_bf16 v[12:15], v[170:173], v[228:231], v[12:15]
	v_mfma_f32_16x16x32_bf16 v[8:11], v[178:181], v[228:231], v[8:11]
	s_setprio 0
	s_setprio 1
	v_mfma_f32_16x16x32_bf16 v[52:55], v[182:185], v[198:201], v[52:55]
	v_mfma_f32_16x16x32_bf16 v[48:51], v[190:193], v[198:201], v[48:51]
	v_mfma_f32_16x16x32_bf16 v[36:39], v[182:185], v[206:209], v[36:39]
	v_mfma_f32_16x16x32_bf16 v[32:35], v[190:193], v[206:209], v[32:35]
	v_mfma_f32_16x16x32_bf16 v[20:23], v[182:185], v[214:217], v[20:23]
	v_mfma_f32_16x16x32_bf16 v[16:19], v[190:193], v[214:217], v[16:19]
	v_mfma_f32_16x16x32_bf16 v[4:7], v[182:185], v[222:225], v[4:7]
	v_mfma_f32_16x16x32_bf16 v[0:3], v[190:193], v[222:225], v[0:3]
	v_mfma_f32_16x16x32_bf16 v[52:55], v[186:189], v[202:205], v[52:55]
	v_mfma_f32_16x16x32_bf16 v[48:51], v[194:197], v[202:205], v[48:51]
	v_mfma_f32_16x16x32_bf16 v[36:39], v[186:189], v[210:213], v[36:39]
	v_mfma_f32_16x16x32_bf16 v[32:35], v[194:197], v[210:213], v[32:35]
	v_mfma_f32_16x16x32_bf16 v[20:23], v[186:189], v[218:221], v[20:23]
	v_mfma_f32_16x16x32_bf16 v[16:19], v[194:197], v[218:221], v[16:19]
	v_mfma_f32_16x16x32_bf16 v[4:7], v[186:189], v[228:231], v[4:7]
	v_mfma_f32_16x16x32_bf16 v[0:3], v[194:197], v[228:231], v[0:3]
	s_setprio 0
	s_barrier
	s_add_i32 s69, s69, 2
	s_add_u32 s52, s52, 0x100
	s_addc_u32 s53, s53, 0
	s_add_u32 s67, s67, 0x100
	s_addc_u32 s68, s68, 0
	s_cmp_gt_u32 s69, 13
	s_cbranch_scc0 .LBB0_685
	s_lshl_b32 s11, s50, 8
	v_lshl_or_b32 v166, s48, 8, v148
	v_mov_b32 v136, 0
	v_xor_b32_e32 v169, 32, v165
	v_add3_u32 v167, s11, v146, v136
	v_add_u32_e32 v168, v166, v136
	v_lshl_add_u32 v136, v167, 10, v168
	v_lshl_add_u64 v[178:179], v[136:137], 1, s[40:41]
	v_add_u32_e32 v136, 0x80, v136
	global_load_dwordx4 v[170:173], v[178:179], off
	v_lshl_add_u64 v[180:181], v[136:137], 1, s[40:41]
	global_load_dwordx4 v[174:177], v[180:181], off
	v_add_u32_e32 v136, 16, v167
	v_lshl_add_u32 v136, v136, 10, v168
	v_lshl_add_u64 v[224:225], v[136:137], 1, s[40:41]
	v_add_u32_e32 v136, 0x80, v136
	global_load_dwordx4 v[192:195], v[224:225], off
	v_lshl_add_u64 v[248:249], v[136:137], 1, s[40:41]
	global_load_dwordx4 v[196:199], v[248:249], off
	v_add_u32_e32 v136, 32, v167
	v_lshl_add_u32 v136, v136, 10, v168
	v_lshl_add_u64 v[224:225], v[136:137], 1, s[40:41]
	v_add_u32_e32 v136, 0x80, v136
	global_load_dwordx4 v[200:203], v[224:225], off
	v_lshl_add_u64 v[248:249], v[136:137], 1, s[40:41]
	global_load_dwordx4 v[204:207], v[248:249], off
	v_add_u32_e32 v136, 48, v167
	v_lshl_add_u32 v136, v136, 10, v168
	v_lshl_add_u64 v[224:225], v[136:137], 1, s[40:41]
	v_add_u32_e32 v136, 0x80, v136
	global_load_dwordx4 v[208:211], v[224:225], off
	v_lshl_add_u64 v[248:249], v[136:137], 1, s[40:41]
	global_load_dwordx4 v[212:215], v[248:249], off
	v_add_u32_e32 v136, 0x80, v167
	v_lshl_add_u32 v136, v136, 10, v168
	v_lshl_add_u64 v[224:225], v[136:137], 1, s[40:41]
	v_add_u32_e32 v136, 0x80, v136
	global_load_dwordx4 v[216:219], v[224:225], off
	v_lshl_add_u64 v[248:249], v[136:137], 1, s[40:41]
	global_load_dwordx4 v[220:223], v[248:249], off
	v_add_u32_e32 v136, 0x90, v167
	v_lshl_add_u32 v136, v136, 10, v168
	v_lshl_add_u64 v[224:225], v[136:137], 1, s[40:41]
	v_add_u32_e32 v136, 0x80, v136
	global_load_dwordx4 v[228:231], v[224:225], off
	v_lshl_add_u64 v[248:249], v[136:137], 1, s[40:41]
	global_load_dwordx4 v[244:247], v[248:249], off
	v_and_b32_e32 v166, 64, v165
	v_xor_b32_e32 v136, 16, v165
	v_add_u32_e32 v166, 64, v166
	v_cmp_lt_i32_e32 vcc, v136, v166
	s_lshl_b32 s11, s48, 2
	s_or_b32 s11, s11, s36
	v_cndmask_b32_e32 v136, v165, v136, vcc
	v_cmp_lt_i32_e32 vcc, v169, v166
	v_lshlrev_b32_e32 v166, 2, v136
	s_waitcnt vmcnt(10)
;   __device__ __forceinline__ void operator()(const pg8::f32x4 (&acc)[2][2][4][2], const pg8::Unit& u, int wr, int wc, int fr, int fq) const {
;     ...
;         const int tok = row0 + ai * 128 + m * 16; float ss = 0.f;
; #pragma unroll
;         for (int bj = 0; bj < 2; ++bj) {
;           const unsigned off = (unsigned)tok * DM + colb + 128 * bj;
;           f8_t n = __builtin_convertvector(*(const h8_t*)(x16 + off), f8_t);
; #pragma unroll
;           for (int c = 0; c < 4; ++c) { n[c] += sc * acc[ai][bj][m][0][c]; n[4 + c] += sc * acc[ai][bj][m][1][c]; }
;           if (aux) {
;             *(h8_t*)(x16 + off) = __builtin_convertvector(n, h8_t);
;             ss += ((n[0] * n[0] + n[1] * n[1]) + (n[2] * n[2] + n[3] * n[3])) + ((n[4] * n[4] + n[5] * n[5]) + (n[6] * n[6] + n[7] * n[7]));
;           } else {
;             *(f32x4*)(xout + off) = (f32x4){n[0], n[1], n[2], n[3]}; *(f32x4*)(xout + off + 4) = (f32x4){n[4], n[5], n[6], n[7]};
;           }
;         }
;         if (aux) { ss += __shfl_xor(ss, 16); ss += __shfl_xor(ss, 32); if (fq == 0) ssq[(unsigned)tok * 16 + u.pn * 4 + wc] = ss; }
	v_cvt_f32_f16_e32 v182, v173
	v_cvt_f32_f16_sdwa v183, v173 dst_sel:DWORD dst_unused:UNUSED_PAD src0_sel:WORD_1
	v_cvt_f32_f16_e32 v184, v171
	v_cvt_f32_f16_sdwa v185, v171 dst_sel:DWORD dst_unused:UNUSED_PAD src0_sel:WORD_1
	v_cvt_f32_f16_e32 v186, v172
	v_cvt_f32_f16_sdwa v187, v172 dst_sel:DWORD dst_unused:UNUSED_PAD src0_sel:WORD_1
	v_cvt_f32_f16_e32 v172, v170
	v_cvt_f32_f16_sdwa v173, v170 dst_sel:DWORD dst_unused:UNUSED_PAD src0_sel:WORD_1
	v_cvt_f32_f16_e32 v170, v177
	v_cvt_f32_f16_sdwa v171, v177 dst_sel:DWORD dst_unused:UNUSED_PAD src0_sel:WORD_1
	v_cvt_f32_f16_e32 v188, v175
	v_cvt_f32_f16_sdwa v189, v175 dst_sel:DWORD dst_unused:UNUSED_PAD src0_sel:WORD_1
	v_cvt_f32_f16_e32 v190, v176
	v_cvt_f32_f16_sdwa v191, v176 dst_sel:DWORD dst_unused:UNUSED_PAD src0_sel:WORD_1
	v_cvt_f32_f16_e32 v176, v174
	v_cvt_f32_f16_sdwa v177, v174 dst_sel:DWORD dst_unused:UNUSED_PAD src0_sel:WORD_1
	v_pk_add_f32 v[124:125], v[124:125], v[172:173]
	v_pk_add_f32 v[172:173], v[120:121], v[186:187]
	v_pk_add_f32 v[126:127], v[126:127], v[184:185]
	v_pk_add_f32 v[122:123], v[122:123], v[182:183]
	v_cvt_pk_f16_f32 v120, v172, v173
	v_cvt_pk_f16_f32 v121, v122, v123
	v_pk_mul_f32 v[174:175], v[124:125], v[124:125]
	v_pk_mul_f32 v[182:183], v[126:127], v[126:127]
	v_pk_mul_f32 v[172:173], v[172:173], v[172:173]
	v_pk_mul_f32 v[122:123], v[122:123], v[122:123]
	v_pk_add_f32 v[176:177], v[116:117], v[176:177]
	v_pk_add_f32 v[116:117], v[112:113], v[190:191]
	v_pk_add_f32 v[184:185], v[118:119], v[188:189]
	v_pk_add_f32 v[112:113], v[114:115], v[170:171]
	v_pk_mul_f32 v[114:115], v[176:177], v[176:177]
	v_pk_mul_f32 v[118:119], v[184:185], v[184:185]
	v_pk_mul_f32 v[170:171], v[116:117], v[116:117]
	v_pk_mul_f32 v[186:187], v[112:113], v[112:113]
	v_add_f32_e32 v122, v122, v123
	v_add_f32_e32 v123, v172, v173
	v_add_f32_e32 v136, v182, v183
	v_add_f32_e32 v172, v174, v175
	v_add_f32_e32 v122, v123, v122
	v_add_f32_e32 v123, v172, v136
	v_add_f32_e32 v136, v186, v187
	v_add_f32_e32 v170, v170, v171
	v_add_f32_e32 v118, v118, v119
	v_add_f32_e32 v114, v114, v115
	v_add_f32_e32 v119, v170, v136
	v_add_f32_e32 v114, v114, v118
	v_add_f32_e32 v115, v123, v122
	v_add_f32_e32 v114, v114, v119
	v_add_f32_e32 v114, v115, v114
	v_mov_b32_e32 v115, v114
	s_nop 1
	v_permlane16_swap_b32_e32 v114, v115
	v_cndmask_b32_e32 v169, v165, v169, vcc
	v_cvt_pk_f16_f32 v119, v126, v127
	v_cvt_pk_f16_f32 v118, v124, v125
	global_store_dwordx4 v[178:179], v[118:121], off
	s_nop 1
	v_cvt_pk_f16_f32 v119, v112, v113
	s_waitcnt lgkmcnt(0)
	v_add_f32_e32 v113, v114, v115
	v_lshlrev_b32_e32 v112, 2, v169
	v_mov_b32_e32 v114, v113
	s_nop 1
	v_permlane32_swap_b32_e32 v113, v114
	v_cvt_pk_f16_f32 v118, v116, v117
	v_cvt_pk_f16_f32 v117, v184, v185
	v_cvt_pk_f16_f32 v116, v176, v177
	global_store_dwordx4 v[180:181], v[116:119], off
	s_and_saveexec_b64 s[48:49], s[4:5]
	s_cbranch_execz .LBB0_688
	v_lshl_add_u32 v136, v167, 4, s11
	s_waitcnt lgkmcnt(0)
	v_add_f32_e32 v113, v113, v114
	v_lshl_add_u64 v[114:115], v[136:137], 2, s[42:43]
	global_store_dword v[114:115], v113, off
.LBB0_688:
	s_or_b64 exec, exec, s[48:49]
	v_add_u32_e32 v113, 16, v167
	v_lshl_add_u32 v136, v113, 10, v168
	v_lshl_add_u64 v[122:123], v[136:137], 1, s[40:41]
	v_add_u32_e32 v136, 0x80, v136
	v_lshl_add_u64 v[124:125], v[136:137], 1, s[40:41]
	s_waitcnt lgkmcnt(0)
	s_waitcnt vmcnt(10)
	v_cvt_f32_f16_e32 v126, v195
	v_cvt_f32_f16_sdwa v127, v195 dst_sel:DWORD dst_unused:UNUSED_PAD src0_sel:WORD_1
	v_cvt_f32_f16_e32 v170, v193
	v_cvt_f32_f16_sdwa v171, v193 dst_sel:DWORD dst_unused:UNUSED_PAD src0_sel:WORD_1
	v_cvt_f32_f16_e32 v172, v194
	v_cvt_f32_f16_sdwa v173, v194 dst_sel:DWORD dst_unused:UNUSED_PAD src0_sel:WORD_1
	v_cvt_f32_f16_e32 v116, v192
	v_cvt_f32_f16_sdwa v117, v192 dst_sel:DWORD dst_unused:UNUSED_PAD src0_sel:WORD_1
	v_cvt_f32_f16_e32 v114, v199
	v_cvt_f32_f16_sdwa v115, v199 dst_sel:DWORD dst_unused:UNUSED_PAD src0_sel:WORD_1
	v_cvt_f32_f16_e32 v174, v197
	v_cvt_f32_f16_sdwa v175, v197 dst_sel:DWORD dst_unused:UNUSED_PAD src0_sel:WORD_1
	v_cvt_f32_f16_e32 v176, v198
	v_cvt_f32_f16_sdwa v177, v198 dst_sel:DWORD dst_unused:UNUSED_PAD src0_sel:WORD_1
	v_cvt_f32_f16_e32 v120, v196
	v_cvt_f32_f16_sdwa v121, v196 dst_sel:DWORD dst_unused:UNUSED_PAD src0_sel:WORD_1
	v_pk_add_f32 v[108:109], v[108:109], v[116:117]
	v_pk_add_f32 v[116:117], v[104:105], v[172:173]
	v_pk_add_f32 v[110:111], v[110:111], v[170:171]
	v_pk_add_f32 v[106:107], v[106:107], v[126:127]
	v_pk_add_f32 v[120:121], v[100:101], v[120:121]
	v_pk_add_f32 v[170:171], v[96:97], v[176:177]
	v_pk_add_f32 v[172:173], v[102:103], v[174:175]
	v_pk_add_f32 v[96:97], v[98:99], v[114:115]
	v_cvt_pk_f16_f32 v105, v106, v107
	v_cvt_pk_f16_f32 v104, v116, v117
	v_pk_mul_f32 v[118:119], v[108:109], v[108:109]
	v_pk_mul_f32 v[126:127], v[110:111], v[110:111]
	v_pk_mul_f32 v[116:117], v[116:117], v[116:117]
	v_pk_mul_f32 v[106:107], v[106:107], v[106:107]
	v_pk_mul_f32 v[98:99], v[120:121], v[120:121]
	v_pk_mul_f32 v[100:101], v[172:173], v[172:173]
	v_pk_mul_f32 v[102:103], v[170:171], v[170:171]
	v_pk_mul_f32 v[114:115], v[96:97], v[96:97]
	v_add_f32_e32 v106, v106, v107
	v_add_f32_e32 v107, v116, v117
	v_add_f32_e32 v116, v126, v127
	v_add_f32_e32 v117, v118, v119
	v_add_f32_e32 v114, v114, v115
	v_add_f32_e32 v102, v102, v103
	v_add_f32_e32 v100, v100, v101
	v_add_f32_e32 v98, v98, v99
	v_add_f32_e32 v106, v107, v106
	v_add_f32_e32 v107, v117, v116
	v_add_f32_e32 v101, v102, v114
	v_add_f32_e32 v98, v98, v100
	v_add_f32_e32 v99, v107, v106
	v_add_f32_e32 v98, v98, v101
	v_add_f32_e32 v98, v99, v98
	v_mov_b32_e32 v99, v98
	s_nop 1
	v_permlane16_swap_b32_e32 v98, v99
	v_cvt_pk_f16_f32 v101, v96, v97
	v_cvt_pk_f16_f32 v103, v110, v111
	v_cvt_pk_f16_f32 v102, v108, v109
	v_cvt_pk_f16_f32 v100, v170, v171
	s_waitcnt lgkmcnt(0)
	v_add_f32_e32 v96, v98, v99
	v_mov_b32_e32 v97, v96
	s_nop 1
	v_permlane32_swap_b32_e32 v96, v97
	v_cvt_pk_f16_f32 v99, v172, v173
	v_cvt_pk_f16_f32 v98, v120, v121
	global_store_dwordx4 v[122:123], v[102:105], off
	global_store_dwordx4 v[124:125], v[98:101], off
	s_and_saveexec_b64 s[48:49], s[4:5]
	s_cbranch_execz .LBB0_690
	v_lshl_add_u32 v136, v113, 4, s11
	s_waitcnt lgkmcnt(0)
	v_add_f32_e32 v98, v96, v97
	v_lshl_add_u64 v[96:97], v[136:137], 2, s[42:43]
	global_store_dword v[96:97], v98, off
;   __device__ __forceinline__ void operator()(const pg8::f32x4 (&acc)[2][2][4][2], const pg8::Unit& u, int wr, int wc, int fr, int fq) const {
;     ...
;         const int tok = row0 + ai * 128 + m * 16; float ss = 0.f;
; #pragma unroll
;         for (int bj = 0; bj < 2; ++bj) {
;           const unsigned off = (unsigned)tok * DM + colb + 128 * bj;
;           f8_t n = __builtin_convertvector(*(const h8_t*)(x16 + off), f8_t);
; #pragma unroll
;           for (int c = 0; c < 4; ++c) { n[c] += sc * acc[ai][bj][m][0][c]; n[4 + c] += sc * acc[ai][bj][m][1][c]; }
;           if (aux) {
;             *(h8_t*)(x16 + off) = __builtin_convertvector(n, h8_t);
;             ss += ((n[0] * n[0] + n[1] * n[1]) + (n[2] * n[2] + n[3] * n[3])) + ((n[4] * n[4] + n[5] * n[5]) + (n[6] * n[6] + n[7] * n[7]));
;           } else {
;             *(f32x4*)(xout + off) = (f32x4){n[0], n[1], n[2], n[3]}; *(f32x4*)(xout + off + 4) = (f32x4){n[4], n[5], n[6], n[7]};
;           }
;         }
;         if (aux) { ss += __shfl_xor(ss, 16); ss += __shfl_xor(ss, 32); if (fq == 0) ssq[(unsigned)tok * 16 + u.pn * 4 + wc] = ss; }
.LBB0_690:
	s_or_b64 exec, exec, s[48:49]
	v_add_u32_e32 v96, 32, v167
	v_lshl_add_u32 v136, v96, 10, v168
	v_lshl_add_u64 v[106:107], v[136:137], 1, s[40:41]
	v_add_u32_e32 v136, 0x80, v136
	v_lshl_add_u64 v[108:109], v[136:137], 1, s[40:41]
	s_waitcnt vmcnt(10)
	v_cvt_f32_f16_e32 v110, v203
	v_cvt_f32_f16_sdwa v111, v203 dst_sel:DWORD dst_unused:UNUSED_PAD src0_sel:WORD_1
	v_cvt_f32_f16_e32 v114, v201
	v_cvt_f32_f16_sdwa v115, v201 dst_sel:DWORD dst_unused:UNUSED_PAD src0_sel:WORD_1
	v_cvt_f32_f16_e32 v116, v202
	v_cvt_f32_f16_sdwa v117, v202 dst_sel:DWORD dst_unused:UNUSED_PAD src0_sel:WORD_1
	v_cvt_f32_f16_e32 v100, v200
	v_cvt_f32_f16_sdwa v101, v200 dst_sel:DWORD dst_unused:UNUSED_PAD src0_sel:WORD_1
	v_cvt_f32_f16_e32 v98, v207
	v_cvt_f32_f16_sdwa v99, v207 dst_sel:DWORD dst_unused:UNUSED_PAD src0_sel:WORD_1
	v_cvt_f32_f16_e32 v118, v205
	v_cvt_f32_f16_sdwa v119, v205 dst_sel:DWORD dst_unused:UNUSED_PAD src0_sel:WORD_1
	v_cvt_f32_f16_e32 v120, v206
	v_cvt_f32_f16_sdwa v121, v206 dst_sel:DWORD dst_unused:UNUSED_PAD src0_sel:WORD_1
	v_cvt_f32_f16_e32 v104, v204
	v_cvt_f32_f16_sdwa v105, v204 dst_sel:DWORD dst_unused:UNUSED_PAD src0_sel:WORD_1
	v_pk_add_f32 v[92:93], v[92:93], v[100:101]
	v_pk_add_f32 v[100:101], v[88:89], v[116:117]
	v_pk_add_f32 v[94:95], v[94:95], v[114:115]
	v_pk_add_f32 v[90:91], v[90:91], v[110:111]
	v_cvt_pk_f16_f32 v88, v100, v101
	v_cvt_pk_f16_f32 v89, v90, v91
	v_pk_mul_f32 v[102:103], v[92:93], v[92:93]
	v_pk_mul_f32 v[110:111], v[94:95], v[94:95]
	v_pk_mul_f32 v[100:101], v[100:101], v[100:101]
	v_pk_mul_f32 v[90:91], v[90:91], v[90:91]
	v_pk_add_f32 v[104:105], v[84:85], v[104:105]
	v_pk_add_f32 v[114:115], v[80:81], v[120:121]
	v_pk_add_f32 v[116:117], v[86:87], v[118:119]
	v_pk_add_f32 v[80:81], v[82:83], v[98:99]
	v_pk_mul_f32 v[82:83], v[104:105], v[104:105]
	v_pk_mul_f32 v[84:85], v[116:117], v[116:117]
	v_pk_mul_f32 v[86:87], v[114:115], v[114:115]
	v_pk_mul_f32 v[98:99], v[80:81], v[80:81]
	v_add_f32_e32 v90, v90, v91
	v_add_f32_e32 v91, v100, v101
	s_waitcnt lgkmcnt(0)
	v_add_f32_e32 v97, v110, v111
	v_add_f32_e32 v100, v102, v103
	v_add_f32_e32 v90, v91, v90
	v_add_f32_e32 v91, v100, v97
	v_add_f32_e32 v97, v98, v99
	v_add_f32_e32 v86, v86, v87
	v_add_f32_e32 v84, v84, v85
	v_add_f32_e32 v82, v82, v83
	v_add_f32_e32 v85, v86, v97
	v_add_f32_e32 v82, v82, v84
	v_add_f32_e32 v83, v91, v90
	v_add_f32_e32 v82, v82, v85
	v_add_f32_e32 v82, v83, v82
	v_mov_b32_e32 v83, v82
	s_nop 1
	v_permlane16_swap_b32_e32 v82, v83
	v_cvt_pk_f16_f32 v85, v80, v81
	v_cvt_pk_f16_f32 v87, v94, v95
	v_cvt_pk_f16_f32 v86, v92, v93
	v_cvt_pk_f16_f32 v84, v114, v115
	s_waitcnt lgkmcnt(0)
	v_add_f32_e32 v80, v82, v83
	v_mov_b32_e32 v81, v80
	s_nop 1
	v_permlane32_swap_b32_e32 v80, v81
	v_cvt_pk_f16_f32 v83, v116, v117
	v_cvt_pk_f16_f32 v82, v104, v105
	global_store_dwordx4 v[106:107], v[86:89], off
	global_store_dwordx4 v[108:109], v[82:85], off
	s_and_saveexec_b64 s[48:49], s[4:5]
	s_cbranch_execz .LBB0_692
	v_lshl_add_u32 v136, v96, 4, s11
	s_waitcnt lgkmcnt(0)
	v_add_f32_e32 v82, v80, v81
	v_lshl_add_u64 v[80:81], v[136:137], 2, s[42:43]
	global_store_dword v[80:81], v82, off
.LBB0_692:
	s_or_b64 exec, exec, s[48:49]
	v_add_u32_e32 v80, 48, v167
	v_lshl_add_u32 v136, v80, 10, v168
	v_lshl_add_u64 v[90:91], v[136:137], 1, s[40:41]
	v_add_u32_e32 v136, 0x80, v136
	v_lshl_add_u64 v[92:93], v[136:137], 1, s[40:41]
	s_waitcnt vmcnt(10)
	v_cvt_f32_f16_e32 v94, v211
	v_cvt_f32_f16_sdwa v95, v211 dst_sel:DWORD dst_unused:UNUSED_PAD src0_sel:WORD_1
	v_cvt_f32_f16_e32 v96, v209
	v_cvt_f32_f16_sdwa v97, v209 dst_sel:DWORD dst_unused:UNUSED_PAD src0_sel:WORD_1
	v_cvt_f32_f16_e32 v98, v210
	v_cvt_f32_f16_sdwa v99, v210 dst_sel:DWORD dst_unused:UNUSED_PAD src0_sel:WORD_1
	v_cvt_f32_f16_e32 v84, v208
	v_cvt_f32_f16_sdwa v85, v208 dst_sel:DWORD dst_unused:UNUSED_PAD src0_sel:WORD_1
	v_cvt_f32_f16_e32 v82, v215
	v_cvt_f32_f16_sdwa v83, v215 dst_sel:DWORD dst_unused:UNUSED_PAD src0_sel:WORD_1
	v_cvt_f32_f16_e32 v100, v213
	v_cvt_f32_f16_sdwa v101, v213 dst_sel:DWORD dst_unused:UNUSED_PAD src0_sel:WORD_1
	v_cvt_f32_f16_e32 v102, v214
	v_cvt_f32_f16_sdwa v103, v214 dst_sel:DWORD dst_unused:UNUSED_PAD src0_sel:WORD_1
	v_cvt_f32_f16_e32 v88, v212
	v_cvt_f32_f16_sdwa v89, v212 dst_sel:DWORD dst_unused:UNUSED_PAD src0_sel:WORD_1
	v_pk_add_f32 v[76:77], v[76:77], v[84:85]
	v_pk_add_f32 v[84:85], v[72:73], v[98:99]
	v_pk_add_f32 v[78:79], v[78:79], v[96:97]
	v_pk_add_f32 v[74:75], v[74:75], v[94:95]
	v_cvt_pk_f16_f32 v72, v84, v85
	v_cvt_pk_f16_f32 v73, v74, v75
	v_pk_mul_f32 v[86:87], v[76:77], v[76:77]
	v_pk_mul_f32 v[94:95], v[78:79], v[78:79]
	v_pk_mul_f32 v[84:85], v[84:85], v[84:85]
	v_pk_mul_f32 v[74:75], v[74:75], v[74:75]
	v_pk_add_f32 v[88:89], v[68:69], v[88:89]
	v_pk_add_f32 v[96:97], v[64:65], v[102:103]
	v_pk_add_f32 v[98:99], v[70:71], v[100:101]
	v_pk_add_f32 v[64:65], v[66:67], v[82:83]
	v_pk_mul_f32 v[66:67], v[88:89], v[88:89]
	v_pk_mul_f32 v[68:69], v[98:99], v[98:99]
	v_pk_mul_f32 v[70:71], v[96:97], v[96:97]
	v_pk_mul_f32 v[82:83], v[64:65], v[64:65]
	v_add_f32_e32 v74, v74, v75
	v_add_f32_e32 v75, v84, v85
	s_waitcnt lgkmcnt(0)
	v_add_f32_e32 v81, v94, v95
	v_add_f32_e32 v84, v86, v87
	v_add_f32_e32 v74, v75, v74
	v_add_f32_e32 v75, v84, v81
	v_add_f32_e32 v81, v82, v83
	v_add_f32_e32 v70, v70, v71
	v_add_f32_e32 v68, v68, v69
	v_add_f32_e32 v66, v66, v67
	v_add_f32_e32 v69, v70, v81
	v_add_f32_e32 v66, v66, v68
	v_add_f32_e32 v67, v75, v74
	v_add_f32_e32 v66, v66, v69
	v_add_f32_e32 v66, v67, v66
	v_mov_b32_e32 v67, v66
	s_nop 1
	v_permlane16_swap_b32_e32 v66, v67
	v_cvt_pk_f16_f32 v69, v64, v65
	v_cvt_pk_f16_f32 v71, v78, v79
	v_cvt_pk_f16_f32 v70, v76, v77
	v_cvt_pk_f16_f32 v68, v96, v97
	s_waitcnt lgkmcnt(0)
	v_add_f32_e32 v64, v66, v67
	v_mov_b32_e32 v65, v64
	s_nop 1
	v_permlane32_swap_b32_e32 v64, v65
	v_cvt_pk_f16_f32 v67, v98, v99
	v_cvt_pk_f16_f32 v66, v88, v89
	global_store_dwordx4 v[90:91], v[70:73], off
	global_store_dwordx4 v[92:93], v[66:69], off
	s_and_saveexec_b64 s[48:49], s[4:5]
	s_cbranch_execz .LBB0_694
	v_lshl_add_u32 v136, v80, 4, s11
	s_waitcnt lgkmcnt(0)
	v_add_f32_e32 v66, v64, v65
	v_lshl_add_u64 v[64:65], v[136:137], 2, s[42:43]
	global_store_dword v[64:65], v66, off
;   __device__ __forceinline__ void operator()(const pg8::f32x4 (&acc)[2][2][4][2], const pg8::Unit& u, int wr, int wc, int fr, int fq) const {
;     ...
;         const int tok = row0 + ai * 128 + m * 16; float ss = 0.f;
; #pragma unroll
;         for (int bj = 0; bj < 2; ++bj) {
;           const unsigned off = (unsigned)tok * DM + colb + 128 * bj;
;           f8_t n = __builtin_convertvector(*(const h8_t*)(x16 + off), f8_t);
; #pragma unroll
;           for (int c = 0; c < 4; ++c) { n[c] += sc * acc[ai][bj][m][0][c]; n[4 + c] += sc * acc[ai][bj][m][1][c]; }
;           if (aux) {
;             *(h8_t*)(x16 + off) = __builtin_convertvector(n, h8_t);
;             ss += ((n[0] * n[0] + n[1] * n[1]) + (n[2] * n[2] + n[3] * n[3])) + ((n[4] * n[4] + n[5] * n[5]) + (n[6] * n[6] + n[7] * n[7]));
;           } else {
;             *(f32x4*)(xout + off) = (f32x4){n[0], n[1], n[2], n[3]}; *(f32x4*)(xout + off + 4) = (f32x4){n[4], n[5], n[6], n[7]};
;           }
;         }
;         if (aux) { ss += __shfl_xor(ss, 16); ss += __shfl_xor(ss, 32); if (fq == 0) ssq[(unsigned)tok * 16 + u.pn * 4 + wc] = ss; }
.LBB0_694:
	s_or_b64 exec, exec, s[48:49]
	v_add_u32_e32 v64, 0x80, v167
	v_lshl_add_u32 v136, v64, 10, v168
	v_lshl_add_u64 v[74:75], v[136:137], 1, s[40:41]
	v_add_u32_e32 v136, 0x80, v136
	v_lshl_add_u64 v[76:77], v[136:137], 1, s[40:41]
	s_waitcnt vmcnt(10)
	v_cvt_f32_f16_e32 v78, v219
	v_cvt_f32_f16_sdwa v79, v219 dst_sel:DWORD dst_unused:UNUSED_PAD src0_sel:WORD_1
	v_cvt_f32_f16_e32 v80, v217
	v_cvt_f32_f16_sdwa v81, v217 dst_sel:DWORD dst_unused:UNUSED_PAD src0_sel:WORD_1
	v_cvt_f32_f16_e32 v82, v218
	v_cvt_f32_f16_sdwa v83, v218 dst_sel:DWORD dst_unused:UNUSED_PAD src0_sel:WORD_1
	v_cvt_f32_f16_e32 v68, v216
	v_cvt_f32_f16_sdwa v69, v216 dst_sel:DWORD dst_unused:UNUSED_PAD src0_sel:WORD_1
	v_cvt_f32_f16_e32 v66, v223
	v_cvt_f32_f16_sdwa v67, v223 dst_sel:DWORD dst_unused:UNUSED_PAD src0_sel:WORD_1
	v_cvt_f32_f16_e32 v84, v221
	v_cvt_f32_f16_sdwa v85, v221 dst_sel:DWORD dst_unused:UNUSED_PAD src0_sel:WORD_1
	v_cvt_f32_f16_e32 v86, v222
	v_cvt_f32_f16_sdwa v87, v222 dst_sel:DWORD dst_unused:UNUSED_PAD src0_sel:WORD_1
	v_cvt_f32_f16_e32 v72, v220
	v_cvt_f32_f16_sdwa v73, v220 dst_sel:DWORD dst_unused:UNUSED_PAD src0_sel:WORD_1
	v_pk_add_f32 v[60:61], v[60:61], v[68:69]
	v_pk_add_f32 v[68:69], v[56:57], v[82:83]
	v_pk_add_f32 v[62:63], v[62:63], v[80:81]
	v_pk_add_f32 v[58:59], v[58:59], v[78:79]
	v_cvt_pk_f16_f32 v56, v68, v69
	v_cvt_pk_f16_f32 v57, v58, v59
	v_pk_mul_f32 v[70:71], v[60:61], v[60:61]
	v_pk_mul_f32 v[78:79], v[62:63], v[62:63]
	v_pk_mul_f32 v[68:69], v[68:69], v[68:69]
	v_pk_mul_f32 v[58:59], v[58:59], v[58:59]
	v_pk_add_f32 v[72:73], v[52:53], v[72:73]
	v_pk_add_f32 v[80:81], v[48:49], v[86:87]
	v_pk_add_f32 v[82:83], v[54:55], v[84:85]
	v_pk_add_f32 v[48:49], v[50:51], v[66:67]
	v_pk_mul_f32 v[50:51], v[72:73], v[72:73]
	v_pk_mul_f32 v[52:53], v[82:83], v[82:83]
	v_pk_mul_f32 v[54:55], v[80:81], v[80:81]
	v_pk_mul_f32 v[66:67], v[48:49], v[48:49]
	v_add_f32_e32 v58, v58, v59
	v_add_f32_e32 v59, v68, v69
	s_waitcnt lgkmcnt(0)
	v_add_f32_e32 v65, v78, v79
	v_add_f32_e32 v68, v70, v71
	v_add_f32_e32 v58, v59, v58
	v_add_f32_e32 v59, v68, v65
	v_add_f32_e32 v65, v66, v67
	v_add_f32_e32 v54, v54, v55
	v_add_f32_e32 v52, v52, v53
	v_add_f32_e32 v50, v50, v51
	v_add_f32_e32 v53, v54, v65
	v_add_f32_e32 v50, v50, v52
	v_add_f32_e32 v51, v59, v58
	v_add_f32_e32 v50, v50, v53
	v_add_f32_e32 v50, v51, v50
	v_mov_b32_e32 v51, v50
	s_nop 1
	v_permlane16_swap_b32_e32 v50, v51
	v_cvt_pk_f16_f32 v53, v48, v49
	v_cvt_pk_f16_f32 v55, v62, v63
	v_cvt_pk_f16_f32 v54, v60, v61
	v_cvt_pk_f16_f32 v52, v80, v81
	s_waitcnt lgkmcnt(0)
	v_add_f32_e32 v48, v50, v51
	v_mov_b32_e32 v49, v48
	s_nop 1
	v_permlane32_swap_b32_e32 v48, v49
	v_cvt_pk_f16_f32 v51, v82, v83
	v_cvt_pk_f16_f32 v50, v72, v73
	global_store_dwordx4 v[74:75], v[54:57], off
	global_store_dwordx4 v[76:77], v[50:53], off
	s_and_saveexec_b64 s[48:49], s[4:5]
	s_cbranch_execz .LBB0_696
	v_lshl_add_u32 v136, v64, 4, s11
	s_waitcnt lgkmcnt(0)
	v_add_f32_e32 v50, v48, v49
	v_lshl_add_u64 v[48:49], v[136:137], 2, s[42:43]
	global_store_dword v[48:49], v50, off
.LBB0_696:
	s_or_b64 exec, exec, s[48:49]
	v_add_u32_e32 v48, 0x90, v167
	v_lshl_add_u32 v136, v48, 10, v168
	v_lshl_add_u64 v[58:59], v[136:137], 1, s[40:41]
	v_add_u32_e32 v136, 0x80, v136
	v_lshl_add_u64 v[60:61], v[136:137], 1, s[40:41]
	s_waitcnt vmcnt(10)
	v_cvt_f32_f16_e32 v62, v231
	v_cvt_f32_f16_sdwa v63, v231 dst_sel:DWORD dst_unused:UNUSED_PAD src0_sel:WORD_1
	v_cvt_f32_f16_e32 v64, v229
	v_cvt_f32_f16_sdwa v65, v229 dst_sel:DWORD dst_unused:UNUSED_PAD src0_sel:WORD_1
	v_cvt_f32_f16_e32 v66, v230
	v_cvt_f32_f16_sdwa v67, v230 dst_sel:DWORD dst_unused:UNUSED_PAD src0_sel:WORD_1
	v_cvt_f32_f16_e32 v52, v228
	v_cvt_f32_f16_sdwa v53, v228 dst_sel:DWORD dst_unused:UNUSED_PAD src0_sel:WORD_1
	v_cvt_f32_f16_e32 v50, v247
	v_cvt_f32_f16_sdwa v51, v247 dst_sel:DWORD dst_unused:UNUSED_PAD src0_sel:WORD_1
	v_cvt_f32_f16_e32 v68, v245
	v_cvt_f32_f16_sdwa v69, v245 dst_sel:DWORD dst_unused:UNUSED_PAD src0_sel:WORD_1
	v_cvt_f32_f16_e32 v70, v246
	v_cvt_f32_f16_sdwa v71, v246 dst_sel:DWORD dst_unused:UNUSED_PAD src0_sel:WORD_1
	v_cvt_f32_f16_e32 v56, v244
	v_cvt_f32_f16_sdwa v57, v244 dst_sel:DWORD dst_unused:UNUSED_PAD src0_sel:WORD_1
	v_pk_add_f32 v[44:45], v[44:45], v[52:53]
	v_pk_add_f32 v[52:53], v[40:41], v[66:67]
	v_pk_add_f32 v[46:47], v[46:47], v[64:65]
	v_pk_add_f32 v[42:43], v[42:43], v[62:63]
	v_cvt_pk_f16_f32 v40, v52, v53
	v_cvt_pk_f16_f32 v41, v42, v43
	v_pk_mul_f32 v[54:55], v[44:45], v[44:45]
	v_pk_mul_f32 v[62:63], v[46:47], v[46:47]
	v_pk_mul_f32 v[52:53], v[52:53], v[52:53]
	v_pk_mul_f32 v[42:43], v[42:43], v[42:43]
	v_pk_add_f32 v[56:57], v[36:37], v[56:57]
	v_pk_add_f32 v[64:65], v[32:33], v[70:71]
	v_pk_add_f32 v[66:67], v[38:39], v[68:69]
	v_pk_add_f32 v[32:33], v[34:35], v[50:51]
	v_pk_mul_f32 v[34:35], v[56:57], v[56:57]
	v_pk_mul_f32 v[36:37], v[66:67], v[66:67]
	v_pk_mul_f32 v[38:39], v[64:65], v[64:65]
	v_pk_mul_f32 v[50:51], v[32:33], v[32:33]
	v_add_f32_e32 v42, v42, v43
	v_add_f32_e32 v43, v52, v53
	s_waitcnt lgkmcnt(0)
	v_add_f32_e32 v49, v62, v63
	v_add_f32_e32 v52, v54, v55
	v_add_f32_e32 v42, v43, v42
	v_add_f32_e32 v43, v52, v49
	v_add_f32_e32 v49, v50, v51
	v_add_f32_e32 v38, v38, v39
	v_add_f32_e32 v36, v36, v37
	v_add_f32_e32 v34, v34, v35
	v_add_f32_e32 v37, v38, v49
	v_add_f32_e32 v34, v34, v36
	v_add_f32_e32 v35, v43, v42
	v_add_f32_e32 v34, v34, v37
	v_add_f32_e32 v34, v35, v34
	v_mov_b32_e32 v35, v34
	s_nop 1
	v_permlane16_swap_b32_e32 v34, v35
	v_cvt_pk_f16_f32 v37, v32, v33
	v_cvt_pk_f16_f32 v39, v46, v47
	v_cvt_pk_f16_f32 v38, v44, v45
	v_cvt_pk_f16_f32 v36, v64, v65
	s_waitcnt lgkmcnt(0)
	v_add_f32_e32 v32, v34, v35
	v_mov_b32_e32 v33, v32
	s_nop 1
	v_permlane32_swap_b32_e32 v32, v33
	v_cvt_pk_f16_f32 v35, v66, v67
	v_cvt_pk_f16_f32 v34, v56, v57
	global_store_dwordx4 v[58:59], v[38:41], off
	global_store_dwordx4 v[60:61], v[34:37], off
	s_and_saveexec_b64 s[48:49], s[4:5]
	s_cbranch_execz .LBB0_698
	v_lshl_add_u32 v136, v48, 4, s11
	s_waitcnt lgkmcnt(0)
	v_add_f32_e32 v34, v32, v33
	v_lshl_add_u64 v[32:33], v[136:137], 2, s[42:43]
	global_store_dword v[32:33], v34, off
;   __device__ __forceinline__ void operator()(const pg8::f32x4 (&acc)[2][2][4][2], const pg8::Unit& u, int wr, int wc, int fr, int fq) const {
;     ...
;         const int tok = row0 + ai * 128 + m * 16; float ss = 0.f;
; #pragma unroll
;         for (int bj = 0; bj < 2; ++bj) {
;           const unsigned off = (unsigned)tok * DM + colb + 128 * bj;
;           f8_t n = __builtin_convertvector(*(const h8_t*)(x16 + off), f8_t);
; #pragma unroll
;           for (int c = 0; c < 4; ++c) { n[c] += sc * acc[ai][bj][m][0][c]; n[4 + c] += sc * acc[ai][bj][m][1][c]; }
;           if (aux) {
;             *(h8_t*)(x16 + off) = __builtin_convertvector(n, h8_t);
;             ss += ((n[0] * n[0] + n[1] * n[1]) + (n[2] * n[2] + n[3] * n[3])) + ((n[4] * n[4] + n[5] * n[5]) + (n[6] * n[6] + n[7] * n[7]));
;           } else {
;             *(f32x4*)(xout + off) = (f32x4){n[0], n[1], n[2], n[3]}; *(f32x4*)(xout + off + 4) = (f32x4){n[4], n[5], n[6], n[7]};
;           }
;         }
;         if (aux) { ss += __shfl_xor(ss, 16); ss += __shfl_xor(ss, 32); if (fq == 0) ssq[(unsigned)tok * 16 + u.pn * 4 + wc] = ss; }
;         if (m & 1) asm volatile("" ::: "memory");
.LBB0_698:
	s_or_b64 exec, exec, s[48:49]
	v_add_u32_e32 v32, 0xa0, v167
	v_lshl_add_u32 v136, v32, 10, v168
	v_lshl_add_u64 v[42:43], v[136:137], 1, s[40:41]
	v_add_u32_e32 v136, 0x80, v136
	global_load_dwordx4 v[34:37], v[42:43], off
	v_lshl_add_u64 v[44:45], v[136:137], 1, s[40:41]
	global_load_dwordx4 v[38:41], v[44:45], off
	s_waitcnt vmcnt(1)
	v_cvt_f32_f16_e32 v46, v37
	v_cvt_f32_f16_sdwa v47, v37 dst_sel:DWORD dst_unused:UNUSED_PAD src0_sel:WORD_1
	v_cvt_f32_f16_e32 v48, v35
	v_cvt_f32_f16_sdwa v49, v35 dst_sel:DWORD dst_unused:UNUSED_PAD src0_sel:WORD_1
	v_cvt_f32_f16_e32 v50, v36
	v_cvt_f32_f16_sdwa v51, v36 dst_sel:DWORD dst_unused:UNUSED_PAD src0_sel:WORD_1
	v_cvt_f32_f16_e32 v36, v34
	v_cvt_f32_f16_sdwa v37, v34 dst_sel:DWORD dst_unused:UNUSED_PAD src0_sel:WORD_1
	s_waitcnt vmcnt(0)
	v_cvt_f32_f16_e32 v34, v41
	v_cvt_f32_f16_sdwa v35, v41 dst_sel:DWORD dst_unused:UNUSED_PAD src0_sel:WORD_1
	v_cvt_f32_f16_e32 v52, v39
	v_cvt_f32_f16_sdwa v53, v39 dst_sel:DWORD dst_unused:UNUSED_PAD src0_sel:WORD_1
	v_cvt_f32_f16_e32 v54, v40
	v_cvt_f32_f16_sdwa v55, v40 dst_sel:DWORD dst_unused:UNUSED_PAD src0_sel:WORD_1
	v_cvt_f32_f16_e32 v40, v38
	v_cvt_f32_f16_sdwa v41, v38 dst_sel:DWORD dst_unused:UNUSED_PAD src0_sel:WORD_1
	v_pk_add_f32 v[28:29], v[28:29], v[36:37]
	v_pk_add_f32 v[36:37], v[24:25], v[50:51]
	v_pk_add_f32 v[30:31], v[30:31], v[48:49]
	v_pk_add_f32 v[26:27], v[26:27], v[46:47]
	v_cvt_pk_f16_f32 v24, v36, v37
	v_cvt_pk_f16_f32 v25, v26, v27
	v_pk_mul_f32 v[38:39], v[28:29], v[28:29]
	v_pk_mul_f32 v[46:47], v[30:31], v[30:31]
	v_pk_mul_f32 v[36:37], v[36:37], v[36:37]
	v_pk_mul_f32 v[26:27], v[26:27], v[26:27]
	v_pk_add_f32 v[40:41], v[20:21], v[40:41]
	v_pk_add_f32 v[48:49], v[16:17], v[54:55]
	v_pk_add_f32 v[50:51], v[22:23], v[52:53]
	v_pk_add_f32 v[16:17], v[18:19], v[34:35]
	v_pk_mul_f32 v[18:19], v[40:41], v[40:41]
	v_pk_mul_f32 v[20:21], v[50:51], v[50:51]
	v_pk_mul_f32 v[22:23], v[48:49], v[48:49]
	v_pk_mul_f32 v[34:35], v[16:17], v[16:17]
	v_add_f32_e32 v26, v26, v27
	v_add_f32_e32 v27, v36, v37
	s_waitcnt lgkmcnt(0)
	v_add_f32_e32 v33, v46, v47
	v_add_f32_e32 v36, v38, v39
	v_add_f32_e32 v26, v27, v26
	v_add_f32_e32 v27, v36, v33
	v_add_f32_e32 v33, v34, v35
	v_add_f32_e32 v22, v22, v23
	v_add_f32_e32 v20, v20, v21
	v_add_f32_e32 v18, v18, v19
	v_add_f32_e32 v21, v22, v33
	v_add_f32_e32 v18, v18, v20
	v_add_f32_e32 v19, v27, v26
	v_add_f32_e32 v18, v18, v21
	v_add_f32_e32 v18, v19, v18
	v_mov_b32_e32 v19, v18
	s_nop 1
	v_permlane16_swap_b32_e32 v18, v19
	v_cvt_pk_f16_f32 v21, v16, v17
	v_cvt_pk_f16_f32 v23, v30, v31
	v_cvt_pk_f16_f32 v22, v28, v29
	v_cvt_pk_f16_f32 v20, v48, v49
	s_waitcnt lgkmcnt(0)
	v_add_f32_e32 v16, v18, v19
	v_mov_b32_e32 v17, v16
	s_nop 1
	v_permlane32_swap_b32_e32 v16, v17
	v_cvt_pk_f16_f32 v19, v50, v51
	v_cvt_pk_f16_f32 v18, v40, v41
	global_store_dwordx4 v[42:43], v[22:25], off
	global_store_dwordx4 v[44:45], v[18:21], off
	s_and_saveexec_b64 s[48:49], s[4:5]
	s_cbranch_execz .LBB0_700
	v_lshl_add_u32 v136, v32, 4, s11
	s_waitcnt lgkmcnt(0)
	v_add_f32_e32 v18, v16, v17
	v_lshl_add_u64 v[16:17], v[136:137], 2, s[42:43]
	global_store_dword v[16:17], v18, off
.LBB0_700:
	s_or_b64 exec, exec, s[48:49]
	v_add_u32_e32 v16, 0xb0, v167
	v_lshl_add_u32 v136, v16, 10, v168
	v_lshl_add_u64 v[26:27], v[136:137], 1, s[40:41]
	v_add_u32_e32 v136, 0x80, v136
	global_load_dwordx4 v[18:21], v[26:27], off
	v_lshl_add_u64 v[28:29], v[136:137], 1, s[40:41]
	global_load_dwordx4 v[22:25], v[28:29], off
	s_waitcnt vmcnt(1)
	v_cvt_f32_f16_e32 v30, v21
	v_cvt_f32_f16_sdwa v31, v21 dst_sel:DWORD dst_unused:UNUSED_PAD src0_sel:WORD_1
	v_cvt_f32_f16_e32 v32, v19
	v_cvt_f32_f16_sdwa v33, v19 dst_sel:DWORD dst_unused:UNUSED_PAD src0_sel:WORD_1
	v_cvt_f32_f16_e32 v34, v20
	v_cvt_f32_f16_sdwa v35, v20 dst_sel:DWORD dst_unused:UNUSED_PAD src0_sel:WORD_1
	v_cvt_f32_f16_e32 v20, v18
	v_cvt_f32_f16_sdwa v21, v18 dst_sel:DWORD dst_unused:UNUSED_PAD src0_sel:WORD_1
	s_waitcnt vmcnt(0)
	v_cvt_f32_f16_e32 v18, v25
	v_cvt_f32_f16_sdwa v19, v25 dst_sel:DWORD dst_unused:UNUSED_PAD src0_sel:WORD_1
	v_cvt_f32_f16_e32 v36, v23
	v_cvt_f32_f16_sdwa v37, v23 dst_sel:DWORD dst_unused:UNUSED_PAD src0_sel:WORD_1
	v_cvt_f32_f16_e32 v38, v24
	v_cvt_f32_f16_sdwa v39, v24 dst_sel:DWORD dst_unused:UNUSED_PAD src0_sel:WORD_1
	v_cvt_f32_f16_e32 v24, v22
	v_cvt_f32_f16_sdwa v25, v22 dst_sel:DWORD dst_unused:UNUSED_PAD src0_sel:WORD_1
	v_pk_add_f32 v[12:13], v[12:13], v[20:21]
	v_pk_add_f32 v[20:21], v[8:9], v[34:35]
	v_pk_add_f32 v[14:15], v[14:15], v[32:33]
	v_pk_add_f32 v[10:11], v[10:11], v[30:31]
	v_cvt_pk_f16_f32 v8, v20, v21
	v_cvt_pk_f16_f32 v9, v10, v11
	v_pk_mul_f32 v[22:23], v[12:13], v[12:13]
	v_pk_mul_f32 v[30:31], v[14:15], v[14:15]
	v_pk_mul_f32 v[20:21], v[20:21], v[20:21]
	v_pk_mul_f32 v[10:11], v[10:11], v[10:11]
	v_pk_add_f32 v[24:25], v[4:5], v[24:25]
	v_pk_add_f32 v[32:33], v[0:1], v[38:39]
	v_pk_add_f32 v[34:35], v[6:7], v[36:37]
	v_pk_add_f32 v[0:1], v[2:3], v[18:19]
	v_pk_mul_f32 v[2:3], v[24:25], v[24:25]
	v_pk_mul_f32 v[4:5], v[34:35], v[34:35]
	v_pk_mul_f32 v[6:7], v[32:33], v[32:33]
	v_pk_mul_f32 v[18:19], v[0:1], v[0:1]
	v_add_f32_e32 v10, v10, v11
	v_add_f32_e32 v11, v20, v21
	s_waitcnt lgkmcnt(0)
	v_add_f32_e32 v17, v30, v31
	v_add_f32_e32 v20, v22, v23
	v_add_f32_e32 v10, v11, v10
	v_add_f32_e32 v11, v20, v17
	v_add_f32_e32 v17, v18, v19
	v_add_f32_e32 v6, v6, v7
	v_add_f32_e32 v4, v4, v5
	v_add_f32_e32 v2, v2, v3
	v_add_f32_e32 v5, v6, v17
	v_add_f32_e32 v2, v2, v4
	v_add_f32_e32 v3, v11, v10
	v_add_f32_e32 v2, v2, v5
	v_add_f32_e32 v2, v3, v2
	v_mov_b32_e32 v3, v2
	s_nop 1
	v_permlane16_swap_b32_e32 v2, v3
	v_cvt_pk_f16_f32 v5, v0, v1
	v_cvt_pk_f16_f32 v7, v14, v15
	v_cvt_pk_f16_f32 v6, v12, v13
	v_cvt_pk_f16_f32 v4, v32, v33
	s_waitcnt lgkmcnt(0)
	v_add_f32_e32 v0, v2, v3
	v_mov_b32_e32 v1, v0
	s_nop 1
	v_permlane32_swap_b32_e32 v0, v1
	v_cvt_pk_f16_f32 v3, v34, v35
	v_cvt_pk_f16_f32 v2, v24, v25
	global_store_dwordx4 v[26:27], v[6:9], off
	global_store_dwordx4 v[28:29], v[2:5], off
	s_and_saveexec_b64 s[48:49], s[4:5]
	s_cbranch_execz .LBB0_677
	v_lshl_add_u32 v136, v16, 4, s11
	s_waitcnt lgkmcnt(0)
	v_add_f32_e32 v2, v0, v1
	v_lshl_add_u64 v[0:1], v[136:137], 2, s[42:43]
	global_store_dword v[0:1], v2, off
	s_branch .LBB0_677

; #define PG8_STAGE(bufoff, gbase, voff) do { _Pragma("unroll") for (int _i = 0; _i < 2; ++_i) \
;         __builtin_amdgcn_global_load_lds((const unsigned*)((const char*)(gbase) + (voff)[_i]), (PG8_LAS unsigned*)(lds + (bufoff) + ldsw + _i * 8192), 16, 0, 0); } while (0)
; #define PG8_LDA(dst, b, h) do { _Pragma("unroll") for (int m = 0; m < 4; ++m) _Pragma("unroll") for (int k = 0; k < 2; ++k) dst[m][k] = *(const PG8_LAS bf16x8*)(lds + PG8_SA(b, h) + aoff + m * 2048 + k * 1024); } while (0)
; #define PG8_LDB(dst, b, h) do { _Pragma("unroll") for (int n = 0; n < 2; ++n) _Pragma("unroll") for (int k = 0; k < 2; ++k) dst[n][k] = *(const PG8_LAS bf16x8*)(lds + PG8_SB(b, h) + boff + n * 2048 + k * 1024); } while (0)
; #define PG8_MMA(ai, bj, At, Bt) do { __builtin_amdgcn_s_setprio(1); _Pragma("unroll") for (int m = 0; m < 4; ++m) _Pragma("unroll") for (int n = 0; n < 2; ++n) _Pragma("unroll") for (int k = 0; k < 2; ++k) \
;         acc[ai][bj][m][n] = mma16<F16>(Bt[n][k], At[m][k], acc[ai][bj][m][n]); __builtin_amdgcn_s_setprio(0); } while (0)
; #define PG8_WAIT_V(n) asm volatile("s_waitcnt vmcnt(" #n ")" ::: "memory")
; #define PG8_WAIT_L(n) asm volatile("s_waitcnt lgkmcnt(" #n ")" ::: "memory")
; #define PG8_BAR __builtin_amdgcn_s_barrier()
; #define PG8_SCHED __builtin_amdgcn_sched_barrier(0)
; template <class Epi, class Sched, bool ALIGN_EPI = false, bool SP2 = false, bool F16 = false, bool TOKPERM = false>
; __device__ __forceinline__ void gemm_phase(PG8_LAS unsigned char* lds, const Gemm g, const Sched& S, const Epi& E, int wv) {
;     ...
;             PG8_LDB(B0, 0, 0); PG8_LDB(B1, 0, 1); PG8_SCHED; PG8_LDA(At, 0, 0); PG8_STAGE(PG8_SA(1, 1), a1 + hstep, voffA);
;             PG8_WAIT_V(8); PG8_WAIT_L(0); PG8_BAR; PG8_MMA(0, 0, At, B0); PG8_MMA(0, 1, At, B1); PG8_BAR; PG8_SCHED;
;             PG8_LDA(At, 0, 1); PG8_STAGE(PG8_SB(0, 0), b2, voffB); PG8_STAGE(PG8_SB(0, 1), b2 + hstep, voffB); PG8_STAGE(PG8_SA(0, 0), a2, voffA);
;             PG8_WAIT_V(8); PG8_WAIT_L(0); PG8_BAR; PG8_MMA(1, 0, At, B0); PG8_MMA(1, 1, At, B1); PG8_BAR; PG8_SCHED;
.LBB0_867:
	ds_read_b128 v[166:169], v149
	ds_read_b128 v[170:173], v150
	ds_read_b128 v[174:177], v151
	ds_read_b128 v[178:181], v152
	ds_read_b128 v[182:185], v153
	ds_read_b128 v[186:189], v154
	ds_read_b128 v[190:193], v155
	ds_read_b128 v[194:197], v156
	s_add_u32 s18, s16, 0x100
	s_addc_u32 s19, s17, 0
	s_cmp_eq_u32 s67, 40
	s_cselect_b32 s23, s11, s19
	s_cselect_b32 s22, s10, s18
	s_cselect_b32 s21, s13, s66
	s_cselect_b32 s20, s12, s65
	s_mov_b32 m0, s59
	v_lshl_add_u64 v[232:233], s[16:17], 0, v[138:139]
	ds_read_b128 v[198:201], v147
	ds_read_b128 v[202:205], v147 offset:1024
	ds_read_b128 v[206:209], v147 offset:2048
	ds_read_b128 v[210:213], v147 offset:3072
	ds_read_b128 v[214:217], v147 offset:4096
	ds_read_b128 v[218:221], v147 offset:5120
	ds_read_b128 v[222:225], v147 offset:6144
	ds_read_b128 v[228:231], v147 offset:7168
	global_load_lds_dwordx4 v[232:233], off
	v_lshl_add_u64 v[232:233], s[16:17], 0, v[140:141]
	s_mov_b32 m0, s60
	s_nop 0
	global_load_lds_dwordx4 v[232:233], off
	s_waitcnt vmcnt(8)
	s_waitcnt lgkmcnt(0)
	s_barrier
	s_setprio 1
	s_waitcnt lgkmcnt(0)
	v_mfma_f32_16x16x32_bf16 v[124:127], v[166:169], v[198:201], v[124:127]
	v_mfma_f32_16x16x32_bf16 v[120:123], v[174:177], v[198:201], v[120:123]
	v_mfma_f32_16x16x32_bf16 v[108:111], v[166:169], v[206:209], v[108:111]
	v_mfma_f32_16x16x32_bf16 v[104:107], v[174:177], v[206:209], v[104:107]
	v_mfma_f32_16x16x32_bf16 v[92:95], v[166:169], v[214:217], v[92:95]
	v_mfma_f32_16x16x32_bf16 v[88:91], v[174:177], v[214:217], v[88:91]
	v_mfma_f32_16x16x32_bf16 v[76:79], v[166:169], v[222:225], v[76:79]
	v_mfma_f32_16x16x32_bf16 v[72:75], v[174:177], v[222:225], v[72:75]
	v_mfma_f32_16x16x32_bf16 v[124:127], v[170:173], v[202:205], v[124:127]
	v_mfma_f32_16x16x32_bf16 v[120:123], v[178:181], v[202:205], v[120:123]
	v_mfma_f32_16x16x32_bf16 v[108:111], v[170:173], v[210:213], v[108:111]
	v_mfma_f32_16x16x32_bf16 v[104:107], v[178:181], v[210:213], v[104:107]
	v_mfma_f32_16x16x32_bf16 v[92:95], v[170:173], v[218:221], v[92:95]
	v_mfma_f32_16x16x32_bf16 v[88:91], v[178:181], v[218:221], v[88:91]
	v_mfma_f32_16x16x32_bf16 v[76:79], v[170:173], v[228:231], v[76:79]
	v_mfma_f32_16x16x32_bf16 v[72:75], v[178:181], v[228:231], v[72:75]
	s_setprio 0
	s_setprio 1
	v_mfma_f32_16x16x32_bf16 v[116:119], v[182:185], v[198:201], v[116:119]
	v_mfma_f32_16x16x32_bf16 v[112:115], v[190:193], v[198:201], v[112:115]
	v_mfma_f32_16x16x32_bf16 v[100:103], v[182:185], v[206:209], v[100:103]
	v_mfma_f32_16x16x32_bf16 v[96:99], v[190:193], v[206:209], v[96:99]
	v_mfma_f32_16x16x32_bf16 v[84:87], v[182:185], v[214:217], v[84:87]
	v_mfma_f32_16x16x32_bf16 v[80:83], v[190:193], v[214:217], v[80:83]
	v_mfma_f32_16x16x32_bf16 v[68:71], v[182:185], v[222:225], v[68:71]
	v_mfma_f32_16x16x32_bf16 v[64:67], v[190:193], v[222:225], v[64:67]
	v_mfma_f32_16x16x32_bf16 v[116:119], v[186:189], v[202:205], v[116:119]
	v_mfma_f32_16x16x32_bf16 v[112:115], v[194:197], v[202:205], v[112:115]
	v_mfma_f32_16x16x32_bf16 v[100:103], v[186:189], v[210:213], v[100:103]
	v_mfma_f32_16x16x32_bf16 v[96:99], v[194:197], v[210:213], v[96:99]
	v_mfma_f32_16x16x32_bf16 v[84:87], v[186:189], v[218:221], v[84:87]
	v_mfma_f32_16x16x32_bf16 v[80:83], v[194:197], v[218:221], v[80:83]
	v_mfma_f32_16x16x32_bf16 v[68:71], v[186:189], v[228:231], v[68:71]
	v_mfma_f32_16x16x32_bf16 v[64:67], v[194:197], v[228:231], v[64:67]
	s_setprio 0
	s_barrier
	s_mov_b32 m0, s4
	v_lshl_add_u64 v[232:233], s[20:21], 0, v[130:131]
	s_add_u32 s16, s20, 0xb0000
	ds_read_b128 v[198:201], v147 offset:16384
	ds_read_b128 v[202:205], v147 offset:17408
	ds_read_b128 v[206:209], v147 offset:18432
	ds_read_b128 v[210:213], v147 offset:19456
	ds_read_b128 v[214:217], v147 offset:20480
	ds_read_b128 v[218:221], v147 offset:21504
	ds_read_b128 v[222:225], v147 offset:22528
	ds_read_b128 v[228:231], v147 offset:23552
	global_load_lds_dwordx4 v[232:233], off
	v_lshl_add_u64 v[234:235], s[20:21], 0, v[134:135]
	s_mov_b32 m0, s5
	s_addc_u32 s17, s21, 0
	global_load_lds_dwordx4 v[234:235], off
	v_lshl_add_u64 v[236:237], s[16:17], 0, v[130:131]
	s_mov_b32 m0, s33
	v_lshl_add_u64 v[238:239], s[22:23], 0, v[132:133]
	global_load_lds_dwordx4 v[236:237], off
	v_lshl_add_u64 v[236:237], s[16:17], 0, v[134:135]
	s_mov_b32 m0, s36
	s_nop 0
	global_load_lds_dwordx4 v[236:237], off
	v_lshl_add_u64 v[236:237], s[22:23], 0, v[128:129]
	s_mov_b32 m0, s3
	s_nop 0
	global_load_lds_dwordx4 v[236:237], off
	s_mov_b32 m0, s37
	s_nop 0
	global_load_lds_dwordx4 v[238:239], off
	s_waitcnt vmcnt(8)
	s_waitcnt lgkmcnt(0)
	s_barrier
; #define PG8_STAGE(bufoff, gbase, voff) do { _Pragma("unroll") for (int _i = 0; _i < 2; ++_i) \
;         __builtin_amdgcn_global_load_lds((const unsigned*)((const char*)(gbase) + (voff)[_i]), (PG8_LAS unsigned*)(lds + (bufoff) + ldsw + _i * 8192), 16, 0, 0); } while (0)
; #define PG8_LDA(dst, b, h) do { _Pragma("unroll") for (int m = 0; m < 4; ++m) _Pragma("unroll") for (int k = 0; k < 2; ++k) dst[m][k] = *(const PG8_LAS bf16x8*)(lds + PG8_SA(b, h) + aoff + m * 2048 + k * 1024); } while (0)
; #define PG8_LDB(dst, b, h) do { _Pragma("unroll") for (int n = 0; n < 2; ++n) _Pragma("unroll") for (int k = 0; k < 2; ++k) dst[n][k] = *(const PG8_LAS bf16x8*)(lds + PG8_SB(b, h) + boff + n * 2048 + k * 1024); } while (0)
; #define PG8_MMA(ai, bj, At, Bt) do { __builtin_amdgcn_s_setprio(1); _Pragma("unroll") for (int m = 0; m < 4; ++m) _Pragma("unroll") for (int n = 0; n < 2; ++n) _Pragma("unroll") for (int k = 0; k < 2; ++k) \
;         acc[ai][bj][m][n] = mma16<F16>(Bt[n][k], At[m][k], acc[ai][bj][m][n]); __builtin_amdgcn_s_setprio(0); } while (0)
; #define PG8_WAIT_V(n) asm volatile("s_waitcnt vmcnt(" #n ")" ::: "memory")
; #define PG8_WAIT_L(n) asm volatile("s_waitcnt lgkmcnt(" #n ")" ::: "memory")
; #define PG8_BAR __builtin_amdgcn_s_barrier()
; #define PG8_SCHED __builtin_amdgcn_sched_barrier(0)
; template <class Epi, class Sched, bool ALIGN_EPI = false, bool SP2 = false, bool F16 = false, bool TOKPERM = false>
; __device__ __forceinline__ void gemm_phase(PG8_LAS unsigned char* lds, const Gemm g, const Sched& S, const Epi& E, int wv) {
;     ...
;             PG8_WAIT_V(8); PG8_WAIT_L(0); PG8_BAR; PG8_MMA(1, 0, At, B0); PG8_MMA(1, 1, At, B1); PG8_BAR; PG8_SCHED;
;             PG8_LDB(B0, 1, 0); PG8_LDB(B1, 1, 1); PG8_SCHED; PG8_LDA(At, 1, 0); PG8_STAGE(PG8_SA(0, 1), a2 + hstep, voffA);
;             PG8_WAIT_V(8); PG8_WAIT_L(0); PG8_BAR; PG8_MMA(0, 0, At, B0); PG8_MMA(0, 1, At, B1); PG8_BAR; PG8_SCHED;
	s_setprio 1
	s_waitcnt lgkmcnt(0)
	v_mfma_f32_16x16x32_bf16 v[60:63], v[166:169], v[198:201], v[60:63]
	v_mfma_f32_16x16x32_bf16 v[56:59], v[174:177], v[198:201], v[56:59]
	v_mfma_f32_16x16x32_bf16 v[44:47], v[166:169], v[206:209], v[44:47]
	v_mfma_f32_16x16x32_bf16 v[40:43], v[174:177], v[206:209], v[40:43]
	v_mfma_f32_16x16x32_bf16 v[28:31], v[166:169], v[214:217], v[28:31]
	v_mfma_f32_16x16x32_bf16 v[24:27], v[174:177], v[214:217], v[24:27]
	v_mfma_f32_16x16x32_bf16 v[12:15], v[166:169], v[222:225], v[12:15]
	v_mfma_f32_16x16x32_bf16 v[8:11], v[174:177], v[222:225], v[8:11]
	v_mfma_f32_16x16x32_bf16 v[60:63], v[170:173], v[202:205], v[60:63]
	v_mfma_f32_16x16x32_bf16 v[56:59], v[178:181], v[202:205], v[56:59]
	v_mfma_f32_16x16x32_bf16 v[44:47], v[170:173], v[210:213], v[44:47]
	v_mfma_f32_16x16x32_bf16 v[40:43], v[178:181], v[210:213], v[40:43]
	v_mfma_f32_16x16x32_bf16 v[28:31], v[170:173], v[218:221], v[28:31]
	v_mfma_f32_16x16x32_bf16 v[24:27], v[178:181], v[218:221], v[24:27]
	v_mfma_f32_16x16x32_bf16 v[12:15], v[170:173], v[228:231], v[12:15]
	v_mfma_f32_16x16x32_bf16 v[8:11], v[178:181], v[228:231], v[8:11]
	s_setprio 0
	s_setprio 1
	v_mfma_f32_16x16x32_bf16 v[52:55], v[182:185], v[198:201], v[52:55]
	v_mfma_f32_16x16x32_bf16 v[48:51], v[190:193], v[198:201], v[48:51]
	v_mfma_f32_16x16x32_bf16 v[36:39], v[182:185], v[206:209], v[36:39]
	v_mfma_f32_16x16x32_bf16 v[32:35], v[190:193], v[206:209], v[32:35]
	v_mfma_f32_16x16x32_bf16 v[20:23], v[182:185], v[214:217], v[20:23]
	v_mfma_f32_16x16x32_bf16 v[16:19], v[190:193], v[214:217], v[16:19]
	v_mfma_f32_16x16x32_bf16 v[4:7], v[182:185], v[222:225], v[4:7]
	v_mfma_f32_16x16x32_bf16 v[0:3], v[190:193], v[222:225], v[0:3]
	v_mfma_f32_16x16x32_bf16 v[52:55], v[186:189], v[202:205], v[52:55]
	v_mfma_f32_16x16x32_bf16 v[48:51], v[194:197], v[202:205], v[48:51]
	v_mfma_f32_16x16x32_bf16 v[36:39], v[186:189], v[210:213], v[36:39]
	v_mfma_f32_16x16x32_bf16 v[32:35], v[194:197], v[210:213], v[32:35]
	v_mfma_f32_16x16x32_bf16 v[20:23], v[186:189], v[218:221], v[20:23]
	v_mfma_f32_16x16x32_bf16 v[16:19], v[194:197], v[218:221], v[16:19]
	v_mfma_f32_16x16x32_bf16 v[4:7], v[186:189], v[228:231], v[4:7]
	v_mfma_f32_16x16x32_bf16 v[0:3], v[194:197], v[228:231], v[0:3]
	s_setprio 0
	s_barrier
	ds_read_b128 v[166:169], v157
	ds_read_b128 v[170:173], v158
	ds_read_b128 v[174:177], v159
	ds_read_b128 v[178:181], v160
	ds_read_b128 v[182:185], v161
	ds_read_b128 v[186:189], v162
	ds_read_b128 v[190:193], v163
	ds_read_b128 v[194:197], v164
	s_add_u32 s16, s22, 0xb0000
	s_addc_u32 s17, s23, 0
	s_mov_b32 m0, s44
	v_lshl_add_u64 v[240:241], s[16:17], 0, v[128:129]
	ds_read_b128 v[198:201], v147 offset:32768
	ds_read_b128 v[202:205], v147 offset:33792
	ds_read_b128 v[206:209], v147 offset:34816
	ds_read_b128 v[210:213], v147 offset:35840
	ds_read_b128 v[214:217], v147 offset:36864
	ds_read_b128 v[218:221], v147 offset:37888
	ds_read_b128 v[222:225], v147 offset:38912
	ds_read_b128 v[228:231], v147 offset:39936
	global_load_lds_dwordx4 v[240:241], off
	v_lshl_add_u64 v[240:241], s[16:17], 0, v[132:133]
	s_mov_b32 m0, s45
	s_nop 0
	global_load_lds_dwordx4 v[240:241], off
	s_waitcnt vmcnt(8)
	s_waitcnt lgkmcnt(0)
	s_barrier
	s_setprio 1
	s_waitcnt lgkmcnt(0)
	v_mfma_f32_16x16x32_bf16 v[124:127], v[166:169], v[198:201], v[124:127]
	v_mfma_f32_16x16x32_bf16 v[120:123], v[174:177], v[198:201], v[120:123]
	v_mfma_f32_16x16x32_bf16 v[108:111], v[166:169], v[206:209], v[108:111]
	v_mfma_f32_16x16x32_bf16 v[104:107], v[174:177], v[206:209], v[104:107]
	v_mfma_f32_16x16x32_bf16 v[92:95], v[166:169], v[214:217], v[92:95]
	v_mfma_f32_16x16x32_bf16 v[88:91], v[174:177], v[214:217], v[88:91]
	v_mfma_f32_16x16x32_bf16 v[76:79], v[166:169], v[222:225], v[76:79]
	v_mfma_f32_16x16x32_bf16 v[72:75], v[174:177], v[222:225], v[72:75]
	v_mfma_f32_16x16x32_bf16 v[124:127], v[170:173], v[202:205], v[124:127]
	v_mfma_f32_16x16x32_bf16 v[120:123], v[178:181], v[202:205], v[120:123]
	v_mfma_f32_16x16x32_bf16 v[108:111], v[170:173], v[210:213], v[108:111]
	v_mfma_f32_16x16x32_bf16 v[104:107], v[178:181], v[210:213], v[104:107]
	v_mfma_f32_16x16x32_bf16 v[92:95], v[170:173], v[218:221], v[92:95]
	v_mfma_f32_16x16x32_bf16 v[88:91], v[178:181], v[218:221], v[88:91]
	v_mfma_f32_16x16x32_bf16 v[76:79], v[170:173], v[228:231], v[76:79]
	v_mfma_f32_16x16x32_bf16 v[72:75], v[178:181], v[228:231], v[72:75]
	s_setprio 0
	s_setprio 1
	v_mfma_f32_16x16x32_bf16 v[116:119], v[182:185], v[198:201], v[116:119]
	v_mfma_f32_16x16x32_bf16 v[112:115], v[190:193], v[198:201], v[112:115]
	v_mfma_f32_16x16x32_bf16 v[100:103], v[182:185], v[206:209], v[100:103]
	v_mfma_f32_16x16x32_bf16 v[96:99], v[190:193], v[206:209], v[96:99]
	v_mfma_f32_16x16x32_bf16 v[84:87], v[182:185], v[214:217], v[84:87]
	v_mfma_f32_16x16x32_bf16 v[80:83], v[190:193], v[214:217], v[80:83]
	v_mfma_f32_16x16x32_bf16 v[68:71], v[182:185], v[222:225], v[68:71]
	v_mfma_f32_16x16x32_bf16 v[64:67], v[190:193], v[222:225], v[64:67]
	v_mfma_f32_16x16x32_bf16 v[116:119], v[186:189], v[202:205], v[116:119]
	v_mfma_f32_16x16x32_bf16 v[112:115], v[194:197], v[202:205], v[112:115]
	v_mfma_f32_16x16x32_bf16 v[100:103], v[186:189], v[210:213], v[100:103]
	v_mfma_f32_16x16x32_bf16 v[96:99], v[194:197], v[210:213], v[96:99]
	v_mfma_f32_16x16x32_bf16 v[84:87], v[186:189], v[218:221], v[84:87]
	v_mfma_f32_16x16x32_bf16 v[80:83], v[194:197], v[218:221], v[80:83]
	v_mfma_f32_16x16x32_bf16 v[68:71], v[186:189], v[228:231], v[68:71]
	v_mfma_f32_16x16x32_bf16 v[64:67], v[194:197], v[228:231], v[64:67]
	s_setprio 0
	s_barrier
; #define PG8_STAGE(bufoff, gbase, voff) do { _Pragma("unroll") for (int _i = 0; _i < 2; ++_i) \
;         __builtin_amdgcn_global_load_lds((const unsigned*)((const char*)(gbase) + (voff)[_i]), (PG8_LAS unsigned*)(lds + (bufoff) + ldsw + _i * 8192), 16, 0, 0); } while (0)
; #define PG8_LDA(dst, b, h) do { _Pragma("unroll") for (int m = 0; m < 4; ++m) _Pragma("unroll") for (int k = 0; k < 2; ++k) dst[m][k] = *(const PG8_LAS bf16x8*)(lds + PG8_SA(b, h) + aoff + m * 2048 + k * 1024); } while (0)
; #define PG8_MMA(ai, bj, At, Bt) do { __builtin_amdgcn_s_setprio(1); _Pragma("unroll") for (int m = 0; m < 4; ++m) _Pragma("unroll") for (int n = 0; n < 2; ++n) _Pragma("unroll") for (int k = 0; k < 2; ++k) \
;         acc[ai][bj][m][n] = mma16<F16>(Bt[n][k], At[m][k], acc[ai][bj][m][n]); __builtin_amdgcn_s_setprio(0); } while (0)
; #define PG8_WAIT_V(n) asm volatile("s_waitcnt vmcnt(" #n ")" ::: "memory")
; #define PG8_WAIT_L(n) asm volatile("s_waitcnt lgkmcnt(" #n ")" ::: "memory")
; #define PG8_BAR __builtin_amdgcn_s_barrier()
; #define PG8_SCHED __builtin_amdgcn_sched_barrier(0)
; template <class Epi, class Sched, bool ALIGN_EPI = false, bool SP2 = false, bool F16 = false, bool TOKPERM = false>
; __device__ __forceinline__ void gemm_phase(PG8_LAS unsigned char* lds, const Gemm g, const Sched& S, const Epi& E, int wv) {
;     ...
;             PG8_LDA(At, 1, 1); PG8_STAGE(PG8_SB(1, 0), b3, voffB); PG8_STAGE(PG8_SB(1, 1), b3 + hstep, voffB); PG8_STAGE(PG8_SA(1, 0), a3, voffA);
;             PG8_WAIT_V(8); PG8_WAIT_L(0); PG8_BAR; PG8_MMA(1, 0, At, B0); PG8_MMA(1, 1, At, B1); PG8_BAR; PG8_SCHED;
;   __device__ __forceinline__ void operator()(const pg8::f32x4 (&acc)[2][2][4][2], const pg8::Unit& u, int wr, int wc, int fr, int fq) const {
;     ...
;     const int row0 = u.pm * 256 + wr * 64 + fr + z, colb = u.pn * 256 + wc * 32 + 8 * fq + z;
; #pragma unroll
;     for (int ai = 0; ai < 2; ++ai)
; #pragma unroll
;       for (int m = 0; m < 4; ++m) {
;         const int tok = row0 + ai * 128 + m * 16; float ss = 0.f;
; #pragma unroll
;         for (int bj = 0; bj < 2; ++bj) {
;           const unsigned off = (unsigned)tok * DM + colb + 128 * bj;
;           f8_t n = __builtin_convertvector(*(const h8_t*)(x16 + off), f8_t);
	s_mov_b32 m0, s49
	v_lshl_add_u64 v[232:233], v[232:233], 0, s[14:15]
	s_add_u32 s16, s20, 0xb0080
	ds_read_b128 v[198:201], v147 offset:49152
	ds_read_b128 v[202:205], v147 offset:50176
	ds_read_b128 v[206:209], v147 offset:51200
	ds_read_b128 v[210:213], v147 offset:52224
	ds_read_b128 v[214:217], v147 offset:53248
	ds_read_b128 v[218:221], v147 offset:54272
	ds_read_b128 v[222:225], v147 offset:55296
	ds_read_b128 v[228:231], v147 offset:56320
	global_load_lds_dwordx4 v[232:233], off
	v_lshl_add_u64 v[232:233], v[234:235], 0, s[14:15]
	s_mov_b32 m0, s50
	s_addc_u32 s17, s21, 0
	global_load_lds_dwordx4 v[232:233], off
	v_lshl_add_u64 v[232:233], s[16:17], 0, v[130:131]
	s_mov_b32 m0, s53
	s_nop 0
	global_load_lds_dwordx4 v[232:233], off
	v_lshl_add_u64 v[232:233], s[16:17], 0, v[134:135]
	s_mov_b32 m0, s54
	s_nop 0
	global_load_lds_dwordx4 v[232:233], off
	v_lshl_add_u64 v[232:233], v[236:237], 0, s[14:15]
	s_mov_b32 m0, s51
	s_nop 0
	global_load_lds_dwordx4 v[232:233], off
	v_lshl_add_u64 v[232:233], v[238:239], 0, s[14:15]
	s_mov_b32 m0, s52
	s_nop 0
	global_load_lds_dwordx4 v[232:233], off
	s_waitcnt vmcnt(8)
	s_waitcnt lgkmcnt(0)
	s_barrier
	s_setprio 1
	s_waitcnt lgkmcnt(0)
	v_mfma_f32_16x16x32_bf16 v[60:63], v[166:169], v[198:201], v[60:63]
	v_mfma_f32_16x16x32_bf16 v[56:59], v[174:177], v[198:201], v[56:59]
	v_mfma_f32_16x16x32_bf16 v[44:47], v[166:169], v[206:209], v[44:47]
	v_mfma_f32_16x16x32_bf16 v[40:43], v[174:177], v[206:209], v[40:43]
	v_mfma_f32_16x16x32_bf16 v[28:31], v[166:169], v[214:217], v[28:31]
	v_mfma_f32_16x16x32_bf16 v[24:27], v[174:177], v[214:217], v[24:27]
	v_mfma_f32_16x16x32_bf16 v[12:15], v[166:169], v[222:225], v[12:15]
	v_mfma_f32_16x16x32_bf16 v[8:11], v[174:177], v[222:225], v[8:11]
	v_mfma_f32_16x16x32_bf16 v[60:63], v[170:173], v[202:205], v[60:63]
	v_mfma_f32_16x16x32_bf16 v[56:59], v[178:181], v[202:205], v[56:59]
	v_mfma_f32_16x16x32_bf16 v[44:47], v[170:173], v[210:213], v[44:47]
	v_mfma_f32_16x16x32_bf16 v[40:43], v[178:181], v[210:213], v[40:43]
	v_mfma_f32_16x16x32_bf16 v[28:31], v[170:173], v[218:221], v[28:31]
	v_mfma_f32_16x16x32_bf16 v[24:27], v[178:181], v[218:221], v[24:27]
	v_mfma_f32_16x16x32_bf16 v[12:15], v[170:173], v[228:231], v[12:15]
	v_mfma_f32_16x16x32_bf16 v[8:11], v[178:181], v[228:231], v[8:11]
	s_setprio 0
	s_setprio 1
	v_mfma_f32_16x16x32_bf16 v[52:55], v[182:185], v[198:201], v[52:55]
	v_mfma_f32_16x16x32_bf16 v[48:51], v[190:193], v[198:201], v[48:51]
	v_mfma_f32_16x16x32_bf16 v[36:39], v[182:185], v[206:209], v[36:39]
	v_mfma_f32_16x16x32_bf16 v[32:35], v[190:193], v[206:209], v[32:35]
	v_mfma_f32_16x16x32_bf16 v[20:23], v[182:185], v[214:217], v[20:23]
	v_mfma_f32_16x16x32_bf16 v[16:19], v[190:193], v[214:217], v[16:19]
	v_mfma_f32_16x16x32_bf16 v[4:7], v[182:185], v[222:225], v[4:7]
	v_mfma_f32_16x16x32_bf16 v[0:3], v[190:193], v[222:225], v[0:3]
	v_mfma_f32_16x16x32_bf16 v[52:55], v[186:189], v[202:205], v[52:55]
	v_mfma_f32_16x16x32_bf16 v[48:51], v[194:197], v[202:205], v[48:51]
	v_mfma_f32_16x16x32_bf16 v[36:39], v[186:189], v[210:213], v[36:39]
	v_mfma_f32_16x16x32_bf16 v[32:35], v[194:197], v[210:213], v[32:35]
	v_mfma_f32_16x16x32_bf16 v[20:23], v[186:189], v[218:221], v[20:23]
	v_mfma_f32_16x16x32_bf16 v[16:19], v[194:197], v[218:221], v[16:19]
	v_mfma_f32_16x16x32_bf16 v[4:7], v[186:189], v[228:231], v[4:7]
	v_mfma_f32_16x16x32_bf16 v[0:3], v[194:197], v[228:231], v[0:3]
	s_setprio 0
	s_barrier
	s_add_i32 s67, s67, 2
	s_add_u32 s65, s65, 0x100
	s_addc_u32 s66, s66, 0
	s_cmp_gt_u32 s67, 41
	s_mov_b64 s[16:17], s[18:19]
	s_cbranch_scc0 .LBB0_867
	s_lshl_b32 s16, s64, 8
	v_lshl_or_b32 v166, s63, 8, v148
	v_mov_b32 v136, 0
	v_xor_b32_e32 v169, 32, v165
	v_add3_u32 v167, s16, v146, v136
	v_add_u32_e32 v168, v166, v136
	v_lshl_add_u32 v136, v167, 10, v168
	v_lshl_add_u64 v[178:179], v[136:137], 1, s[40:41]
	v_add_u32_e32 v136, 0x80, v136
	global_load_dwordx4 v[170:173], v[178:179], off
	v_lshl_add_u64 v[180:181], v[136:137], 1, s[40:41]
	global_load_dwordx4 v[174:177], v[180:181], off
	v_add_u32_e32 v136, 16, v167
	v_lshl_add_u32 v136, v136, 10, v168
	v_lshl_add_u64 v[224:225], v[136:137], 1, s[40:41]
	v_add_u32_e32 v136, 0x80, v136
	global_load_dwordx4 v[192:195], v[224:225], off
	v_lshl_add_u64 v[248:249], v[136:137], 1, s[40:41]
	global_load_dwordx4 v[196:199], v[248:249], off
	v_add_u32_e32 v136, 32, v167
	v_lshl_add_u32 v136, v136, 10, v168
	v_lshl_add_u64 v[224:225], v[136:137], 1, s[40:41]
	v_add_u32_e32 v136, 0x80, v136
	global_load_dwordx4 v[200:203], v[224:225], off
	v_lshl_add_u64 v[248:249], v[136:137], 1, s[40:41]
	global_load_dwordx4 v[204:207], v[248:249], off
	v_add_u32_e32 v136, 48, v167
	v_lshl_add_u32 v136, v136, 10, v168
	v_lshl_add_u64 v[224:225], v[136:137], 1, s[40:41]
	v_add_u32_e32 v136, 0x80, v136
	global_load_dwordx4 v[208:211], v[224:225], off
	v_lshl_add_u64 v[248:249], v[136:137], 1, s[40:41]
	global_load_dwordx4 v[212:215], v[248:249], off
	v_add_u32_e32 v136, 0x80, v167
	v_lshl_add_u32 v136, v136, 10, v168
	v_lshl_add_u64 v[224:225], v[136:137], 1, s[40:41]
	v_add_u32_e32 v136, 0x80, v136
	global_load_dwordx4 v[216:219], v[224:225], off
	v_lshl_add_u64 v[248:249], v[136:137], 1, s[40:41]
	global_load_dwordx4 v[220:223], v[248:249], off
	v_add_u32_e32 v136, 0x90, v167
	v_lshl_add_u32 v136, v136, 10, v168
	v_lshl_add_u64 v[224:225], v[136:137], 1, s[40:41]
	v_add_u32_e32 v136, 0x80, v136
	global_load_dwordx4 v[228:231], v[224:225], off
	v_lshl_add_u64 v[248:249], v[136:137], 1, s[40:41]
	global_load_dwordx4 v[244:247], v[248:249], off
	v_and_b32_e32 v166, 64, v165
	v_xor_b32_e32 v136, 16, v165
	v_add_u32_e32 v166, 64, v166
	v_cmp_lt_i32_e32 vcc, v136, v166
	s_lshl_b32 s16, s63, 2
	s_or_b32 s18, s16, s48
	v_cndmask_b32_e32 v136, v165, v136, vcc
	v_cmp_lt_i32_e32 vcc, v169, v166
	v_lshlrev_b32_e32 v166, 2, v136
	s_waitcnt vmcnt(10)
;   __device__ __forceinline__ void operator()(const pg8::f32x4 (&acc)[2][2][4][2], const pg8::Unit& u, int wr, int wc, int fr, int fq) const {
;     ...
;         const int tok = row0 + ai * 128 + m * 16; float ss = 0.f;
; #pragma unroll
;         for (int bj = 0; bj < 2; ++bj) {
;           const unsigned off = (unsigned)tok * DM + colb + 128 * bj;
;           f8_t n = __builtin_convertvector(*(const h8_t*)(x16 + off), f8_t);
; #pragma unroll
;           for (int c = 0; c < 4; ++c) { n[c] += sc * acc[ai][bj][m][0][c]; n[4 + c] += sc * acc[ai][bj][m][1][c]; }
;           if (aux) {
;             *(h8_t*)(x16 + off) = __builtin_convertvector(n, h8_t);
;             ss += ((n[0] * n[0] + n[1] * n[1]) + (n[2] * n[2] + n[3] * n[3])) + ((n[4] * n[4] + n[5] * n[5]) + (n[6] * n[6] + n[7] * n[7]));
;           } else {
;             *(f32x4*)(xout + off) = (f32x4){n[0], n[1], n[2], n[3]}; *(f32x4*)(xout + off + 4) = (f32x4){n[4], n[5], n[6], n[7]};
;           }
;         }
;         if (aux) { ss += __shfl_xor(ss, 16); ss += __shfl_xor(ss, 32); if (fq == 0) ssq[(unsigned)tok * 16 + u.pn * 4 + wc] = ss; }
	v_cvt_f32_f16_e32 v182, v173
	v_cvt_f32_f16_sdwa v183, v173 dst_sel:DWORD dst_unused:UNUSED_PAD src0_sel:WORD_1
	v_cvt_f32_f16_e32 v184, v171
	v_cvt_f32_f16_sdwa v185, v171 dst_sel:DWORD dst_unused:UNUSED_PAD src0_sel:WORD_1
	v_cvt_f32_f16_e32 v186, v172
	v_cvt_f32_f16_sdwa v187, v172 dst_sel:DWORD dst_unused:UNUSED_PAD src0_sel:WORD_1
	v_cvt_f32_f16_e32 v172, v170
	v_cvt_f32_f16_sdwa v173, v170 dst_sel:DWORD dst_unused:UNUSED_PAD src0_sel:WORD_1
	v_cvt_f32_f16_e32 v170, v177
	v_cvt_f32_f16_sdwa v171, v177 dst_sel:DWORD dst_unused:UNUSED_PAD src0_sel:WORD_1
	v_cvt_f32_f16_e32 v188, v175
	v_cvt_f32_f16_sdwa v189, v175 dst_sel:DWORD dst_unused:UNUSED_PAD src0_sel:WORD_1
	v_cvt_f32_f16_e32 v190, v176
	v_cvt_f32_f16_sdwa v191, v176 dst_sel:DWORD dst_unused:UNUSED_PAD src0_sel:WORD_1
	v_cvt_f32_f16_e32 v176, v174
	v_cvt_f32_f16_sdwa v177, v174 dst_sel:DWORD dst_unused:UNUSED_PAD src0_sel:WORD_1
	v_pk_fma_f32 v[124:125], v[124:125], 0.5, v[172:173] op_sel_hi:[1,0,1]
	v_pk_fma_f32 v[172:173], v[120:121], 0.5, v[186:187] op_sel_hi:[1,0,1]
	v_pk_fma_f32 v[126:127], v[126:127], 0.5, v[184:185] op_sel_hi:[1,0,1]
	v_pk_fma_f32 v[122:123], v[122:123], 0.5, v[182:183] op_sel_hi:[1,0,1]
	v_cvt_pk_f16_f32 v120, v172, v173
	v_cvt_pk_f16_f32 v121, v122, v123
	v_pk_mul_f32 v[174:175], v[124:125], v[124:125]
	v_pk_mul_f32 v[182:183], v[126:127], v[126:127]
	v_pk_mul_f32 v[172:173], v[172:173], v[172:173]
	v_pk_mul_f32 v[122:123], v[122:123], v[122:123]
	v_pk_fma_f32 v[176:177], v[116:117], 0.5, v[176:177] op_sel_hi:[1,0,1]
	v_pk_fma_f32 v[116:117], v[112:113], 0.5, v[190:191] op_sel_hi:[1,0,1]
	v_pk_fma_f32 v[184:185], v[118:119], 0.5, v[188:189] op_sel_hi:[1,0,1]
	v_pk_fma_f32 v[112:113], v[114:115], 0.5, v[170:171] op_sel_hi:[1,0,1]
	v_pk_mul_f32 v[114:115], v[176:177], v[176:177]
	v_pk_mul_f32 v[118:119], v[184:185], v[184:185]
	v_pk_mul_f32 v[170:171], v[116:117], v[116:117]
	v_pk_mul_f32 v[186:187], v[112:113], v[112:113]
	v_add_f32_e32 v122, v122, v123
	v_add_f32_e32 v123, v172, v173
	v_add_f32_e32 v136, v182, v183
	v_add_f32_e32 v172, v174, v175
	v_add_f32_e32 v122, v123, v122
	v_add_f32_e32 v123, v172, v136
	v_add_f32_e32 v136, v186, v187
	v_add_f32_e32 v170, v170, v171
	v_add_f32_e32 v118, v118, v119
	v_add_f32_e32 v114, v114, v115
	v_add_f32_e32 v119, v170, v136
	v_add_f32_e32 v114, v114, v118
	v_add_f32_e32 v115, v123, v122
	v_add_f32_e32 v114, v114, v119
	v_add_f32_e32 v114, v115, v114
	v_mov_b32_e32 v115, v114
	s_nop 1
	v_permlane16_swap_b32_e32 v114, v115
	v_cndmask_b32_e32 v169, v165, v169, vcc
	v_cvt_pk_f16_f32 v119, v126, v127
	v_cvt_pk_f16_f32 v118, v124, v125
	global_store_dwordx4 v[178:179], v[118:121], off
	s_nop 1
	v_cvt_pk_f16_f32 v119, v112, v113
	s_waitcnt lgkmcnt(0)
	v_add_f32_e32 v113, v114, v115
	v_lshlrev_b32_e32 v112, 2, v169
	v_mov_b32_e32 v114, v113
	s_nop 1
	v_permlane32_swap_b32_e32 v113, v114
	v_cvt_pk_f16_f32 v118, v116, v117
	v_cvt_pk_f16_f32 v117, v184, v185
	v_cvt_pk_f16_f32 v116, v176, v177
	global_store_dwordx4 v[180:181], v[116:119], off
	s_and_saveexec_b64 s[16:17], s[6:7]
	s_cbranch_execz .LBB0_870
	v_lshl_add_u32 v136, v167, 4, s18
	s_waitcnt lgkmcnt(0)
	v_add_f32_e32 v113, v113, v114
	v_lshl_add_u64 v[114:115], v[136:137], 2, s[42:43]
	global_store_dword v[114:115], v113, off
.LBB0_870:
	s_or_b64 exec, exec, s[16:17]
	v_add_u32_e32 v113, 16, v167
	v_lshl_add_u32 v136, v113, 10, v168
	v_lshl_add_u64 v[122:123], v[136:137], 1, s[40:41]
	v_add_u32_e32 v136, 0x80, v136
	v_lshl_add_u64 v[124:125], v[136:137], 1, s[40:41]
	s_waitcnt lgkmcnt(0)
	s_waitcnt vmcnt(10)
	v_cvt_f32_f16_e32 v126, v195
	v_cvt_f32_f16_sdwa v127, v195 dst_sel:DWORD dst_unused:UNUSED_PAD src0_sel:WORD_1
	v_cvt_f32_f16_e32 v170, v193
	v_cvt_f32_f16_sdwa v171, v193 dst_sel:DWORD dst_unused:UNUSED_PAD src0_sel:WORD_1
	v_cvt_f32_f16_e32 v172, v194
	v_cvt_f32_f16_sdwa v173, v194 dst_sel:DWORD dst_unused:UNUSED_PAD src0_sel:WORD_1
	v_cvt_f32_f16_e32 v116, v192
	v_cvt_f32_f16_sdwa v117, v192 dst_sel:DWORD dst_unused:UNUSED_PAD src0_sel:WORD_1
	v_cvt_f32_f16_e32 v114, v199
	v_cvt_f32_f16_sdwa v115, v199 dst_sel:DWORD dst_unused:UNUSED_PAD src0_sel:WORD_1
	v_cvt_f32_f16_e32 v174, v197
	v_cvt_f32_f16_sdwa v175, v197 dst_sel:DWORD dst_unused:UNUSED_PAD src0_sel:WORD_1
	v_cvt_f32_f16_e32 v176, v198
	v_cvt_f32_f16_sdwa v177, v198 dst_sel:DWORD dst_unused:UNUSED_PAD src0_sel:WORD_1
	v_cvt_f32_f16_e32 v120, v196
	v_cvt_f32_f16_sdwa v121, v196 dst_sel:DWORD dst_unused:UNUSED_PAD src0_sel:WORD_1
	v_pk_fma_f32 v[108:109], v[108:109], 0.5, v[116:117] op_sel_hi:[1,0,1]
	v_pk_fma_f32 v[116:117], v[104:105], 0.5, v[172:173] op_sel_hi:[1,0,1]
	v_pk_fma_f32 v[110:111], v[110:111], 0.5, v[170:171] op_sel_hi:[1,0,1]
	v_pk_fma_f32 v[106:107], v[106:107], 0.5, v[126:127] op_sel_hi:[1,0,1]
	v_pk_fma_f32 v[120:121], v[100:101], 0.5, v[120:121] op_sel_hi:[1,0,1]
	v_pk_fma_f32 v[170:171], v[96:97], 0.5, v[176:177] op_sel_hi:[1,0,1]
	v_pk_fma_f32 v[172:173], v[102:103], 0.5, v[174:175] op_sel_hi:[1,0,1]
	v_pk_fma_f32 v[96:97], v[98:99], 0.5, v[114:115] op_sel_hi:[1,0,1]
	v_cvt_pk_f16_f32 v105, v106, v107
	v_cvt_pk_f16_f32 v104, v116, v117
	v_pk_mul_f32 v[118:119], v[108:109], v[108:109]
	v_pk_mul_f32 v[126:127], v[110:111], v[110:111]
	v_pk_mul_f32 v[116:117], v[116:117], v[116:117]
	v_pk_mul_f32 v[106:107], v[106:107], v[106:107]
	v_pk_mul_f32 v[98:99], v[120:121], v[120:121]
	v_pk_mul_f32 v[100:101], v[172:173], v[172:173]
	v_pk_mul_f32 v[102:103], v[170:171], v[170:171]
	v_pk_mul_f32 v[114:115], v[96:97], v[96:97]
	v_add_f32_e32 v106, v106, v107
	v_add_f32_e32 v107, v116, v117
	v_add_f32_e32 v116, v126, v127
	v_add_f32_e32 v117, v118, v119
	v_add_f32_e32 v114, v114, v115
	v_add_f32_e32 v102, v102, v103
	v_add_f32_e32 v100, v100, v101
	v_add_f32_e32 v98, v98, v99
	v_add_f32_e32 v106, v107, v106
	v_add_f32_e32 v107, v117, v116
	v_add_f32_e32 v101, v102, v114
	v_add_f32_e32 v98, v98, v100
	v_add_f32_e32 v99, v107, v106
	v_add_f32_e32 v98, v98, v101
	v_add_f32_e32 v98, v99, v98
	v_mov_b32_e32 v99, v98
	s_nop 1
	v_permlane16_swap_b32_e32 v98, v99
	v_cvt_pk_f16_f32 v101, v96, v97
	v_cvt_pk_f16_f32 v103, v110, v111
	v_cvt_pk_f16_f32 v102, v108, v109
	v_cvt_pk_f16_f32 v100, v170, v171
	s_waitcnt lgkmcnt(0)
	v_add_f32_e32 v96, v98, v99
	v_mov_b32_e32 v97, v96
	s_nop 1
	v_permlane32_swap_b32_e32 v96, v97
	v_cvt_pk_f16_f32 v99, v172, v173
	v_cvt_pk_f16_f32 v98, v120, v121
	global_store_dwordx4 v[122:123], v[102:105], off
	global_store_dwordx4 v[124:125], v[98:101], off
	s_and_saveexec_b64 s[16:17], s[6:7]
	s_cbranch_execz .LBB0_872
	v_lshl_add_u32 v136, v113, 4, s18
	s_waitcnt lgkmcnt(0)
	v_add_f32_e32 v98, v96, v97
	v_lshl_add_u64 v[96:97], v[136:137], 2, s[42:43]
	global_store_dword v[96:97], v98, off
;   __device__ __forceinline__ void operator()(const pg8::f32x4 (&acc)[2][2][4][2], const pg8::Unit& u, int wr, int wc, int fr, int fq) const {
;     ...
;         const int tok = row0 + ai * 128 + m * 16; float ss = 0.f;
; #pragma unroll
;         for (int bj = 0; bj < 2; ++bj) {
;           const unsigned off = (unsigned)tok * DM + colb + 128 * bj;
;           f8_t n = __builtin_convertvector(*(const h8_t*)(x16 + off), f8_t);
; #pragma unroll
;           for (int c = 0; c < 4; ++c) { n[c] += sc * acc[ai][bj][m][0][c]; n[4 + c] += sc * acc[ai][bj][m][1][c]; }
;           if (aux) {
;             *(h8_t*)(x16 + off) = __builtin_convertvector(n, h8_t);
;             ss += ((n[0] * n[0] + n[1] * n[1]) + (n[2] * n[2] + n[3] * n[3])) + ((n[4] * n[4] + n[5] * n[5]) + (n[6] * n[6] + n[7] * n[7]));
;           } else {
;             *(f32x4*)(xout + off) = (f32x4){n[0], n[1], n[2], n[3]}; *(f32x4*)(xout + off + 4) = (f32x4){n[4], n[5], n[6], n[7]};
;           }
;         }
;         if (aux) { ss += __shfl_xor(ss, 16); ss += __shfl_xor(ss, 32); if (fq == 0) ssq[(unsigned)tok * 16 + u.pn * 4 + wc] = ss; }
.LBB0_872:
	s_or_b64 exec, exec, s[16:17]
	v_add_u32_e32 v96, 32, v167
	v_lshl_add_u32 v136, v96, 10, v168
	v_lshl_add_u64 v[106:107], v[136:137], 1, s[40:41]
	v_add_u32_e32 v136, 0x80, v136
	v_lshl_add_u64 v[108:109], v[136:137], 1, s[40:41]
	s_waitcnt vmcnt(10)
	v_cvt_f32_f16_e32 v110, v203
	v_cvt_f32_f16_sdwa v111, v203 dst_sel:DWORD dst_unused:UNUSED_PAD src0_sel:WORD_1
	v_cvt_f32_f16_e32 v114, v201
	v_cvt_f32_f16_sdwa v115, v201 dst_sel:DWORD dst_unused:UNUSED_PAD src0_sel:WORD_1
	v_cvt_f32_f16_e32 v116, v202
	v_cvt_f32_f16_sdwa v117, v202 dst_sel:DWORD dst_unused:UNUSED_PAD src0_sel:WORD_1
	v_cvt_f32_f16_e32 v100, v200
	v_cvt_f32_f16_sdwa v101, v200 dst_sel:DWORD dst_unused:UNUSED_PAD src0_sel:WORD_1
	v_cvt_f32_f16_e32 v98, v207
	v_cvt_f32_f16_sdwa v99, v207 dst_sel:DWORD dst_unused:UNUSED_PAD src0_sel:WORD_1
	v_cvt_f32_f16_e32 v118, v205
	v_cvt_f32_f16_sdwa v119, v205 dst_sel:DWORD dst_unused:UNUSED_PAD src0_sel:WORD_1
	v_cvt_f32_f16_e32 v120, v206
	v_cvt_f32_f16_sdwa v121, v206 dst_sel:DWORD dst_unused:UNUSED_PAD src0_sel:WORD_1
	v_cvt_f32_f16_e32 v104, v204
	v_cvt_f32_f16_sdwa v105, v204 dst_sel:DWORD dst_unused:UNUSED_PAD src0_sel:WORD_1
	v_pk_fma_f32 v[92:93], v[92:93], 0.5, v[100:101] op_sel_hi:[1,0,1]
	v_pk_fma_f32 v[100:101], v[88:89], 0.5, v[116:117] op_sel_hi:[1,0,1]
	v_pk_fma_f32 v[94:95], v[94:95], 0.5, v[114:115] op_sel_hi:[1,0,1]
	v_pk_fma_f32 v[90:91], v[90:91], 0.5, v[110:111] op_sel_hi:[1,0,1]
	v_cvt_pk_f16_f32 v88, v100, v101
	v_cvt_pk_f16_f32 v89, v90, v91
	v_pk_mul_f32 v[102:103], v[92:93], v[92:93]
	v_pk_mul_f32 v[110:111], v[94:95], v[94:95]
	v_pk_mul_f32 v[100:101], v[100:101], v[100:101]
	v_pk_mul_f32 v[90:91], v[90:91], v[90:91]
	v_pk_fma_f32 v[104:105], v[84:85], 0.5, v[104:105] op_sel_hi:[1,0,1]
	v_pk_fma_f32 v[114:115], v[80:81], 0.5, v[120:121] op_sel_hi:[1,0,1]
	v_pk_fma_f32 v[116:117], v[86:87], 0.5, v[118:119] op_sel_hi:[1,0,1]
	v_pk_fma_f32 v[80:81], v[82:83], 0.5, v[98:99] op_sel_hi:[1,0,1]
	v_pk_mul_f32 v[82:83], v[104:105], v[104:105]
	v_pk_mul_f32 v[84:85], v[116:117], v[116:117]
	v_pk_mul_f32 v[86:87], v[114:115], v[114:115]
	v_pk_mul_f32 v[98:99], v[80:81], v[80:81]
	v_add_f32_e32 v90, v90, v91
	v_add_f32_e32 v91, v100, v101
	s_waitcnt lgkmcnt(0)
	v_add_f32_e32 v97, v110, v111
	v_add_f32_e32 v100, v102, v103
	v_add_f32_e32 v90, v91, v90
	v_add_f32_e32 v91, v100, v97
	v_add_f32_e32 v97, v98, v99
	v_add_f32_e32 v86, v86, v87
	v_add_f32_e32 v84, v84, v85
	v_add_f32_e32 v82, v82, v83
	v_add_f32_e32 v85, v86, v97
	v_add_f32_e32 v82, v82, v84
	v_add_f32_e32 v83, v91, v90
	v_add_f32_e32 v82, v82, v85
	v_add_f32_e32 v82, v83, v82
	v_mov_b32_e32 v83, v82
	s_nop 1
	v_permlane16_swap_b32_e32 v82, v83
	v_cvt_pk_f16_f32 v85, v80, v81
	v_cvt_pk_f16_f32 v87, v94, v95
	v_cvt_pk_f16_f32 v86, v92, v93
	v_cvt_pk_f16_f32 v84, v114, v115
	s_waitcnt lgkmcnt(0)
	v_add_f32_e32 v80, v82, v83
	v_mov_b32_e32 v81, v80
	s_nop 1
	v_permlane32_swap_b32_e32 v80, v81
	v_cvt_pk_f16_f32 v83, v116, v117
	v_cvt_pk_f16_f32 v82, v104, v105
	global_store_dwordx4 v[106:107], v[86:89], off
	global_store_dwordx4 v[108:109], v[82:85], off
	s_and_saveexec_b64 s[16:17], s[6:7]
	s_cbranch_execz .LBB0_874
	v_lshl_add_u32 v136, v96, 4, s18
	s_waitcnt lgkmcnt(0)
	v_add_f32_e32 v82, v80, v81
	v_lshl_add_u64 v[80:81], v[136:137], 2, s[42:43]
	global_store_dword v[80:81], v82, off
.LBB0_874:
	s_or_b64 exec, exec, s[16:17]
	v_add_u32_e32 v80, 48, v167
	v_lshl_add_u32 v136, v80, 10, v168
	v_lshl_add_u64 v[90:91], v[136:137], 1, s[40:41]
	v_add_u32_e32 v136, 0x80, v136
	v_lshl_add_u64 v[92:93], v[136:137], 1, s[40:41]
	s_waitcnt vmcnt(10)
	v_cvt_f32_f16_e32 v94, v211
	v_cvt_f32_f16_sdwa v95, v211 dst_sel:DWORD dst_unused:UNUSED_PAD src0_sel:WORD_1
	v_cvt_f32_f16_e32 v96, v209
	v_cvt_f32_f16_sdwa v97, v209 dst_sel:DWORD dst_unused:UNUSED_PAD src0_sel:WORD_1
	v_cvt_f32_f16_e32 v98, v210
	v_cvt_f32_f16_sdwa v99, v210 dst_sel:DWORD dst_unused:UNUSED_PAD src0_sel:WORD_1
	v_cvt_f32_f16_e32 v84, v208
	v_cvt_f32_f16_sdwa v85, v208 dst_sel:DWORD dst_unused:UNUSED_PAD src0_sel:WORD_1
	v_cvt_f32_f16_e32 v82, v215
	v_cvt_f32_f16_sdwa v83, v215 dst_sel:DWORD dst_unused:UNUSED_PAD src0_sel:WORD_1
	v_cvt_f32_f16_e32 v100, v213
	v_cvt_f32_f16_sdwa v101, v213 dst_sel:DWORD dst_unused:UNUSED_PAD src0_sel:WORD_1
	v_cvt_f32_f16_e32 v102, v214
	v_cvt_f32_f16_sdwa v103, v214 dst_sel:DWORD dst_unused:UNUSED_PAD src0_sel:WORD_1
	v_cvt_f32_f16_e32 v88, v212
	v_cvt_f32_f16_sdwa v89, v212 dst_sel:DWORD dst_unused:UNUSED_PAD src0_sel:WORD_1
	v_pk_fma_f32 v[76:77], v[76:77], 0.5, v[84:85] op_sel_hi:[1,0,1]
	v_pk_fma_f32 v[84:85], v[72:73], 0.5, v[98:99] op_sel_hi:[1,0,1]
	v_pk_fma_f32 v[78:79], v[78:79], 0.5, v[96:97] op_sel_hi:[1,0,1]
	v_pk_fma_f32 v[74:75], v[74:75], 0.5, v[94:95] op_sel_hi:[1,0,1]
	v_cvt_pk_f16_f32 v72, v84, v85
	v_cvt_pk_f16_f32 v73, v74, v75
	v_pk_mul_f32 v[86:87], v[76:77], v[76:77]
	v_pk_mul_f32 v[94:95], v[78:79], v[78:79]
	v_pk_mul_f32 v[84:85], v[84:85], v[84:85]
	v_pk_mul_f32 v[74:75], v[74:75], v[74:75]
	v_pk_fma_f32 v[88:89], v[68:69], 0.5, v[88:89] op_sel_hi:[1,0,1]
	v_pk_fma_f32 v[96:97], v[64:65], 0.5, v[102:103] op_sel_hi:[1,0,1]
	v_pk_fma_f32 v[98:99], v[70:71], 0.5, v[100:101] op_sel_hi:[1,0,1]
	v_pk_fma_f32 v[64:65], v[66:67], 0.5, v[82:83] op_sel_hi:[1,0,1]
	v_pk_mul_f32 v[66:67], v[88:89], v[88:89]
	v_pk_mul_f32 v[68:69], v[98:99], v[98:99]
	v_pk_mul_f32 v[70:71], v[96:97], v[96:97]
	v_pk_mul_f32 v[82:83], v[64:65], v[64:65]
	v_add_f32_e32 v74, v74, v75
	v_add_f32_e32 v75, v84, v85
	s_waitcnt lgkmcnt(0)
	v_add_f32_e32 v81, v94, v95
	v_add_f32_e32 v84, v86, v87
	v_add_f32_e32 v74, v75, v74
	v_add_f32_e32 v75, v84, v81
	v_add_f32_e32 v81, v82, v83
	v_add_f32_e32 v70, v70, v71
	v_add_f32_e32 v68, v68, v69
	v_add_f32_e32 v66, v66, v67
	v_add_f32_e32 v69, v70, v81
	v_add_f32_e32 v66, v66, v68
	v_add_f32_e32 v67, v75, v74
	v_add_f32_e32 v66, v66, v69
	v_add_f32_e32 v66, v67, v66
	v_mov_b32_e32 v67, v66
	s_nop 1
	v_permlane16_swap_b32_e32 v66, v67
	v_cvt_pk_f16_f32 v69, v64, v65
	v_cvt_pk_f16_f32 v71, v78, v79
	v_cvt_pk_f16_f32 v70, v76, v77
	v_cvt_pk_f16_f32 v68, v96, v97
	s_waitcnt lgkmcnt(0)
	v_add_f32_e32 v64, v66, v67
	v_mov_b32_e32 v65, v64
	s_nop 1
	v_permlane32_swap_b32_e32 v64, v65
	v_cvt_pk_f16_f32 v67, v98, v99
	v_cvt_pk_f16_f32 v66, v88, v89
	global_store_dwordx4 v[90:91], v[70:73], off
	global_store_dwordx4 v[92:93], v[66:69], off
	s_and_saveexec_b64 s[16:17], s[6:7]
	s_cbranch_execz .LBB0_876
	v_lshl_add_u32 v136, v80, 4, s18
	s_waitcnt lgkmcnt(0)
	v_add_f32_e32 v66, v64, v65
	v_lshl_add_u64 v[64:65], v[136:137], 2, s[42:43]
	global_store_dword v[64:65], v66, off
;   __device__ __forceinline__ void operator()(const pg8::f32x4 (&acc)[2][2][4][2], const pg8::Unit& u, int wr, int wc, int fr, int fq) const {
;     ...
;         const int tok = row0 + ai * 128 + m * 16; float ss = 0.f;
; #pragma unroll
;         for (int bj = 0; bj < 2; ++bj) {
;           const unsigned off = (unsigned)tok * DM + colb + 128 * bj;
;           f8_t n = __builtin_convertvector(*(const h8_t*)(x16 + off), f8_t);
; #pragma unroll
;           for (int c = 0; c < 4; ++c) { n[c] += sc * acc[ai][bj][m][0][c]; n[4 + c] += sc * acc[ai][bj][m][1][c]; }
;           if (aux) {
;             *(h8_t*)(x16 + off) = __builtin_convertvector(n, h8_t);
;             ss += ((n[0] * n[0] + n[1] * n[1]) + (n[2] * n[2] + n[3] * n[3])) + ((n[4] * n[4] + n[5] * n[5]) + (n[6] * n[6] + n[7] * n[7]));
;           } else {
;             *(f32x4*)(xout + off) = (f32x4){n[0], n[1], n[2], n[3]}; *(f32x4*)(xout + off + 4) = (f32x4){n[4], n[5], n[6], n[7]};
;           }
;         }
;         if (aux) { ss += __shfl_xor(ss, 16); ss += __shfl_xor(ss, 32); if (fq == 0) ssq[(unsigned)tok * 16 + u.pn * 4 + wc] = ss; }
.LBB0_876:
	s_or_b64 exec, exec, s[16:17]
	v_add_u32_e32 v64, 0x80, v167
	v_lshl_add_u32 v136, v64, 10, v168
	v_lshl_add_u64 v[74:75], v[136:137], 1, s[40:41]
	v_add_u32_e32 v136, 0x80, v136
	v_lshl_add_u64 v[76:77], v[136:137], 1, s[40:41]
	s_waitcnt vmcnt(10)
	v_cvt_f32_f16_e32 v78, v219
	v_cvt_f32_f16_sdwa v79, v219 dst_sel:DWORD dst_unused:UNUSED_PAD src0_sel:WORD_1
	v_cvt_f32_f16_e32 v80, v217
	v_cvt_f32_f16_sdwa v81, v217 dst_sel:DWORD dst_unused:UNUSED_PAD src0_sel:WORD_1
	v_cvt_f32_f16_e32 v82, v218
	v_cvt_f32_f16_sdwa v83, v218 dst_sel:DWORD dst_unused:UNUSED_PAD src0_sel:WORD_1
	v_cvt_f32_f16_e32 v68, v216
	v_cvt_f32_f16_sdwa v69, v216 dst_sel:DWORD dst_unused:UNUSED_PAD src0_sel:WORD_1
	v_cvt_f32_f16_e32 v66, v223
	v_cvt_f32_f16_sdwa v67, v223 dst_sel:DWORD dst_unused:UNUSED_PAD src0_sel:WORD_1
	v_cvt_f32_f16_e32 v84, v221
	v_cvt_f32_f16_sdwa v85, v221 dst_sel:DWORD dst_unused:UNUSED_PAD src0_sel:WORD_1
	v_cvt_f32_f16_e32 v86, v222
	v_cvt_f32_f16_sdwa v87, v222 dst_sel:DWORD dst_unused:UNUSED_PAD src0_sel:WORD_1
	v_cvt_f32_f16_e32 v72, v220
	v_cvt_f32_f16_sdwa v73, v220 dst_sel:DWORD dst_unused:UNUSED_PAD src0_sel:WORD_1
	v_pk_fma_f32 v[60:61], v[60:61], 0.5, v[68:69] op_sel_hi:[1,0,1]
	v_pk_fma_f32 v[68:69], v[56:57], 0.5, v[82:83] op_sel_hi:[1,0,1]
	v_pk_fma_f32 v[62:63], v[62:63], 0.5, v[80:81] op_sel_hi:[1,0,1]
	v_pk_fma_f32 v[58:59], v[58:59], 0.5, v[78:79] op_sel_hi:[1,0,1]
	v_cvt_pk_f16_f32 v56, v68, v69
	v_cvt_pk_f16_f32 v57, v58, v59
	v_pk_mul_f32 v[70:71], v[60:61], v[60:61]
	v_pk_mul_f32 v[78:79], v[62:63], v[62:63]
	v_pk_mul_f32 v[68:69], v[68:69], v[68:69]
	v_pk_mul_f32 v[58:59], v[58:59], v[58:59]
	v_pk_fma_f32 v[72:73], v[52:53], 0.5, v[72:73] op_sel_hi:[1,0,1]
	v_pk_fma_f32 v[80:81], v[48:49], 0.5, v[86:87] op_sel_hi:[1,0,1]
	v_pk_fma_f32 v[82:83], v[54:55], 0.5, v[84:85] op_sel_hi:[1,0,1]
	v_pk_fma_f32 v[48:49], v[50:51], 0.5, v[66:67] op_sel_hi:[1,0,1]
	v_pk_mul_f32 v[50:51], v[72:73], v[72:73]
	v_pk_mul_f32 v[52:53], v[82:83], v[82:83]
	v_pk_mul_f32 v[54:55], v[80:81], v[80:81]
	v_pk_mul_f32 v[66:67], v[48:49], v[48:49]
	v_add_f32_e32 v58, v58, v59
	v_add_f32_e32 v59, v68, v69
	s_waitcnt lgkmcnt(0)
	v_add_f32_e32 v65, v78, v79
	v_add_f32_e32 v68, v70, v71
	v_add_f32_e32 v58, v59, v58
	v_add_f32_e32 v59, v68, v65
	v_add_f32_e32 v65, v66, v67
	v_add_f32_e32 v54, v54, v55
	v_add_f32_e32 v52, v52, v53
	v_add_f32_e32 v50, v50, v51
	v_add_f32_e32 v53, v54, v65
	v_add_f32_e32 v50, v50, v52
	v_add_f32_e32 v51, v59, v58
	v_add_f32_e32 v50, v50, v53
	v_add_f32_e32 v50, v51, v50
	v_mov_b32_e32 v51, v50
	s_nop 1
	v_permlane16_swap_b32_e32 v50, v51
	v_cvt_pk_f16_f32 v53, v48, v49
	v_cvt_pk_f16_f32 v55, v62, v63
	v_cvt_pk_f16_f32 v54, v60, v61
	v_cvt_pk_f16_f32 v52, v80, v81
	s_waitcnt lgkmcnt(0)
	v_add_f32_e32 v48, v50, v51
	v_mov_b32_e32 v49, v48
	s_nop 1
	v_permlane32_swap_b32_e32 v48, v49
	v_cvt_pk_f16_f32 v51, v82, v83
	v_cvt_pk_f16_f32 v50, v72, v73
	global_store_dwordx4 v[74:75], v[54:57], off
	global_store_dwordx4 v[76:77], v[50:53], off
	s_and_saveexec_b64 s[16:17], s[6:7]
	s_cbranch_execz .LBB0_878
	v_lshl_add_u32 v136, v64, 4, s18
	s_waitcnt lgkmcnt(0)
	v_add_f32_e32 v50, v48, v49
	v_lshl_add_u64 v[48:49], v[136:137], 2, s[42:43]
	global_store_dword v[48:49], v50, off
.LBB0_878:
	s_or_b64 exec, exec, s[16:17]
	v_add_u32_e32 v48, 0x90, v167
	v_lshl_add_u32 v136, v48, 10, v168
	v_lshl_add_u64 v[58:59], v[136:137], 1, s[40:41]
	v_add_u32_e32 v136, 0x80, v136
	v_lshl_add_u64 v[60:61], v[136:137], 1, s[40:41]
	s_waitcnt vmcnt(10)
	v_cvt_f32_f16_e32 v62, v231
	v_cvt_f32_f16_sdwa v63, v231 dst_sel:DWORD dst_unused:UNUSED_PAD src0_sel:WORD_1
	v_cvt_f32_f16_e32 v64, v229
	v_cvt_f32_f16_sdwa v65, v229 dst_sel:DWORD dst_unused:UNUSED_PAD src0_sel:WORD_1
	v_cvt_f32_f16_e32 v66, v230
	v_cvt_f32_f16_sdwa v67, v230 dst_sel:DWORD dst_unused:UNUSED_PAD src0_sel:WORD_1
	v_cvt_f32_f16_e32 v52, v228
	v_cvt_f32_f16_sdwa v53, v228 dst_sel:DWORD dst_unused:UNUSED_PAD src0_sel:WORD_1
	v_cvt_f32_f16_e32 v50, v247
	v_cvt_f32_f16_sdwa v51, v247 dst_sel:DWORD dst_unused:UNUSED_PAD src0_sel:WORD_1
	v_cvt_f32_f16_e32 v68, v245
	v_cvt_f32_f16_sdwa v69, v245 dst_sel:DWORD dst_unused:UNUSED_PAD src0_sel:WORD_1
	v_cvt_f32_f16_e32 v70, v246
	v_cvt_f32_f16_sdwa v71, v246 dst_sel:DWORD dst_unused:UNUSED_PAD src0_sel:WORD_1
	v_cvt_f32_f16_e32 v56, v244
	v_cvt_f32_f16_sdwa v57, v244 dst_sel:DWORD dst_unused:UNUSED_PAD src0_sel:WORD_1
	v_pk_fma_f32 v[44:45], v[44:45], 0.5, v[52:53] op_sel_hi:[1,0,1]
	v_pk_fma_f32 v[52:53], v[40:41], 0.5, v[66:67] op_sel_hi:[1,0,1]
	v_pk_fma_f32 v[46:47], v[46:47], 0.5, v[64:65] op_sel_hi:[1,0,1]
	v_pk_fma_f32 v[42:43], v[42:43], 0.5, v[62:63] op_sel_hi:[1,0,1]
	v_cvt_pk_f16_f32 v40, v52, v53
	v_cvt_pk_f16_f32 v41, v42, v43
	v_pk_mul_f32 v[54:55], v[44:45], v[44:45]
	v_pk_mul_f32 v[62:63], v[46:47], v[46:47]
	v_pk_mul_f32 v[52:53], v[52:53], v[52:53]
	v_pk_mul_f32 v[42:43], v[42:43], v[42:43]
	v_pk_fma_f32 v[56:57], v[36:37], 0.5, v[56:57] op_sel_hi:[1,0,1]
	v_pk_fma_f32 v[64:65], v[32:33], 0.5, v[70:71] op_sel_hi:[1,0,1]
	v_pk_fma_f32 v[66:67], v[38:39], 0.5, v[68:69] op_sel_hi:[1,0,1]
	v_pk_fma_f32 v[32:33], v[34:35], 0.5, v[50:51] op_sel_hi:[1,0,1]
	v_pk_mul_f32 v[34:35], v[56:57], v[56:57]
	v_pk_mul_f32 v[36:37], v[66:67], v[66:67]
	v_pk_mul_f32 v[38:39], v[64:65], v[64:65]
	v_pk_mul_f32 v[50:51], v[32:33], v[32:33]
	v_add_f32_e32 v42, v42, v43
	v_add_f32_e32 v43, v52, v53
	s_waitcnt lgkmcnt(0)
	v_add_f32_e32 v49, v62, v63
	v_add_f32_e32 v52, v54, v55
	v_add_f32_e32 v42, v43, v42
	v_add_f32_e32 v43, v52, v49
	v_add_f32_e32 v49, v50, v51
	v_add_f32_e32 v38, v38, v39
	v_add_f32_e32 v36, v36, v37
	v_add_f32_e32 v34, v34, v35
	v_add_f32_e32 v37, v38, v49
	v_add_f32_e32 v34, v34, v36
	v_add_f32_e32 v35, v43, v42
	v_add_f32_e32 v34, v34, v37
	v_add_f32_e32 v34, v35, v34
	v_mov_b32_e32 v35, v34
	s_nop 1
	v_permlane16_swap_b32_e32 v34, v35
	v_cvt_pk_f16_f32 v37, v32, v33
	v_cvt_pk_f16_f32 v39, v46, v47
	v_cvt_pk_f16_f32 v38, v44, v45
	v_cvt_pk_f16_f32 v36, v64, v65
	s_waitcnt lgkmcnt(0)
	v_add_f32_e32 v32, v34, v35
	v_mov_b32_e32 v33, v32
	s_nop 1
	v_permlane32_swap_b32_e32 v32, v33
	v_cvt_pk_f16_f32 v35, v66, v67
	v_cvt_pk_f16_f32 v34, v56, v57
	global_store_dwordx4 v[58:59], v[38:41], off
	global_store_dwordx4 v[60:61], v[34:37], off
	s_and_saveexec_b64 s[16:17], s[6:7]
	s_cbranch_execz .LBB0_880
	v_lshl_add_u32 v136, v48, 4, s18
	s_waitcnt lgkmcnt(0)
	v_add_f32_e32 v34, v32, v33
	v_lshl_add_u64 v[32:33], v[136:137], 2, s[42:43]
	global_store_dword v[32:33], v34, off
;   __device__ __forceinline__ void operator()(const pg8::f32x4 (&acc)[2][2][4][2], const pg8::Unit& u, int wr, int wc, int fr, int fq) const {
;     ...
;         const int tok = row0 + ai * 128 + m * 16; float ss = 0.f;
; #pragma unroll
;         for (int bj = 0; bj < 2; ++bj) {
;           const unsigned off = (unsigned)tok * DM + colb + 128 * bj;
;           f8_t n = __builtin_convertvector(*(const h8_t*)(x16 + off), f8_t);
; #pragma unroll
;           for (int c = 0; c < 4; ++c) { n[c] += sc * acc[ai][bj][m][0][c]; n[4 + c] += sc * acc[ai][bj][m][1][c]; }
;           if (aux) {
;             *(h8_t*)(x16 + off) = __builtin_convertvector(n, h8_t);
;             ss += ((n[0] * n[0] + n[1] * n[1]) + (n[2] * n[2] + n[3] * n[3])) + ((n[4] * n[4] + n[5] * n[5]) + (n[6] * n[6] + n[7] * n[7]));
;           } else {
;             *(f32x4*)(xout + off) = (f32x4){n[0], n[1], n[2], n[3]}; *(f32x4*)(xout + off + 4) = (f32x4){n[4], n[5], n[6], n[7]};
;           }
;         }
;         if (aux) { ss += __shfl_xor(ss, 16); ss += __shfl_xor(ss, 32); if (fq == 0) ssq[(unsigned)tok * 16 + u.pn * 4 + wc] = ss; }
.LBB0_880:
	s_or_b64 exec, exec, s[16:17]
	v_add_u32_e32 v32, 0xa0, v167
	v_lshl_add_u32 v136, v32, 10, v168
	v_lshl_add_u64 v[42:43], v[136:137], 1, s[40:41]
	v_add_u32_e32 v136, 0x80, v136
	global_load_dwordx4 v[34:37], v[42:43], off
	v_lshl_add_u64 v[44:45], v[136:137], 1, s[40:41]
	global_load_dwordx4 v[38:41], v[44:45], off
	s_waitcnt vmcnt(1)
	v_cvt_f32_f16_e32 v46, v37
	v_cvt_f32_f16_sdwa v47, v37 dst_sel:DWORD dst_unused:UNUSED_PAD src0_sel:WORD_1
	v_cvt_f32_f16_e32 v48, v35
	v_cvt_f32_f16_sdwa v49, v35 dst_sel:DWORD dst_unused:UNUSED_PAD src0_sel:WORD_1
	v_cvt_f32_f16_e32 v50, v36
	v_cvt_f32_f16_sdwa v51, v36 dst_sel:DWORD dst_unused:UNUSED_PAD src0_sel:WORD_1
	v_cvt_f32_f16_e32 v36, v34
	v_cvt_f32_f16_sdwa v37, v34 dst_sel:DWORD dst_unused:UNUSED_PAD src0_sel:WORD_1
	s_waitcnt vmcnt(0)
	v_cvt_f32_f16_e32 v34, v41
	v_cvt_f32_f16_sdwa v35, v41 dst_sel:DWORD dst_unused:UNUSED_PAD src0_sel:WORD_1
	v_cvt_f32_f16_e32 v52, v39
	v_cvt_f32_f16_sdwa v53, v39 dst_sel:DWORD dst_unused:UNUSED_PAD src0_sel:WORD_1
	v_cvt_f32_f16_e32 v54, v40
	v_cvt_f32_f16_sdwa v55, v40 dst_sel:DWORD dst_unused:UNUSED_PAD src0_sel:WORD_1
	v_cvt_f32_f16_e32 v40, v38
	v_cvt_f32_f16_sdwa v41, v38 dst_sel:DWORD dst_unused:UNUSED_PAD src0_sel:WORD_1
	v_pk_fma_f32 v[28:29], v[28:29], 0.5, v[36:37] op_sel_hi:[1,0,1]
	v_pk_fma_f32 v[36:37], v[24:25], 0.5, v[50:51] op_sel_hi:[1,0,1]
	v_pk_fma_f32 v[30:31], v[30:31], 0.5, v[48:49] op_sel_hi:[1,0,1]
	v_pk_fma_f32 v[26:27], v[26:27], 0.5, v[46:47] op_sel_hi:[1,0,1]
	v_cvt_pk_f16_f32 v24, v36, v37
	v_cvt_pk_f16_f32 v25, v26, v27
	v_pk_mul_f32 v[38:39], v[28:29], v[28:29]
	v_pk_mul_f32 v[46:47], v[30:31], v[30:31]
	v_pk_mul_f32 v[36:37], v[36:37], v[36:37]
	v_pk_mul_f32 v[26:27], v[26:27], v[26:27]
	v_pk_fma_f32 v[40:41], v[20:21], 0.5, v[40:41] op_sel_hi:[1,0,1]
	v_pk_fma_f32 v[48:49], v[16:17], 0.5, v[54:55] op_sel_hi:[1,0,1]
	v_pk_fma_f32 v[50:51], v[22:23], 0.5, v[52:53] op_sel_hi:[1,0,1]
	v_pk_fma_f32 v[16:17], v[18:19], 0.5, v[34:35] op_sel_hi:[1,0,1]
	v_pk_mul_f32 v[18:19], v[40:41], v[40:41]
	v_pk_mul_f32 v[20:21], v[50:51], v[50:51]
	v_pk_mul_f32 v[22:23], v[48:49], v[48:49]
	v_pk_mul_f32 v[34:35], v[16:17], v[16:17]
	v_add_f32_e32 v26, v26, v27
	v_add_f32_e32 v27, v36, v37
	s_waitcnt lgkmcnt(0)
	v_add_f32_e32 v33, v46, v47
	v_add_f32_e32 v36, v38, v39
	v_add_f32_e32 v26, v27, v26
	v_add_f32_e32 v27, v36, v33
	v_add_f32_e32 v33, v34, v35
	v_add_f32_e32 v22, v22, v23
	v_add_f32_e32 v20, v20, v21
	v_add_f32_e32 v18, v18, v19
	v_add_f32_e32 v21, v22, v33
	v_add_f32_e32 v18, v18, v20
	v_add_f32_e32 v19, v27, v26
	v_add_f32_e32 v18, v18, v21
	v_add_f32_e32 v18, v19, v18
	v_mov_b32_e32 v19, v18
	s_nop 1
	v_permlane16_swap_b32_e32 v18, v19
	v_cvt_pk_f16_f32 v21, v16, v17
	v_cvt_pk_f16_f32 v23, v30, v31
	v_cvt_pk_f16_f32 v22, v28, v29
	v_cvt_pk_f16_f32 v20, v48, v49
	s_waitcnt lgkmcnt(0)
	v_add_f32_e32 v16, v18, v19
	v_mov_b32_e32 v17, v16
	s_nop 1
	v_permlane32_swap_b32_e32 v16, v17
	v_cvt_pk_f16_f32 v19, v50, v51
	v_cvt_pk_f16_f32 v18, v40, v41
	global_store_dwordx4 v[42:43], v[22:25], off
	global_store_dwordx4 v[44:45], v[18:21], off
	s_and_saveexec_b64 s[16:17], s[6:7]
	s_cbranch_execz .LBB0_882
	v_lshl_add_u32 v136, v32, 4, s18
	s_waitcnt lgkmcnt(0)
	v_add_f32_e32 v18, v16, v17
	v_lshl_add_u64 v[16:17], v[136:137], 2, s[42:43]
	global_store_dword v[16:17], v18, off
.LBB0_882:
	s_or_b64 exec, exec, s[16:17]
	v_add_u32_e32 v16, 0xb0, v167
	v_lshl_add_u32 v136, v16, 10, v168
	v_lshl_add_u64 v[26:27], v[136:137], 1, s[40:41]
	v_add_u32_e32 v136, 0x80, v136
	global_load_dwordx4 v[18:21], v[26:27], off
	v_lshl_add_u64 v[28:29], v[136:137], 1, s[40:41]
	global_load_dwordx4 v[22:25], v[28:29], off
	s_waitcnt vmcnt(1)
	v_cvt_f32_f16_e32 v30, v21
	v_cvt_f32_f16_sdwa v31, v21 dst_sel:DWORD dst_unused:UNUSED_PAD src0_sel:WORD_1
	v_cvt_f32_f16_e32 v32, v19
	v_cvt_f32_f16_sdwa v33, v19 dst_sel:DWORD dst_unused:UNUSED_PAD src0_sel:WORD_1
	v_cvt_f32_f16_e32 v34, v20
	v_cvt_f32_f16_sdwa v35, v20 dst_sel:DWORD dst_unused:UNUSED_PAD src0_sel:WORD_1
	v_cvt_f32_f16_e32 v20, v18
	v_cvt_f32_f16_sdwa v21, v18 dst_sel:DWORD dst_unused:UNUSED_PAD src0_sel:WORD_1
	s_waitcnt vmcnt(0)
	v_cvt_f32_f16_e32 v18, v25
	v_cvt_f32_f16_sdwa v19, v25 dst_sel:DWORD dst_unused:UNUSED_PAD src0_sel:WORD_1
	v_cvt_f32_f16_e32 v36, v23
	v_cvt_f32_f16_sdwa v37, v23 dst_sel:DWORD dst_unused:UNUSED_PAD src0_sel:WORD_1
	v_cvt_f32_f16_e32 v38, v24
	v_cvt_f32_f16_sdwa v39, v24 dst_sel:DWORD dst_unused:UNUSED_PAD src0_sel:WORD_1
	v_cvt_f32_f16_e32 v24, v22
	v_cvt_f32_f16_sdwa v25, v22 dst_sel:DWORD dst_unused:UNUSED_PAD src0_sel:WORD_1
	v_pk_fma_f32 v[12:13], v[12:13], 0.5, v[20:21] op_sel_hi:[1,0,1]
	v_pk_fma_f32 v[20:21], v[8:9], 0.5, v[34:35] op_sel_hi:[1,0,1]
	v_pk_fma_f32 v[14:15], v[14:15], 0.5, v[32:33] op_sel_hi:[1,0,1]
	v_pk_fma_f32 v[10:11], v[10:11], 0.5, v[30:31] op_sel_hi:[1,0,1]
	v_cvt_pk_f16_f32 v8, v20, v21
	v_cvt_pk_f16_f32 v9, v10, v11
	v_pk_mul_f32 v[22:23], v[12:13], v[12:13]
	v_pk_mul_f32 v[30:31], v[14:15], v[14:15]
	v_pk_mul_f32 v[20:21], v[20:21], v[20:21]
	v_pk_mul_f32 v[10:11], v[10:11], v[10:11]
	v_pk_fma_f32 v[24:25], v[4:5], 0.5, v[24:25] op_sel_hi:[1,0,1]
	v_pk_fma_f32 v[32:33], v[0:1], 0.5, v[38:39] op_sel_hi:[1,0,1]
	v_pk_fma_f32 v[34:35], v[6:7], 0.5, v[36:37] op_sel_hi:[1,0,1]
	v_pk_fma_f32 v[0:1], v[2:3], 0.5, v[18:19] op_sel_hi:[1,0,1]
	v_pk_mul_f32 v[2:3], v[24:25], v[24:25]
	v_pk_mul_f32 v[4:5], v[34:35], v[34:35]
	v_pk_mul_f32 v[6:7], v[32:33], v[32:33]
	v_pk_mul_f32 v[18:19], v[0:1], v[0:1]
	v_add_f32_e32 v10, v10, v11
	v_add_f32_e32 v11, v20, v21
	s_waitcnt lgkmcnt(0)
	v_add_f32_e32 v17, v30, v31
	v_add_f32_e32 v20, v22, v23
	v_add_f32_e32 v10, v11, v10
	v_add_f32_e32 v11, v20, v17
	v_add_f32_e32 v17, v18, v19
	v_add_f32_e32 v6, v6, v7
	v_add_f32_e32 v4, v4, v5
	v_add_f32_e32 v2, v2, v3
	v_add_f32_e32 v5, v6, v17
	v_add_f32_e32 v2, v2, v4
	v_add_f32_e32 v3, v11, v10
	v_add_f32_e32 v2, v2, v5
	v_add_f32_e32 v2, v3, v2
	v_mov_b32_e32 v3, v2
	s_nop 1
	v_permlane16_swap_b32_e32 v2, v3
	v_cvt_pk_f16_f32 v5, v0, v1
	v_cvt_pk_f16_f32 v7, v14, v15
	v_cvt_pk_f16_f32 v6, v12, v13
	v_cvt_pk_f16_f32 v4, v32, v33
	s_waitcnt lgkmcnt(0)
	v_add_f32_e32 v0, v2, v3
	v_mov_b32_e32 v1, v0
	s_nop 1
	v_permlane32_swap_b32_e32 v0, v1
	v_cvt_pk_f16_f32 v3, v34, v35
	v_cvt_pk_f16_f32 v2, v24, v25
	global_store_dwordx4 v[26:27], v[6:9], off
	global_store_dwordx4 v[28:29], v[2:5], off
	s_and_saveexec_b64 s[16:17], s[6:7]
	s_cbranch_execz .LBB0_855
	v_lshl_add_u32 v136, v16, 4, s18
	s_waitcnt lgkmcnt(0)
	v_add_f32_e32 v2, v0, v1
	v_lshl_add_u64 v[0:1], v[136:137], 2, s[42:43]
	global_store_dword v[0:1], v2, off
	s_branch .LBB0_855

; #define PG8_STAGE(bufoff, gbase, voff) do { _Pragma("unroll") for (int _i = 0; _i < 2; ++_i) \
;         __builtin_amdgcn_global_load_lds((const unsigned*)((const char*)(gbase) + (voff)[_i]), (PG8_LAS unsigned*)(lds + (bufoff) + ldsw + _i * 8192), 16, 0, 0); } while (0)
; #define PG8_LDA(dst, b, h) do { _Pragma("unroll") for (int m = 0; m < 4; ++m) _Pragma("unroll") for (int k = 0; k < 2; ++k) dst[m][k] = *(const PG8_LAS bf16x8*)(lds + PG8_SA(b, h) + aoff + m * 2048 + k * 1024); } while (0)
; #define PG8_LDB(dst, b, h) do { _Pragma("unroll") for (int n = 0; n < 2; ++n) _Pragma("unroll") for (int k = 0; k < 2; ++k) dst[n][k] = *(const PG8_LAS bf16x8*)(lds + PG8_SB(b, h) + boff + n * 2048 + k * 1024); } while (0)
; #define PG8_MMA(ai, bj, At, Bt) do { __builtin_amdgcn_s_setprio(1); _Pragma("unroll") for (int m = 0; m < 4; ++m) _Pragma("unroll") for (int n = 0; n < 2; ++n) _Pragma("unroll") for (int k = 0; k < 2; ++k) \
;         acc[ai][bj][m][n] = mma16<F16>(Bt[n][k], At[m][k], acc[ai][bj][m][n]); __builtin_amdgcn_s_setprio(0); } while (0)
; #define PG8_WAIT_V(n) asm volatile("s_waitcnt vmcnt(" #n ")" ::: "memory")
; #define PG8_WAIT_L(n) asm volatile("s_waitcnt lgkmcnt(" #n ")" ::: "memory")
; #define PG8_BAR __builtin_amdgcn_s_barrier()
; #define PG8_SCHED __builtin_amdgcn_sched_barrier(0)
; template <class Epi, class Sched, bool ALIGN_EPI = false, bool SP2 = false, bool F16 = false, bool TOKPERM = false>
; __device__ __forceinline__ void gemm_phase(PG8_LAS unsigned char* lds, const Gemm g, const Sched& S, const Epi& E, int wv) {
;     ...
;             PG8_LDB(B0, 0, 0); PG8_LDB(B1, 0, 1); PG8_SCHED; PG8_LDA(At, 0, 0); PG8_STAGE(PG8_SA(1, 1), a1 + hstep, voffA);
;             PG8_WAIT_V(8); PG8_WAIT_L(0); PG8_BAR; PG8_MMA(0, 0, At, B0); PG8_MMA(0, 1, At, B1); PG8_BAR; PG8_SCHED;
;             PG8_LDA(At, 0, 1); PG8_STAGE(PG8_SB(0, 0), b2, voffB); PG8_STAGE(PG8_SB(0, 1), b2 + hstep, voffB); PG8_STAGE(PG8_SA(0, 0), a2, voffA);
;             PG8_WAIT_V(8); PG8_WAIT_L(0); PG8_BAR; PG8_MMA(1, 0, At, B0); PG8_MMA(1, 1, At, B1); PG8_BAR; PG8_SCHED;
.LBB0_1524:
	ds_read_b128 v[166:169], v149
	ds_read_b128 v[170:173], v150
	ds_read_b128 v[174:177], v151
	ds_read_b128 v[178:181], v152
	ds_read_b128 v[182:185], v153
	ds_read_b128 v[186:189], v154
	ds_read_b128 v[190:193], v155
	ds_read_b128 v[194:197], v156
	s_add_u32 s44, s24, 0xfffc0080
	s_addc_u32 s45, s25, -1
	s_cmp_eq_u32 s65, 12
	s_cselect_b32 s47, s15, s45
	s_cselect_b32 s46, s21, s44
	s_cselect_b32 s45, s13, s64
	s_cselect_b32 s44, s62, s63
	s_mov_b32 m0, s60
	v_lshl_add_u64 v[232:233], s[24:25], 0, v[138:139]
	ds_read_b128 v[198:201], v147
	ds_read_b128 v[202:205], v147 offset:1024
	ds_read_b128 v[206:209], v147 offset:2048
	ds_read_b128 v[210:213], v147 offset:3072
	ds_read_b128 v[214:217], v147 offset:4096
	ds_read_b128 v[218:221], v147 offset:5120
	ds_read_b128 v[222:225], v147 offset:6144
	ds_read_b128 v[228:231], v147 offset:7168
	global_load_lds_dwordx4 v[232:233], off
	v_lshl_add_u64 v[232:233], s[24:25], 0, v[140:141]
	s_mov_b32 m0, s61
	s_nop 0
	global_load_lds_dwordx4 v[232:233], off
	s_waitcnt vmcnt(8)
	s_waitcnt lgkmcnt(0)
	s_barrier
	s_setprio 1
	s_waitcnt lgkmcnt(0)
	v_mfma_f32_16x16x32_bf16 v[124:127], v[166:169], v[198:201], v[124:127]
	v_mfma_f32_16x16x32_bf16 v[120:123], v[174:177], v[198:201], v[120:123]
	v_mfma_f32_16x16x32_bf16 v[108:111], v[166:169], v[206:209], v[108:111]
	v_mfma_f32_16x16x32_bf16 v[104:107], v[174:177], v[206:209], v[104:107]
	v_mfma_f32_16x16x32_bf16 v[92:95], v[166:169], v[214:217], v[92:95]
	v_mfma_f32_16x16x32_bf16 v[88:91], v[174:177], v[214:217], v[88:91]
	v_mfma_f32_16x16x32_bf16 v[76:79], v[166:169], v[222:225], v[76:79]
	v_mfma_f32_16x16x32_bf16 v[72:75], v[174:177], v[222:225], v[72:75]
	v_mfma_f32_16x16x32_bf16 v[124:127], v[170:173], v[202:205], v[124:127]
	v_mfma_f32_16x16x32_bf16 v[120:123], v[178:181], v[202:205], v[120:123]
	v_mfma_f32_16x16x32_bf16 v[108:111], v[170:173], v[210:213], v[108:111]
	v_mfma_f32_16x16x32_bf16 v[104:107], v[178:181], v[210:213], v[104:107]
	v_mfma_f32_16x16x32_bf16 v[92:95], v[170:173], v[218:221], v[92:95]
	v_mfma_f32_16x16x32_bf16 v[88:91], v[178:181], v[218:221], v[88:91]
	v_mfma_f32_16x16x32_bf16 v[76:79], v[170:173], v[228:231], v[76:79]
	v_mfma_f32_16x16x32_bf16 v[72:75], v[178:181], v[228:231], v[72:75]
	s_setprio 0
	s_setprio 1
	v_mfma_f32_16x16x32_bf16 v[116:119], v[182:185], v[198:201], v[116:119]
	v_mfma_f32_16x16x32_bf16 v[112:115], v[190:193], v[198:201], v[112:115]
	v_mfma_f32_16x16x32_bf16 v[100:103], v[182:185], v[206:209], v[100:103]
	v_mfma_f32_16x16x32_bf16 v[96:99], v[190:193], v[206:209], v[96:99]
	v_mfma_f32_16x16x32_bf16 v[84:87], v[182:185], v[214:217], v[84:87]
	v_mfma_f32_16x16x32_bf16 v[80:83], v[190:193], v[214:217], v[80:83]
	v_mfma_f32_16x16x32_bf16 v[68:71], v[182:185], v[222:225], v[68:71]
	v_mfma_f32_16x16x32_bf16 v[64:67], v[190:193], v[222:225], v[64:67]
	v_mfma_f32_16x16x32_bf16 v[116:119], v[186:189], v[202:205], v[116:119]
	v_mfma_f32_16x16x32_bf16 v[112:115], v[194:197], v[202:205], v[112:115]
	v_mfma_f32_16x16x32_bf16 v[100:103], v[186:189], v[210:213], v[100:103]
	v_mfma_f32_16x16x32_bf16 v[96:99], v[194:197], v[210:213], v[96:99]
	v_mfma_f32_16x16x32_bf16 v[84:87], v[186:189], v[218:221], v[84:87]
	v_mfma_f32_16x16x32_bf16 v[80:83], v[194:197], v[218:221], v[80:83]
	v_mfma_f32_16x16x32_bf16 v[68:71], v[186:189], v[228:231], v[68:71]
	v_mfma_f32_16x16x32_bf16 v[64:67], v[194:197], v[228:231], v[64:67]
	s_setprio 0
	s_barrier
	s_mov_b32 m0, s4
	v_lshl_add_u64 v[232:233], s[44:45], 0, v[130:131]
	s_add_u32 s66, s44, 0x40000
	ds_read_b128 v[198:201], v147 offset:16384
	ds_read_b128 v[202:205], v147 offset:17408
	ds_read_b128 v[206:209], v147 offset:18432
	ds_read_b128 v[210:213], v147 offset:19456
	ds_read_b128 v[214:217], v147 offset:20480
	ds_read_b128 v[218:221], v147 offset:21504
	ds_read_b128 v[222:225], v147 offset:22528
	ds_read_b128 v[228:231], v147 offset:23552
	global_load_lds_dwordx4 v[232:233], off
	v_lshl_add_u64 v[234:235], s[44:45], 0, v[134:135]
	s_mov_b32 m0, s5
	s_addc_u32 s67, s45, 0
	global_load_lds_dwordx4 v[234:235], off
	v_lshl_add_u64 v[236:237], s[66:67], 0, v[130:131]
	s_mov_b32 m0, s23
	v_lshl_add_u64 v[238:239], s[46:47], 0, v[132:133]
	global_load_lds_dwordx4 v[236:237], off
	v_lshl_add_u64 v[236:237], s[66:67], 0, v[134:135]
	s_mov_b32 m0, s33
	s_nop 0
	global_load_lds_dwordx4 v[236:237], off
	v_lshl_add_u64 v[236:237], s[46:47], 0, v[128:129]
	s_mov_b32 m0, s3
	s_nop 0
	global_load_lds_dwordx4 v[236:237], off
	s_mov_b32 m0, s36
	s_nop 0
	global_load_lds_dwordx4 v[238:239], off
	s_waitcnt vmcnt(8)
	s_waitcnt lgkmcnt(0)
	s_barrier
; #define PG8_STAGE(bufoff, gbase, voff) do { _Pragma("unroll") for (int _i = 0; _i < 2; ++_i) \
;         __builtin_amdgcn_global_load_lds((const unsigned*)((const char*)(gbase) + (voff)[_i]), (PG8_LAS unsigned*)(lds + (bufoff) + ldsw + _i * 8192), 16, 0, 0); } while (0)
; #define PG8_LDA(dst, b, h) do { _Pragma("unroll") for (int m = 0; m < 4; ++m) _Pragma("unroll") for (int k = 0; k < 2; ++k) dst[m][k] = *(const PG8_LAS bf16x8*)(lds + PG8_SA(b, h) + aoff + m * 2048 + k * 1024); } while (0)
; #define PG8_LDB(dst, b, h) do { _Pragma("unroll") for (int n = 0; n < 2; ++n) _Pragma("unroll") for (int k = 0; k < 2; ++k) dst[n][k] = *(const PG8_LAS bf16x8*)(lds + PG8_SB(b, h) + boff + n * 2048 + k * 1024); } while (0)
; #define PG8_MMA(ai, bj, At, Bt) do { __builtin_amdgcn_s_setprio(1); _Pragma("unroll") for (int m = 0; m < 4; ++m) _Pragma("unroll") for (int n = 0; n < 2; ++n) _Pragma("unroll") for (int k = 0; k < 2; ++k) \
;         acc[ai][bj][m][n] = mma16<F16>(Bt[n][k], At[m][k], acc[ai][bj][m][n]); __builtin_amdgcn_s_setprio(0); } while (0)
; #define PG8_WAIT_V(n) asm volatile("s_waitcnt vmcnt(" #n ")" ::: "memory")
; #define PG8_WAIT_L(n) asm volatile("s_waitcnt lgkmcnt(" #n ")" ::: "memory")
; #define PG8_BAR __builtin_amdgcn_s_barrier()
; #define PG8_SCHED __builtin_amdgcn_sched_barrier(0)
; template <class Epi, class Sched, bool ALIGN_EPI = false, bool SP2 = false, bool F16 = false, bool TOKPERM = false>
; __device__ __forceinline__ void gemm_phase(PG8_LAS unsigned char* lds, const Gemm g, const Sched& S, const Epi& E, int wv) {
;     ...
;             PG8_WAIT_V(8); PG8_WAIT_L(0); PG8_BAR; PG8_MMA(1, 0, At, B0); PG8_MMA(1, 1, At, B1); PG8_BAR; PG8_SCHED;
;             PG8_LDB(B0, 1, 0); PG8_LDB(B1, 1, 1); PG8_SCHED; PG8_LDA(At, 1, 0); PG8_STAGE(PG8_SA(0, 1), a2 + hstep, voffA);
;             PG8_WAIT_V(8); PG8_WAIT_L(0); PG8_BAR; PG8_MMA(0, 0, At, B0); PG8_MMA(0, 1, At, B1); PG8_BAR; PG8_SCHED;
	s_setprio 1
	s_waitcnt lgkmcnt(0)
	v_mfma_f32_16x16x32_bf16 v[60:63], v[166:169], v[198:201], v[60:63]
	v_mfma_f32_16x16x32_bf16 v[56:59], v[174:177], v[198:201], v[56:59]
	v_mfma_f32_16x16x32_bf16 v[44:47], v[166:169], v[206:209], v[44:47]
	v_mfma_f32_16x16x32_bf16 v[40:43], v[174:177], v[206:209], v[40:43]
	v_mfma_f32_16x16x32_bf16 v[28:31], v[166:169], v[214:217], v[28:31]
	v_mfma_f32_16x16x32_bf16 v[24:27], v[174:177], v[214:217], v[24:27]
	v_mfma_f32_16x16x32_bf16 v[12:15], v[166:169], v[222:225], v[12:15]
	v_mfma_f32_16x16x32_bf16 v[8:11], v[174:177], v[222:225], v[8:11]
	v_mfma_f32_16x16x32_bf16 v[60:63], v[170:173], v[202:205], v[60:63]
	v_mfma_f32_16x16x32_bf16 v[56:59], v[178:181], v[202:205], v[56:59]
	v_mfma_f32_16x16x32_bf16 v[44:47], v[170:173], v[210:213], v[44:47]
	v_mfma_f32_16x16x32_bf16 v[40:43], v[178:181], v[210:213], v[40:43]
	v_mfma_f32_16x16x32_bf16 v[28:31], v[170:173], v[218:221], v[28:31]
	v_mfma_f32_16x16x32_bf16 v[24:27], v[178:181], v[218:221], v[24:27]
	v_mfma_f32_16x16x32_bf16 v[12:15], v[170:173], v[228:231], v[12:15]
	v_mfma_f32_16x16x32_bf16 v[8:11], v[178:181], v[228:231], v[8:11]
	s_setprio 0
	s_setprio 1
	v_mfma_f32_16x16x32_bf16 v[52:55], v[182:185], v[198:201], v[52:55]
	v_mfma_f32_16x16x32_bf16 v[48:51], v[190:193], v[198:201], v[48:51]
	v_mfma_f32_16x16x32_bf16 v[36:39], v[182:185], v[206:209], v[36:39]
	v_mfma_f32_16x16x32_bf16 v[32:35], v[190:193], v[206:209], v[32:35]
	v_mfma_f32_16x16x32_bf16 v[20:23], v[182:185], v[214:217], v[20:23]
	v_mfma_f32_16x16x32_bf16 v[16:19], v[190:193], v[214:217], v[16:19]
	v_mfma_f32_16x16x32_bf16 v[4:7], v[182:185], v[222:225], v[4:7]
	v_mfma_f32_16x16x32_bf16 v[0:3], v[190:193], v[222:225], v[0:3]
	v_mfma_f32_16x16x32_bf16 v[52:55], v[186:189], v[202:205], v[52:55]
	v_mfma_f32_16x16x32_bf16 v[48:51], v[194:197], v[202:205], v[48:51]
	v_mfma_f32_16x16x32_bf16 v[36:39], v[186:189], v[210:213], v[36:39]
	v_mfma_f32_16x16x32_bf16 v[32:35], v[194:197], v[210:213], v[32:35]
	v_mfma_f32_16x16x32_bf16 v[20:23], v[186:189], v[218:221], v[20:23]
	v_mfma_f32_16x16x32_bf16 v[16:19], v[194:197], v[218:221], v[16:19]
	v_mfma_f32_16x16x32_bf16 v[4:7], v[186:189], v[228:231], v[4:7]
	v_mfma_f32_16x16x32_bf16 v[0:3], v[194:197], v[228:231], v[0:3]
	s_setprio 0
	s_barrier
	ds_read_b128 v[166:169], v157
	ds_read_b128 v[170:173], v158
	ds_read_b128 v[174:177], v159
	ds_read_b128 v[178:181], v160
	ds_read_b128 v[182:185], v161
	ds_read_b128 v[186:189], v162
	ds_read_b128 v[190:193], v163
	ds_read_b128 v[194:197], v164
	s_add_u32 s46, s46, 0x40000
	s_addc_u32 s47, s47, 0
	s_mov_b32 m0, s37
	v_lshl_add_u64 v[240:241], s[46:47], 0, v[128:129]
	ds_read_b128 v[198:201], v147 offset:32768
	ds_read_b128 v[202:205], v147 offset:33792
	ds_read_b128 v[206:209], v147 offset:34816
	ds_read_b128 v[210:213], v147 offset:35840
	ds_read_b128 v[214:217], v147 offset:36864
	ds_read_b128 v[218:221], v147 offset:37888
	ds_read_b128 v[222:225], v147 offset:38912
	ds_read_b128 v[228:231], v147 offset:39936
	global_load_lds_dwordx4 v[240:241], off
	v_lshl_add_u64 v[240:241], s[46:47], 0, v[132:133]
	s_mov_b32 m0, s48
	s_nop 0
	global_load_lds_dwordx4 v[240:241], off
	s_waitcnt vmcnt(8)
	s_waitcnt lgkmcnt(0)
	s_barrier
	s_setprio 1
	s_waitcnt lgkmcnt(0)
	v_mfma_f32_16x16x32_bf16 v[124:127], v[166:169], v[198:201], v[124:127]
	v_mfma_f32_16x16x32_bf16 v[120:123], v[174:177], v[198:201], v[120:123]
	v_mfma_f32_16x16x32_bf16 v[108:111], v[166:169], v[206:209], v[108:111]
	v_mfma_f32_16x16x32_bf16 v[104:107], v[174:177], v[206:209], v[104:107]
	v_mfma_f32_16x16x32_bf16 v[92:95], v[166:169], v[214:217], v[92:95]
	v_mfma_f32_16x16x32_bf16 v[88:91], v[174:177], v[214:217], v[88:91]
	v_mfma_f32_16x16x32_bf16 v[76:79], v[166:169], v[222:225], v[76:79]
	v_mfma_f32_16x16x32_bf16 v[72:75], v[174:177], v[222:225], v[72:75]
	v_mfma_f32_16x16x32_bf16 v[124:127], v[170:173], v[202:205], v[124:127]
	v_mfma_f32_16x16x32_bf16 v[120:123], v[178:181], v[202:205], v[120:123]
	v_mfma_f32_16x16x32_bf16 v[108:111], v[170:173], v[210:213], v[108:111]
	v_mfma_f32_16x16x32_bf16 v[104:107], v[178:181], v[210:213], v[104:107]
	v_mfma_f32_16x16x32_bf16 v[92:95], v[170:173], v[218:221], v[92:95]
	v_mfma_f32_16x16x32_bf16 v[88:91], v[178:181], v[218:221], v[88:91]
	v_mfma_f32_16x16x32_bf16 v[76:79], v[170:173], v[228:231], v[76:79]
	v_mfma_f32_16x16x32_bf16 v[72:75], v[178:181], v[228:231], v[72:75]
	s_setprio 0
	s_setprio 1
	v_mfma_f32_16x16x32_bf16 v[116:119], v[182:185], v[198:201], v[116:119]
	v_mfma_f32_16x16x32_bf16 v[112:115], v[190:193], v[198:201], v[112:115]
	v_mfma_f32_16x16x32_bf16 v[100:103], v[182:185], v[206:209], v[100:103]
	v_mfma_f32_16x16x32_bf16 v[96:99], v[190:193], v[206:209], v[96:99]
	v_mfma_f32_16x16x32_bf16 v[84:87], v[182:185], v[214:217], v[84:87]
	v_mfma_f32_16x16x32_bf16 v[80:83], v[190:193], v[214:217], v[80:83]
	v_mfma_f32_16x16x32_bf16 v[68:71], v[182:185], v[222:225], v[68:71]
	v_mfma_f32_16x16x32_bf16 v[64:67], v[190:193], v[222:225], v[64:67]
	v_mfma_f32_16x16x32_bf16 v[116:119], v[186:189], v[202:205], v[116:119]
	v_mfma_f32_16x16x32_bf16 v[112:115], v[194:197], v[202:205], v[112:115]
	v_mfma_f32_16x16x32_bf16 v[100:103], v[186:189], v[210:213], v[100:103]
	v_mfma_f32_16x16x32_bf16 v[96:99], v[194:197], v[210:213], v[96:99]
	v_mfma_f32_16x16x32_bf16 v[84:87], v[186:189], v[218:221], v[84:87]
	v_mfma_f32_16x16x32_bf16 v[80:83], v[194:197], v[218:221], v[80:83]
	v_mfma_f32_16x16x32_bf16 v[68:71], v[186:189], v[228:231], v[68:71]
	v_mfma_f32_16x16x32_bf16 v[64:67], v[194:197], v[228:231], v[64:67]
	s_setprio 0
	s_barrier
; #define PG8_STAGE(bufoff, gbase, voff) do { _Pragma("unroll") for (int _i = 0; _i < 2; ++_i) \
;         __builtin_amdgcn_global_load_lds((const unsigned*)((const char*)(gbase) + (voff)[_i]), (PG8_LAS unsigned*)(lds + (bufoff) + ldsw + _i * 8192), 16, 0, 0); } while (0)
; #define PG8_LDA(dst, b, h) do { _Pragma("unroll") for (int m = 0; m < 4; ++m) _Pragma("unroll") for (int k = 0; k < 2; ++k) dst[m][k] = *(const PG8_LAS bf16x8*)(lds + PG8_SA(b, h) + aoff + m * 2048 + k * 1024); } while (0)
; #define PG8_MMA(ai, bj, At, Bt) do { __builtin_amdgcn_s_setprio(1); _Pragma("unroll") for (int m = 0; m < 4; ++m) _Pragma("unroll") for (int n = 0; n < 2; ++n) _Pragma("unroll") for (int k = 0; k < 2; ++k) \
;         acc[ai][bj][m][n] = mma16<F16>(Bt[n][k], At[m][k], acc[ai][bj][m][n]); __builtin_amdgcn_s_setprio(0); } while (0)
; #define PG8_WAIT_V(n) asm volatile("s_waitcnt vmcnt(" #n ")" ::: "memory")
; #define PG8_WAIT_L(n) asm volatile("s_waitcnt lgkmcnt(" #n ")" ::: "memory")
; #define PG8_BAR __builtin_amdgcn_s_barrier()
; #define PG8_SCHED __builtin_amdgcn_sched_barrier(0)
; template <class Epi, class Sched, bool ALIGN_EPI = false, bool SP2 = false, bool F16 = false, bool TOKPERM = false>
; __device__ __forceinline__ void gemm_phase(PG8_LAS unsigned char* lds, const Gemm g, const Sched& S, const Epi& E, int wv) {
;     ...
;             PG8_LDA(At, 1, 1); PG8_STAGE(PG8_SB(1, 0), b3, voffB); PG8_STAGE(PG8_SB(1, 1), b3 + hstep, voffB); PG8_STAGE(PG8_SA(1, 0), a3, voffA);
;             PG8_WAIT_V(8); PG8_WAIT_L(0); PG8_BAR; PG8_MMA(1, 0, At, B0); PG8_MMA(1, 1, At, B1); PG8_BAR; PG8_SCHED;
;   __device__ __forceinline__ void operator()(const pg8::f32x4 (&acc)[2][2][4][2], const pg8::Unit& u, int wr, int wc, int fr, int fq) const {
;     ...
;     const int row0 = u.pm * 256 + wr * 64 + fr + z, colb = u.pn * 256 + wc * 32 + 8 * fq + z;
; #pragma unroll
;     for (int ai = 0; ai < 2; ++ai)
; #pragma unroll
;       for (int m = 0; m < 4; ++m) {
;         const int tok = row0 + ai * 128 + m * 16; float ss = 0.f;
; #pragma unroll
;         for (int bj = 0; bj < 2; ++bj) {
;           const unsigned off = (unsigned)tok * DM + colb + 128 * bj;
;           f8_t n = __builtin_convertvector(*(const h8_t*)(x16 + off), f8_t);
	s_mov_b32 m0, s50
	v_lshl_add_u64 v[232:233], v[232:233], 0, s[10:11]
	s_add_u32 s44, s44, 0x40080
	ds_read_b128 v[198:201], v147 offset:49152
	ds_read_b128 v[202:205], v147 offset:50176
	ds_read_b128 v[206:209], v147 offset:51200
	ds_read_b128 v[210:213], v147 offset:52224
	ds_read_b128 v[214:217], v147 offset:53248
	ds_read_b128 v[218:221], v147 offset:54272
	ds_read_b128 v[222:225], v147 offset:55296
	ds_read_b128 v[228:231], v147 offset:56320
	global_load_lds_dwordx4 v[232:233], off
	v_lshl_add_u64 v[232:233], v[234:235], 0, s[10:11]
	s_mov_b32 m0, s51
	s_addc_u32 s45, s45, 0
	global_load_lds_dwordx4 v[232:233], off
	v_lshl_add_u64 v[232:233], s[44:45], 0, v[130:131]
	s_mov_b32 m0, s54
	s_nop 0
	global_load_lds_dwordx4 v[232:233], off
	v_lshl_add_u64 v[232:233], s[44:45], 0, v[134:135]
	s_mov_b32 m0, s55
	s_nop 0
	global_load_lds_dwordx4 v[232:233], off
	v_lshl_add_u64 v[232:233], v[236:237], 0, s[10:11]
	s_mov_b32 m0, s52
	s_nop 0
	global_load_lds_dwordx4 v[232:233], off
	v_lshl_add_u64 v[232:233], v[238:239], 0, s[10:11]
	s_mov_b32 m0, s53
	s_nop 0
	global_load_lds_dwordx4 v[232:233], off
	s_waitcnt vmcnt(8)
	s_waitcnt lgkmcnt(0)
	s_barrier
	s_setprio 1
	s_waitcnt lgkmcnt(0)
	v_mfma_f32_16x16x32_bf16 v[60:63], v[166:169], v[198:201], v[60:63]
	v_mfma_f32_16x16x32_bf16 v[56:59], v[174:177], v[198:201], v[56:59]
	v_mfma_f32_16x16x32_bf16 v[44:47], v[166:169], v[206:209], v[44:47]
	v_mfma_f32_16x16x32_bf16 v[40:43], v[174:177], v[206:209], v[40:43]
	v_mfma_f32_16x16x32_bf16 v[28:31], v[166:169], v[214:217], v[28:31]
	v_mfma_f32_16x16x32_bf16 v[24:27], v[174:177], v[214:217], v[24:27]
	v_mfma_f32_16x16x32_bf16 v[12:15], v[166:169], v[222:225], v[12:15]
	v_mfma_f32_16x16x32_bf16 v[8:11], v[174:177], v[222:225], v[8:11]
	v_mfma_f32_16x16x32_bf16 v[60:63], v[170:173], v[202:205], v[60:63]
	v_mfma_f32_16x16x32_bf16 v[56:59], v[178:181], v[202:205], v[56:59]
	v_mfma_f32_16x16x32_bf16 v[44:47], v[170:173], v[210:213], v[44:47]
	v_mfma_f32_16x16x32_bf16 v[40:43], v[178:181], v[210:213], v[40:43]
	v_mfma_f32_16x16x32_bf16 v[28:31], v[170:173], v[218:221], v[28:31]
	v_mfma_f32_16x16x32_bf16 v[24:27], v[178:181], v[218:221], v[24:27]
	v_mfma_f32_16x16x32_bf16 v[12:15], v[170:173], v[228:231], v[12:15]
	v_mfma_f32_16x16x32_bf16 v[8:11], v[178:181], v[228:231], v[8:11]
	s_setprio 0
	s_setprio 1
	v_mfma_f32_16x16x32_bf16 v[52:55], v[182:185], v[198:201], v[52:55]
	v_mfma_f32_16x16x32_bf16 v[48:51], v[190:193], v[198:201], v[48:51]
	v_mfma_f32_16x16x32_bf16 v[36:39], v[182:185], v[206:209], v[36:39]
	v_mfma_f32_16x16x32_bf16 v[32:35], v[190:193], v[206:209], v[32:35]
	v_mfma_f32_16x16x32_bf16 v[20:23], v[182:185], v[214:217], v[20:23]
	v_mfma_f32_16x16x32_bf16 v[16:19], v[190:193], v[214:217], v[16:19]
	v_mfma_f32_16x16x32_bf16 v[4:7], v[182:185], v[222:225], v[4:7]
	v_mfma_f32_16x16x32_bf16 v[0:3], v[190:193], v[222:225], v[0:3]
	v_mfma_f32_16x16x32_bf16 v[52:55], v[186:189], v[202:205], v[52:55]
	v_mfma_f32_16x16x32_bf16 v[48:51], v[194:197], v[202:205], v[48:51]
	v_mfma_f32_16x16x32_bf16 v[36:39], v[186:189], v[210:213], v[36:39]
	v_mfma_f32_16x16x32_bf16 v[32:35], v[194:197], v[210:213], v[32:35]
	v_mfma_f32_16x16x32_bf16 v[20:23], v[186:189], v[218:221], v[20:23]
	v_mfma_f32_16x16x32_bf16 v[16:19], v[194:197], v[218:221], v[16:19]
	v_mfma_f32_16x16x32_bf16 v[4:7], v[186:189], v[228:231], v[4:7]
	v_mfma_f32_16x16x32_bf16 v[0:3], v[194:197], v[228:231], v[0:3]
	s_setprio 0
	s_barrier
	s_add_i32 s65, s65, 2
	s_add_u32 s24, s24, 0x100
	s_addc_u32 s25, s25, 0
	s_add_u32 s63, s63, 0x100
	s_addc_u32 s64, s64, 0
	s_cmp_gt_u32 s65, 13
	s_cbranch_scc0 .LBB0_1524
	s_lshl_b32 s13, s22, 8
	v_lshl_or_b32 v166, s20, 8, v148
	v_mov_b32 v136, 0
	v_xor_b32_e32 v169, 32, v165
	v_add3_u32 v167, s13, v146, v136
	v_add_u32_e32 v168, v166, v136
	v_lshl_add_u32 v136, v167, 10, v168
	v_lshl_add_u64 v[178:179], v[136:137], 1, s[40:41]
	v_add_u32_e32 v136, 0x80, v136
	global_load_dwordx4 v[170:173], v[178:179], off
	v_lshl_add_u64 v[180:181], v[136:137], 1, s[40:41]
	global_load_dwordx4 v[174:177], v[180:181], off
	v_add_u32_e32 v136, 16, v167
	v_lshl_add_u32 v136, v136, 10, v168
	v_lshl_add_u64 v[224:225], v[136:137], 1, s[40:41]
	v_add_u32_e32 v136, 0x80, v136
	global_load_dwordx4 v[192:195], v[224:225], off
	v_lshl_add_u64 v[248:249], v[136:137], 1, s[40:41]
	global_load_dwordx4 v[196:199], v[248:249], off
	v_add_u32_e32 v136, 32, v167
	v_lshl_add_u32 v136, v136, 10, v168
	v_lshl_add_u64 v[224:225], v[136:137], 1, s[40:41]
	v_add_u32_e32 v136, 0x80, v136
	global_load_dwordx4 v[200:203], v[224:225], off
	v_lshl_add_u64 v[248:249], v[136:137], 1, s[40:41]
	global_load_dwordx4 v[204:207], v[248:249], off
	v_add_u32_e32 v136, 48, v167
	v_lshl_add_u32 v136, v136, 10, v168
	v_lshl_add_u64 v[224:225], v[136:137], 1, s[40:41]
	v_add_u32_e32 v136, 0x80, v136
	global_load_dwordx4 v[208:211], v[224:225], off
	v_lshl_add_u64 v[248:249], v[136:137], 1, s[40:41]
	global_load_dwordx4 v[212:215], v[248:249], off
	v_add_u32_e32 v136, 0x80, v167
	v_lshl_add_u32 v136, v136, 10, v168
	v_lshl_add_u64 v[224:225], v[136:137], 1, s[40:41]
	v_add_u32_e32 v136, 0x80, v136
	global_load_dwordx4 v[216:219], v[224:225], off
	v_lshl_add_u64 v[248:249], v[136:137], 1, s[40:41]
	global_load_dwordx4 v[220:223], v[248:249], off
	v_add_u32_e32 v136, 0x90, v167
	v_lshl_add_u32 v136, v136, 10, v168
	v_lshl_add_u64 v[224:225], v[136:137], 1, s[40:41]
	v_add_u32_e32 v136, 0x80, v136
	global_load_dwordx4 v[228:231], v[224:225], off
	v_lshl_add_u64 v[248:249], v[136:137], 1, s[40:41]
	global_load_dwordx4 v[244:247], v[248:249], off
	v_and_b32_e32 v166, 64, v165
	v_xor_b32_e32 v136, 16, v165
	v_add_u32_e32 v166, 64, v166
	v_cmp_lt_i32_e32 vcc, v136, v166
	s_lshl_b32 s13, s20, 2
	s_or_b32 s13, s13, s49
	v_cndmask_b32_e32 v136, v165, v136, vcc
	v_cmp_lt_i32_e32 vcc, v169, v166
	v_lshlrev_b32_e32 v166, 2, v136
	s_waitcnt vmcnt(10)
;   __device__ __forceinline__ void operator()(const pg8::f32x4 (&acc)[2][2][4][2], const pg8::Unit& u, int wr, int wc, int fr, int fq) const {
;     ...
;         const int tok = row0 + ai * 128 + m * 16; float ss = 0.f;
; #pragma unroll
;         for (int bj = 0; bj < 2; ++bj) {
;           const unsigned off = (unsigned)tok * DM + colb + 128 * bj;
;           f8_t n = __builtin_convertvector(*(const h8_t*)(x16 + off), f8_t);
; #pragma unroll
;           for (int c = 0; c < 4; ++c) { n[c] += sc * acc[ai][bj][m][0][c]; n[4 + c] += sc * acc[ai][bj][m][1][c]; }
;           if (aux) {
;             *(h8_t*)(x16 + off) = __builtin_convertvector(n, h8_t);
;             ss += ((n[0] * n[0] + n[1] * n[1]) + (n[2] * n[2] + n[3] * n[3])) + ((n[4] * n[4] + n[5] * n[5]) + (n[6] * n[6] + n[7] * n[7]));
;           } else {
;             *(f32x4*)(xout + off) = (f32x4){n[0], n[1], n[2], n[3]}; *(f32x4*)(xout + off + 4) = (f32x4){n[4], n[5], n[6], n[7]};
;           }
;         }
;         if (aux) { ss += __shfl_xor(ss, 16); ss += __shfl_xor(ss, 32); if (fq == 0) ssq[(unsigned)tok * 16 + u.pn * 4 + wc] = ss; }
	v_cvt_f32_f16_e32 v182, v173
	v_cvt_f32_f16_sdwa v183, v173 dst_sel:DWORD dst_unused:UNUSED_PAD src0_sel:WORD_1
	v_cvt_f32_f16_e32 v184, v171
	v_cvt_f32_f16_sdwa v185, v171 dst_sel:DWORD dst_unused:UNUSED_PAD src0_sel:WORD_1
	v_cvt_f32_f16_e32 v186, v172
	v_cvt_f32_f16_sdwa v187, v172 dst_sel:DWORD dst_unused:UNUSED_PAD src0_sel:WORD_1
	v_cvt_f32_f16_e32 v172, v170
	v_cvt_f32_f16_sdwa v173, v170 dst_sel:DWORD dst_unused:UNUSED_PAD src0_sel:WORD_1
	v_cvt_f32_f16_e32 v170, v177
	v_cvt_f32_f16_sdwa v171, v177 dst_sel:DWORD dst_unused:UNUSED_PAD src0_sel:WORD_1
	v_cvt_f32_f16_e32 v188, v175
	v_cvt_f32_f16_sdwa v189, v175 dst_sel:DWORD dst_unused:UNUSED_PAD src0_sel:WORD_1
	v_cvt_f32_f16_e32 v190, v176
	v_cvt_f32_f16_sdwa v191, v176 dst_sel:DWORD dst_unused:UNUSED_PAD src0_sel:WORD_1
	v_cvt_f32_f16_e32 v176, v174
	v_cvt_f32_f16_sdwa v177, v174 dst_sel:DWORD dst_unused:UNUSED_PAD src0_sel:WORD_1
	v_pk_add_f32 v[124:125], v[124:125], v[172:173]
	v_pk_add_f32 v[172:173], v[120:121], v[186:187]
	v_pk_add_f32 v[126:127], v[126:127], v[184:185]
	v_pk_add_f32 v[122:123], v[122:123], v[182:183]
	v_cvt_pk_f16_f32 v120, v172, v173
	v_cvt_pk_f16_f32 v121, v122, v123
	v_pk_mul_f32 v[174:175], v[124:125], v[124:125]
	v_pk_mul_f32 v[182:183], v[126:127], v[126:127]
	v_pk_mul_f32 v[172:173], v[172:173], v[172:173]
	v_pk_mul_f32 v[122:123], v[122:123], v[122:123]
	v_pk_add_f32 v[176:177], v[116:117], v[176:177]
	v_pk_add_f32 v[116:117], v[112:113], v[190:191]
	v_pk_add_f32 v[184:185], v[118:119], v[188:189]
	v_pk_add_f32 v[112:113], v[114:115], v[170:171]
	v_pk_mul_f32 v[114:115], v[176:177], v[176:177]
	v_pk_mul_f32 v[118:119], v[184:185], v[184:185]
	v_pk_mul_f32 v[170:171], v[116:117], v[116:117]
	v_pk_mul_f32 v[186:187], v[112:113], v[112:113]
	v_add_f32_e32 v122, v122, v123
	v_add_f32_e32 v123, v172, v173
	v_add_f32_e32 v136, v182, v183
	v_add_f32_e32 v172, v174, v175
	v_add_f32_e32 v122, v123, v122
	v_add_f32_e32 v123, v172, v136
	v_add_f32_e32 v136, v186, v187
	v_add_f32_e32 v170, v170, v171
	v_add_f32_e32 v118, v118, v119
	v_add_f32_e32 v114, v114, v115
	v_add_f32_e32 v119, v170, v136
	v_add_f32_e32 v114, v114, v118
	v_add_f32_e32 v115, v123, v122
	v_add_f32_e32 v114, v114, v119
	v_add_f32_e32 v114, v115, v114
	v_mov_b32_e32 v115, v114
	s_nop 1
	v_permlane16_swap_b32_e32 v114, v115
	v_cndmask_b32_e32 v169, v165, v169, vcc
	v_cvt_pk_f16_f32 v119, v126, v127
	v_cvt_pk_f16_f32 v118, v124, v125
	global_store_dwordx4 v[178:179], v[118:121], off
	s_nop 1
	v_cvt_pk_f16_f32 v119, v112, v113
	s_waitcnt lgkmcnt(0)
	v_add_f32_e32 v113, v114, v115
	v_lshlrev_b32_e32 v112, 2, v169
	v_mov_b32_e32 v114, v113
	s_nop 1
	v_permlane32_swap_b32_e32 v113, v114
	v_cvt_pk_f16_f32 v118, v116, v117
	v_cvt_pk_f16_f32 v117, v184, v185
	v_cvt_pk_f16_f32 v116, v176, v177
	global_store_dwordx4 v[180:181], v[116:119], off
	s_and_saveexec_b64 s[20:21], s[6:7]
	s_cbranch_execz .LBB0_1527
	v_lshl_add_u32 v136, v167, 4, s13
	s_waitcnt lgkmcnt(0)
	v_add_f32_e32 v113, v113, v114
	v_lshl_add_u64 v[114:115], v[136:137], 2, s[42:43]
	global_store_dword v[114:115], v113, off
.LBB0_1527:
	s_or_b64 exec, exec, s[20:21]
	v_add_u32_e32 v113, 16, v167
	v_lshl_add_u32 v136, v113, 10, v168
	v_lshl_add_u64 v[122:123], v[136:137], 1, s[40:41]
	v_add_u32_e32 v136, 0x80, v136
	v_lshl_add_u64 v[124:125], v[136:137], 1, s[40:41]
	s_waitcnt lgkmcnt(0)
	s_waitcnt vmcnt(10)
	v_cvt_f32_f16_e32 v126, v195
	v_cvt_f32_f16_sdwa v127, v195 dst_sel:DWORD dst_unused:UNUSED_PAD src0_sel:WORD_1
	v_cvt_f32_f16_e32 v170, v193
	v_cvt_f32_f16_sdwa v171, v193 dst_sel:DWORD dst_unused:UNUSED_PAD src0_sel:WORD_1
	v_cvt_f32_f16_e32 v172, v194
	v_cvt_f32_f16_sdwa v173, v194 dst_sel:DWORD dst_unused:UNUSED_PAD src0_sel:WORD_1
	v_cvt_f32_f16_e32 v116, v192
	v_cvt_f32_f16_sdwa v117, v192 dst_sel:DWORD dst_unused:UNUSED_PAD src0_sel:WORD_1
	v_cvt_f32_f16_e32 v114, v199
	v_cvt_f32_f16_sdwa v115, v199 dst_sel:DWORD dst_unused:UNUSED_PAD src0_sel:WORD_1
	v_cvt_f32_f16_e32 v174, v197
	v_cvt_f32_f16_sdwa v175, v197 dst_sel:DWORD dst_unused:UNUSED_PAD src0_sel:WORD_1
	v_cvt_f32_f16_e32 v176, v198
	v_cvt_f32_f16_sdwa v177, v198 dst_sel:DWORD dst_unused:UNUSED_PAD src0_sel:WORD_1
	v_cvt_f32_f16_e32 v120, v196
	v_cvt_f32_f16_sdwa v121, v196 dst_sel:DWORD dst_unused:UNUSED_PAD src0_sel:WORD_1
	v_pk_add_f32 v[108:109], v[108:109], v[116:117]
	v_pk_add_f32 v[116:117], v[104:105], v[172:173]
	v_pk_add_f32 v[110:111], v[110:111], v[170:171]
	v_pk_add_f32 v[106:107], v[106:107], v[126:127]
	v_pk_add_f32 v[120:121], v[100:101], v[120:121]
	v_pk_add_f32 v[170:171], v[96:97], v[176:177]
	v_pk_add_f32 v[172:173], v[102:103], v[174:175]
	v_pk_add_f32 v[96:97], v[98:99], v[114:115]
	v_cvt_pk_f16_f32 v105, v106, v107
	v_cvt_pk_f16_f32 v104, v116, v117
	v_pk_mul_f32 v[118:119], v[108:109], v[108:109]
	v_pk_mul_f32 v[126:127], v[110:111], v[110:111]
	v_pk_mul_f32 v[116:117], v[116:117], v[116:117]
	v_pk_mul_f32 v[106:107], v[106:107], v[106:107]
	v_pk_mul_f32 v[98:99], v[120:121], v[120:121]
	v_pk_mul_f32 v[100:101], v[172:173], v[172:173]
	v_pk_mul_f32 v[102:103], v[170:171], v[170:171]
	v_pk_mul_f32 v[114:115], v[96:97], v[96:97]
	v_add_f32_e32 v106, v106, v107
	v_add_f32_e32 v107, v116, v117
	v_add_f32_e32 v116, v126, v127
	v_add_f32_e32 v117, v118, v119
	v_add_f32_e32 v114, v114, v115
	v_add_f32_e32 v102, v102, v103
	v_add_f32_e32 v100, v100, v101
	v_add_f32_e32 v98, v98, v99
	v_add_f32_e32 v106, v107, v106
	v_add_f32_e32 v107, v117, v116
	v_add_f32_e32 v101, v102, v114
	v_add_f32_e32 v98, v98, v100
	v_add_f32_e32 v99, v107, v106
	v_add_f32_e32 v98, v98, v101
	v_add_f32_e32 v98, v99, v98
	v_mov_b32_e32 v99, v98
	s_nop 1
	v_permlane16_swap_b32_e32 v98, v99
	v_cvt_pk_f16_f32 v101, v96, v97
	v_cvt_pk_f16_f32 v103, v110, v111
	v_cvt_pk_f16_f32 v102, v108, v109
	v_cvt_pk_f16_f32 v100, v170, v171
	s_waitcnt lgkmcnt(0)
	v_add_f32_e32 v96, v98, v99
	v_mov_b32_e32 v97, v96
	s_nop 1
	v_permlane32_swap_b32_e32 v96, v97
	v_cvt_pk_f16_f32 v99, v172, v173
	v_cvt_pk_f16_f32 v98, v120, v121
	global_store_dwordx4 v[122:123], v[102:105], off
	global_store_dwordx4 v[124:125], v[98:101], off
	s_and_saveexec_b64 s[20:21], s[6:7]
	s_cbranch_execz .LBB0_1529
	v_lshl_add_u32 v136, v113, 4, s13
	s_waitcnt lgkmcnt(0)
	v_add_f32_e32 v98, v96, v97
	v_lshl_add_u64 v[96:97], v[136:137], 2, s[42:43]
	global_store_dword v[96:97], v98, off
;   __device__ __forceinline__ void operator()(const pg8::f32x4 (&acc)[2][2][4][2], const pg8::Unit& u, int wr, int wc, int fr, int fq) const {
;     ...
;         const int tok = row0 + ai * 128 + m * 16; float ss = 0.f;
; #pragma unroll
;         for (int bj = 0; bj < 2; ++bj) {
;           const unsigned off = (unsigned)tok * DM + colb + 128 * bj;
;           f8_t n = __builtin_convertvector(*(const h8_t*)(x16 + off), f8_t);
; #pragma unroll
;           for (int c = 0; c < 4; ++c) { n[c] += sc * acc[ai][bj][m][0][c]; n[4 + c] += sc * acc[ai][bj][m][1][c]; }
;           if (aux) {
;             *(h8_t*)(x16 + off) = __builtin_convertvector(n, h8_t);
;             ss += ((n[0] * n[0] + n[1] * n[1]) + (n[2] * n[2] + n[3] * n[3])) + ((n[4] * n[4] + n[5] * n[5]) + (n[6] * n[6] + n[7] * n[7]));
;           } else {
;             *(f32x4*)(xout + off) = (f32x4){n[0], n[1], n[2], n[3]}; *(f32x4*)(xout + off + 4) = (f32x4){n[4], n[5], n[6], n[7]};
;           }
;         }
;         if (aux) { ss += __shfl_xor(ss, 16); ss += __shfl_xor(ss, 32); if (fq == 0) ssq[(unsigned)tok * 16 + u.pn * 4 + wc] = ss; }
.LBB0_1529:
	s_or_b64 exec, exec, s[20:21]
	v_add_u32_e32 v96, 32, v167
	v_lshl_add_u32 v136, v96, 10, v168
	v_lshl_add_u64 v[106:107], v[136:137], 1, s[40:41]
	v_add_u32_e32 v136, 0x80, v136
	v_lshl_add_u64 v[108:109], v[136:137], 1, s[40:41]
	s_waitcnt vmcnt(10)
	v_cvt_f32_f16_e32 v110, v203
	v_cvt_f32_f16_sdwa v111, v203 dst_sel:DWORD dst_unused:UNUSED_PAD src0_sel:WORD_1
	v_cvt_f32_f16_e32 v114, v201
	v_cvt_f32_f16_sdwa v115, v201 dst_sel:DWORD dst_unused:UNUSED_PAD src0_sel:WORD_1
	v_cvt_f32_f16_e32 v116, v202
	v_cvt_f32_f16_sdwa v117, v202 dst_sel:DWORD dst_unused:UNUSED_PAD src0_sel:WORD_1
	v_cvt_f32_f16_e32 v100, v200
	v_cvt_f32_f16_sdwa v101, v200 dst_sel:DWORD dst_unused:UNUSED_PAD src0_sel:WORD_1
	v_cvt_f32_f16_e32 v98, v207
	v_cvt_f32_f16_sdwa v99, v207 dst_sel:DWORD dst_unused:UNUSED_PAD src0_sel:WORD_1
	v_cvt_f32_f16_e32 v118, v205
	v_cvt_f32_f16_sdwa v119, v205 dst_sel:DWORD dst_unused:UNUSED_PAD src0_sel:WORD_1
	v_cvt_f32_f16_e32 v120, v206
	v_cvt_f32_f16_sdwa v121, v206 dst_sel:DWORD dst_unused:UNUSED_PAD src0_sel:WORD_1
	v_cvt_f32_f16_e32 v104, v204
	v_cvt_f32_f16_sdwa v105, v204 dst_sel:DWORD dst_unused:UNUSED_PAD src0_sel:WORD_1
	v_pk_add_f32 v[92:93], v[92:93], v[100:101]
	v_pk_add_f32 v[100:101], v[88:89], v[116:117]
	v_pk_add_f32 v[94:95], v[94:95], v[114:115]
	v_pk_add_f32 v[90:91], v[90:91], v[110:111]
	v_cvt_pk_f16_f32 v88, v100, v101
	v_cvt_pk_f16_f32 v89, v90, v91
	v_pk_mul_f32 v[102:103], v[92:93], v[92:93]
	v_pk_mul_f32 v[110:111], v[94:95], v[94:95]
	v_pk_mul_f32 v[100:101], v[100:101], v[100:101]
	v_pk_mul_f32 v[90:91], v[90:91], v[90:91]
	v_pk_add_f32 v[104:105], v[84:85], v[104:105]
	v_pk_add_f32 v[114:115], v[80:81], v[120:121]
	v_pk_add_f32 v[116:117], v[86:87], v[118:119]
	v_pk_add_f32 v[80:81], v[82:83], v[98:99]
	v_pk_mul_f32 v[82:83], v[104:105], v[104:105]
	v_pk_mul_f32 v[84:85], v[116:117], v[116:117]
	v_pk_mul_f32 v[86:87], v[114:115], v[114:115]
	v_pk_mul_f32 v[98:99], v[80:81], v[80:81]
	v_add_f32_e32 v90, v90, v91
	v_add_f32_e32 v91, v100, v101
	s_waitcnt lgkmcnt(0)
	v_add_f32_e32 v97, v110, v111
	v_add_f32_e32 v100, v102, v103
	v_add_f32_e32 v90, v91, v90
	v_add_f32_e32 v91, v100, v97
	v_add_f32_e32 v97, v98, v99
	v_add_f32_e32 v86, v86, v87
	v_add_f32_e32 v84, v84, v85
	v_add_f32_e32 v82, v82, v83
	v_add_f32_e32 v85, v86, v97
	v_add_f32_e32 v82, v82, v84
	v_add_f32_e32 v83, v91, v90
	v_add_f32_e32 v82, v82, v85
	v_add_f32_e32 v82, v83, v82
	v_mov_b32_e32 v83, v82
	s_nop 1
	v_permlane16_swap_b32_e32 v82, v83
	v_cvt_pk_f16_f32 v85, v80, v81
	v_cvt_pk_f16_f32 v87, v94, v95
	v_cvt_pk_f16_f32 v86, v92, v93
	v_cvt_pk_f16_f32 v84, v114, v115
	s_waitcnt lgkmcnt(0)
	v_add_f32_e32 v80, v82, v83
	v_mov_b32_e32 v81, v80
	s_nop 1
	v_permlane32_swap_b32_e32 v80, v81
	v_cvt_pk_f16_f32 v83, v116, v117
	v_cvt_pk_f16_f32 v82, v104, v105
	global_store_dwordx4 v[106:107], v[86:89], off
	global_store_dwordx4 v[108:109], v[82:85], off
	s_and_saveexec_b64 s[20:21], s[6:7]
	s_cbranch_execz .LBB0_1531
	v_lshl_add_u32 v136, v96, 4, s13
	s_waitcnt lgkmcnt(0)
	v_add_f32_e32 v82, v80, v81
	v_lshl_add_u64 v[80:81], v[136:137], 2, s[42:43]
	global_store_dword v[80:81], v82, off
.LBB0_1531:
	s_or_b64 exec, exec, s[20:21]
	v_add_u32_e32 v80, 48, v167
	v_lshl_add_u32 v136, v80, 10, v168
	v_lshl_add_u64 v[90:91], v[136:137], 1, s[40:41]
	v_add_u32_e32 v136, 0x80, v136
	v_lshl_add_u64 v[92:93], v[136:137], 1, s[40:41]
	s_waitcnt vmcnt(10)
	v_cvt_f32_f16_e32 v94, v211
	v_cvt_f32_f16_sdwa v95, v211 dst_sel:DWORD dst_unused:UNUSED_PAD src0_sel:WORD_1
	v_cvt_f32_f16_e32 v96, v209
	v_cvt_f32_f16_sdwa v97, v209 dst_sel:DWORD dst_unused:UNUSED_PAD src0_sel:WORD_1
	v_cvt_f32_f16_e32 v98, v210
	v_cvt_f32_f16_sdwa v99, v210 dst_sel:DWORD dst_unused:UNUSED_PAD src0_sel:WORD_1
	v_cvt_f32_f16_e32 v84, v208
	v_cvt_f32_f16_sdwa v85, v208 dst_sel:DWORD dst_unused:UNUSED_PAD src0_sel:WORD_1
	v_cvt_f32_f16_e32 v82, v215
	v_cvt_f32_f16_sdwa v83, v215 dst_sel:DWORD dst_unused:UNUSED_PAD src0_sel:WORD_1
	v_cvt_f32_f16_e32 v100, v213
	v_cvt_f32_f16_sdwa v101, v213 dst_sel:DWORD dst_unused:UNUSED_PAD src0_sel:WORD_1
	v_cvt_f32_f16_e32 v102, v214
	v_cvt_f32_f16_sdwa v103, v214 dst_sel:DWORD dst_unused:UNUSED_PAD src0_sel:WORD_1
	v_cvt_f32_f16_e32 v88, v212
	v_cvt_f32_f16_sdwa v89, v212 dst_sel:DWORD dst_unused:UNUSED_PAD src0_sel:WORD_1
	v_pk_add_f32 v[76:77], v[76:77], v[84:85]
	v_pk_add_f32 v[84:85], v[72:73], v[98:99]
	v_pk_add_f32 v[78:79], v[78:79], v[96:97]
	v_pk_add_f32 v[74:75], v[74:75], v[94:95]
	v_cvt_pk_f16_f32 v72, v84, v85
	v_cvt_pk_f16_f32 v73, v74, v75
	v_pk_mul_f32 v[86:87], v[76:77], v[76:77]
	v_pk_mul_f32 v[94:95], v[78:79], v[78:79]
	v_pk_mul_f32 v[84:85], v[84:85], v[84:85]
	v_pk_mul_f32 v[74:75], v[74:75], v[74:75]
	v_pk_add_f32 v[88:89], v[68:69], v[88:89]
	v_pk_add_f32 v[96:97], v[64:65], v[102:103]
	v_pk_add_f32 v[98:99], v[70:71], v[100:101]
	v_pk_add_f32 v[64:65], v[66:67], v[82:83]
	v_pk_mul_f32 v[66:67], v[88:89], v[88:89]
	v_pk_mul_f32 v[68:69], v[98:99], v[98:99]
	v_pk_mul_f32 v[70:71], v[96:97], v[96:97]
	v_pk_mul_f32 v[82:83], v[64:65], v[64:65]
	v_add_f32_e32 v74, v74, v75
	v_add_f32_e32 v75, v84, v85
	s_waitcnt lgkmcnt(0)
	v_add_f32_e32 v81, v94, v95
	v_add_f32_e32 v84, v86, v87
	v_add_f32_e32 v74, v75, v74
	v_add_f32_e32 v75, v84, v81
	v_add_f32_e32 v81, v82, v83
	v_add_f32_e32 v70, v70, v71
	v_add_f32_e32 v68, v68, v69
	v_add_f32_e32 v66, v66, v67
	v_add_f32_e32 v69, v70, v81
	v_add_f32_e32 v66, v66, v68
	v_add_f32_e32 v67, v75, v74
	v_add_f32_e32 v66, v66, v69
	v_add_f32_e32 v66, v67, v66
	v_mov_b32_e32 v67, v66
	s_nop 1
	v_permlane16_swap_b32_e32 v66, v67
	v_cvt_pk_f16_f32 v69, v64, v65
	v_cvt_pk_f16_f32 v71, v78, v79
	v_cvt_pk_f16_f32 v70, v76, v77
	v_cvt_pk_f16_f32 v68, v96, v97
	s_waitcnt lgkmcnt(0)
	v_add_f32_e32 v64, v66, v67
	v_mov_b32_e32 v65, v64
	s_nop 1
	v_permlane32_swap_b32_e32 v64, v65
	v_cvt_pk_f16_f32 v67, v98, v99
	v_cvt_pk_f16_f32 v66, v88, v89
	global_store_dwordx4 v[90:91], v[70:73], off
	global_store_dwordx4 v[92:93], v[66:69], off
	s_and_saveexec_b64 s[20:21], s[6:7]
	s_cbranch_execz .LBB0_1533
	v_lshl_add_u32 v136, v80, 4, s13
	s_waitcnt lgkmcnt(0)
	v_add_f32_e32 v66, v64, v65
	v_lshl_add_u64 v[64:65], v[136:137], 2, s[42:43]
	global_store_dword v[64:65], v66, off
;   __device__ __forceinline__ void operator()(const pg8::f32x4 (&acc)[2][2][4][2], const pg8::Unit& u, int wr, int wc, int fr, int fq) const {
;     ...
;         const int tok = row0 + ai * 128 + m * 16; float ss = 0.f;
; #pragma unroll
;         for (int bj = 0; bj < 2; ++bj) {
;           const unsigned off = (unsigned)tok * DM + colb + 128 * bj;
;           f8_t n = __builtin_convertvector(*(const h8_t*)(x16 + off), f8_t);
; #pragma unroll
;           for (int c = 0; c < 4; ++c) { n[c] += sc * acc[ai][bj][m][0][c]; n[4 + c] += sc * acc[ai][bj][m][1][c]; }
;           if (aux) {
;             *(h8_t*)(x16 + off) = __builtin_convertvector(n, h8_t);
;             ss += ((n[0] * n[0] + n[1] * n[1]) + (n[2] * n[2] + n[3] * n[3])) + ((n[4] * n[4] + n[5] * n[5]) + (n[6] * n[6] + n[7] * n[7]));
;           } else {
;             *(f32x4*)(xout + off) = (f32x4){n[0], n[1], n[2], n[3]}; *(f32x4*)(xout + off + 4) = (f32x4){n[4], n[5], n[6], n[7]};
;           }
;         }
;         if (aux) { ss += __shfl_xor(ss, 16); ss += __shfl_xor(ss, 32); if (fq == 0) ssq[(unsigned)tok * 16 + u.pn * 4 + wc] = ss; }
.LBB0_1533:
	s_or_b64 exec, exec, s[20:21]
	v_add_u32_e32 v64, 0x80, v167
	v_lshl_add_u32 v136, v64, 10, v168
	v_lshl_add_u64 v[74:75], v[136:137], 1, s[40:41]
	v_add_u32_e32 v136, 0x80, v136
	v_lshl_add_u64 v[76:77], v[136:137], 1, s[40:41]
	s_waitcnt vmcnt(10)
	v_cvt_f32_f16_e32 v78, v219
	v_cvt_f32_f16_sdwa v79, v219 dst_sel:DWORD dst_unused:UNUSED_PAD src0_sel:WORD_1
	v_cvt_f32_f16_e32 v80, v217
	v_cvt_f32_f16_sdwa v81, v217 dst_sel:DWORD dst_unused:UNUSED_PAD src0_sel:WORD_1
	v_cvt_f32_f16_e32 v82, v218
	v_cvt_f32_f16_sdwa v83, v218 dst_sel:DWORD dst_unused:UNUSED_PAD src0_sel:WORD_1
	v_cvt_f32_f16_e32 v68, v216
	v_cvt_f32_f16_sdwa v69, v216 dst_sel:DWORD dst_unused:UNUSED_PAD src0_sel:WORD_1
	v_cvt_f32_f16_e32 v66, v223
	v_cvt_f32_f16_sdwa v67, v223 dst_sel:DWORD dst_unused:UNUSED_PAD src0_sel:WORD_1
	v_cvt_f32_f16_e32 v84, v221
	v_cvt_f32_f16_sdwa v85, v221 dst_sel:DWORD dst_unused:UNUSED_PAD src0_sel:WORD_1
	v_cvt_f32_f16_e32 v86, v222
	v_cvt_f32_f16_sdwa v87, v222 dst_sel:DWORD dst_unused:UNUSED_PAD src0_sel:WORD_1
	v_cvt_f32_f16_e32 v72, v220
	v_cvt_f32_f16_sdwa v73, v220 dst_sel:DWORD dst_unused:UNUSED_PAD src0_sel:WORD_1
	v_pk_add_f32 v[60:61], v[60:61], v[68:69]
	v_pk_add_f32 v[68:69], v[56:57], v[82:83]
	v_pk_add_f32 v[62:63], v[62:63], v[80:81]
	v_pk_add_f32 v[58:59], v[58:59], v[78:79]
	v_cvt_pk_f16_f32 v56, v68, v69
	v_cvt_pk_f16_f32 v57, v58, v59
	v_pk_mul_f32 v[70:71], v[60:61], v[60:61]
	v_pk_mul_f32 v[78:79], v[62:63], v[62:63]
	v_pk_mul_f32 v[68:69], v[68:69], v[68:69]
	v_pk_mul_f32 v[58:59], v[58:59], v[58:59]
	v_pk_add_f32 v[72:73], v[52:53], v[72:73]
	v_pk_add_f32 v[80:81], v[48:49], v[86:87]
	v_pk_add_f32 v[82:83], v[54:55], v[84:85]
	v_pk_add_f32 v[48:49], v[50:51], v[66:67]
	v_pk_mul_f32 v[50:51], v[72:73], v[72:73]
	v_pk_mul_f32 v[52:53], v[82:83], v[82:83]
	v_pk_mul_f32 v[54:55], v[80:81], v[80:81]
	v_pk_mul_f32 v[66:67], v[48:49], v[48:49]
	v_add_f32_e32 v58, v58, v59
	v_add_f32_e32 v59, v68, v69
	s_waitcnt lgkmcnt(0)
	v_add_f32_e32 v65, v78, v79
	v_add_f32_e32 v68, v70, v71
	v_add_f32_e32 v58, v59, v58
	v_add_f32_e32 v59, v68, v65
	v_add_f32_e32 v65, v66, v67
	v_add_f32_e32 v54, v54, v55
	v_add_f32_e32 v52, v52, v53
	v_add_f32_e32 v50, v50, v51
	v_add_f32_e32 v53, v54, v65
	v_add_f32_e32 v50, v50, v52
	v_add_f32_e32 v51, v59, v58
	v_add_f32_e32 v50, v50, v53
	v_add_f32_e32 v50, v51, v50
	v_mov_b32_e32 v51, v50
	s_nop 1
	v_permlane16_swap_b32_e32 v50, v51
	v_cvt_pk_f16_f32 v53, v48, v49
	v_cvt_pk_f16_f32 v55, v62, v63
	v_cvt_pk_f16_f32 v54, v60, v61
	v_cvt_pk_f16_f32 v52, v80, v81
	s_waitcnt lgkmcnt(0)
	v_add_f32_e32 v48, v50, v51
	v_mov_b32_e32 v49, v48
	s_nop 1
	v_permlane32_swap_b32_e32 v48, v49
	v_cvt_pk_f16_f32 v51, v82, v83
	v_cvt_pk_f16_f32 v50, v72, v73
	global_store_dwordx4 v[74:75], v[54:57], off
	global_store_dwordx4 v[76:77], v[50:53], off
	s_and_saveexec_b64 s[20:21], s[6:7]
	s_cbranch_execz .LBB0_1535
	v_lshl_add_u32 v136, v64, 4, s13
	s_waitcnt lgkmcnt(0)
	v_add_f32_e32 v50, v48, v49
	v_lshl_add_u64 v[48:49], v[136:137], 2, s[42:43]
	global_store_dword v[48:49], v50, off
.LBB0_1535:
	s_or_b64 exec, exec, s[20:21]
	v_add_u32_e32 v48, 0x90, v167
	v_lshl_add_u32 v136, v48, 10, v168
	v_lshl_add_u64 v[58:59], v[136:137], 1, s[40:41]
	v_add_u32_e32 v136, 0x80, v136
	v_lshl_add_u64 v[60:61], v[136:137], 1, s[40:41]
	s_waitcnt vmcnt(10)
	v_cvt_f32_f16_e32 v62, v231
	v_cvt_f32_f16_sdwa v63, v231 dst_sel:DWORD dst_unused:UNUSED_PAD src0_sel:WORD_1
	v_cvt_f32_f16_e32 v64, v229
	v_cvt_f32_f16_sdwa v65, v229 dst_sel:DWORD dst_unused:UNUSED_PAD src0_sel:WORD_1
	v_cvt_f32_f16_e32 v66, v230
	v_cvt_f32_f16_sdwa v67, v230 dst_sel:DWORD dst_unused:UNUSED_PAD src0_sel:WORD_1
	v_cvt_f32_f16_e32 v52, v228
	v_cvt_f32_f16_sdwa v53, v228 dst_sel:DWORD dst_unused:UNUSED_PAD src0_sel:WORD_1
	v_cvt_f32_f16_e32 v50, v247
	v_cvt_f32_f16_sdwa v51, v247 dst_sel:DWORD dst_unused:UNUSED_PAD src0_sel:WORD_1
	v_cvt_f32_f16_e32 v68, v245
	v_cvt_f32_f16_sdwa v69, v245 dst_sel:DWORD dst_unused:UNUSED_PAD src0_sel:WORD_1
	v_cvt_f32_f16_e32 v70, v246
	v_cvt_f32_f16_sdwa v71, v246 dst_sel:DWORD dst_unused:UNUSED_PAD src0_sel:WORD_1
	v_cvt_f32_f16_e32 v56, v244
	v_cvt_f32_f16_sdwa v57, v244 dst_sel:DWORD dst_unused:UNUSED_PAD src0_sel:WORD_1
	v_pk_add_f32 v[44:45], v[44:45], v[52:53]
	v_pk_add_f32 v[52:53], v[40:41], v[66:67]
	v_pk_add_f32 v[46:47], v[46:47], v[64:65]
	v_pk_add_f32 v[42:43], v[42:43], v[62:63]
	v_cvt_pk_f16_f32 v40, v52, v53
	v_cvt_pk_f16_f32 v41, v42, v43
	v_pk_mul_f32 v[54:55], v[44:45], v[44:45]
	v_pk_mul_f32 v[62:63], v[46:47], v[46:47]
	v_pk_mul_f32 v[52:53], v[52:53], v[52:53]
	v_pk_mul_f32 v[42:43], v[42:43], v[42:43]
	v_pk_add_f32 v[56:57], v[36:37], v[56:57]
	v_pk_add_f32 v[64:65], v[32:33], v[70:71]
	v_pk_add_f32 v[66:67], v[38:39], v[68:69]
	v_pk_add_f32 v[32:33], v[34:35], v[50:51]
	v_pk_mul_f32 v[34:35], v[56:57], v[56:57]
	v_pk_mul_f32 v[36:37], v[66:67], v[66:67]
	v_pk_mul_f32 v[38:39], v[64:65], v[64:65]
	v_pk_mul_f32 v[50:51], v[32:33], v[32:33]
	v_add_f32_e32 v42, v42, v43
	v_add_f32_e32 v43, v52, v53
	s_waitcnt lgkmcnt(0)
	v_add_f32_e32 v49, v62, v63
	v_add_f32_e32 v52, v54, v55
	v_add_f32_e32 v42, v43, v42
	v_add_f32_e32 v43, v52, v49
	v_add_f32_e32 v49, v50, v51
	v_add_f32_e32 v38, v38, v39
	v_add_f32_e32 v36, v36, v37
	v_add_f32_e32 v34, v34, v35
	v_add_f32_e32 v37, v38, v49
	v_add_f32_e32 v34, v34, v36
	v_add_f32_e32 v35, v43, v42
	v_add_f32_e32 v34, v34, v37
	v_add_f32_e32 v34, v35, v34
	v_mov_b32_e32 v35, v34
	s_nop 1
	v_permlane16_swap_b32_e32 v34, v35
	v_cvt_pk_f16_f32 v37, v32, v33
	v_cvt_pk_f16_f32 v39, v46, v47
	v_cvt_pk_f16_f32 v38, v44, v45
	v_cvt_pk_f16_f32 v36, v64, v65
	s_waitcnt lgkmcnt(0)
	v_add_f32_e32 v32, v34, v35
	v_mov_b32_e32 v33, v32
	s_nop 1
	v_permlane32_swap_b32_e32 v32, v33
	v_cvt_pk_f16_f32 v35, v66, v67
	v_cvt_pk_f16_f32 v34, v56, v57
	global_store_dwordx4 v[58:59], v[38:41], off
	global_store_dwordx4 v[60:61], v[34:37], off
	s_and_saveexec_b64 s[20:21], s[6:7]
	s_cbranch_execz .LBB0_1537
	v_lshl_add_u32 v136, v48, 4, s13
	s_waitcnt lgkmcnt(0)
	v_add_f32_e32 v34, v32, v33
	v_lshl_add_u64 v[32:33], v[136:137], 2, s[42:43]
	global_store_dword v[32:33], v34, off
;   __device__ __forceinline__ void operator()(const pg8::f32x4 (&acc)[2][2][4][2], const pg8::Unit& u, int wr, int wc, int fr, int fq) const {
;     ...
;         const int tok = row0 + ai * 128 + m * 16; float ss = 0.f;
; #pragma unroll
;         for (int bj = 0; bj < 2; ++bj) {
;           const unsigned off = (unsigned)tok * DM + colb + 128 * bj;
;           f8_t n = __builtin_convertvector(*(const h8_t*)(x16 + off), f8_t);
; #pragma unroll
;           for (int c = 0; c < 4; ++c) { n[c] += sc * acc[ai][bj][m][0][c]; n[4 + c] += sc * acc[ai][bj][m][1][c]; }
;           if (aux) {
;             *(h8_t*)(x16 + off) = __builtin_convertvector(n, h8_t);
;             ss += ((n[0] * n[0] + n[1] * n[1]) + (n[2] * n[2] + n[3] * n[3])) + ((n[4] * n[4] + n[5] * n[5]) + (n[6] * n[6] + n[7] * n[7]));
;           } else {
;             *(f32x4*)(xout + off) = (f32x4){n[0], n[1], n[2], n[3]}; *(f32x4*)(xout + off + 4) = (f32x4){n[4], n[5], n[6], n[7]};
;           }
;         }
;         if (aux) { ss += __shfl_xor(ss, 16); ss += __shfl_xor(ss, 32); if (fq == 0) ssq[(unsigned)tok * 16 + u.pn * 4 + wc] = ss; }
.LBB0_1537:
	s_or_b64 exec, exec, s[20:21]
	v_add_u32_e32 v32, 0xa0, v167
	v_lshl_add_u32 v136, v32, 10, v168
	v_lshl_add_u64 v[42:43], v[136:137], 1, s[40:41]
	v_add_u32_e32 v136, 0x80, v136
	global_load_dwordx4 v[34:37], v[42:43], off
	v_lshl_add_u64 v[44:45], v[136:137], 1, s[40:41]
	global_load_dwordx4 v[38:41], v[44:45], off
	s_waitcnt vmcnt(1)
	v_cvt_f32_f16_e32 v46, v37
	v_cvt_f32_f16_sdwa v47, v37 dst_sel:DWORD dst_unused:UNUSED_PAD src0_sel:WORD_1
	v_cvt_f32_f16_e32 v48, v35
	v_cvt_f32_f16_sdwa v49, v35 dst_sel:DWORD dst_unused:UNUSED_PAD src0_sel:WORD_1
	v_cvt_f32_f16_e32 v50, v36
	v_cvt_f32_f16_sdwa v51, v36 dst_sel:DWORD dst_unused:UNUSED_PAD src0_sel:WORD_1
	v_cvt_f32_f16_e32 v36, v34
	v_cvt_f32_f16_sdwa v37, v34 dst_sel:DWORD dst_unused:UNUSED_PAD src0_sel:WORD_1
	s_waitcnt vmcnt(0)
	v_cvt_f32_f16_e32 v34, v41
	v_cvt_f32_f16_sdwa v35, v41 dst_sel:DWORD dst_unused:UNUSED_PAD src0_sel:WORD_1
	v_cvt_f32_f16_e32 v52, v39
	v_cvt_f32_f16_sdwa v53, v39 dst_sel:DWORD dst_unused:UNUSED_PAD src0_sel:WORD_1
	v_cvt_f32_f16_e32 v54, v40
	v_cvt_f32_f16_sdwa v55, v40 dst_sel:DWORD dst_unused:UNUSED_PAD src0_sel:WORD_1
	v_cvt_f32_f16_e32 v40, v38
	v_cvt_f32_f16_sdwa v41, v38 dst_sel:DWORD dst_unused:UNUSED_PAD src0_sel:WORD_1
	v_pk_add_f32 v[28:29], v[28:29], v[36:37]
	v_pk_add_f32 v[36:37], v[24:25], v[50:51]
	v_pk_add_f32 v[30:31], v[30:31], v[48:49]
	v_pk_add_f32 v[26:27], v[26:27], v[46:47]
	v_cvt_pk_f16_f32 v24, v36, v37
	v_cvt_pk_f16_f32 v25, v26, v27
	v_pk_mul_f32 v[38:39], v[28:29], v[28:29]
	v_pk_mul_f32 v[46:47], v[30:31], v[30:31]
	v_pk_mul_f32 v[36:37], v[36:37], v[36:37]
	v_pk_mul_f32 v[26:27], v[26:27], v[26:27]
	v_pk_add_f32 v[40:41], v[20:21], v[40:41]
	v_pk_add_f32 v[48:49], v[16:17], v[54:55]
	v_pk_add_f32 v[50:51], v[22:23], v[52:53]
	v_pk_add_f32 v[16:17], v[18:19], v[34:35]
	v_pk_mul_f32 v[18:19], v[40:41], v[40:41]
	v_pk_mul_f32 v[20:21], v[50:51], v[50:51]
	v_pk_mul_f32 v[22:23], v[48:49], v[48:49]
	v_pk_mul_f32 v[34:35], v[16:17], v[16:17]
	v_add_f32_e32 v26, v26, v27
	v_add_f32_e32 v27, v36, v37
	s_waitcnt lgkmcnt(0)
	v_add_f32_e32 v33, v46, v47
	v_add_f32_e32 v36, v38, v39
	v_add_f32_e32 v26, v27, v26
	v_add_f32_e32 v27, v36, v33
	v_add_f32_e32 v33, v34, v35
	v_add_f32_e32 v22, v22, v23
	v_add_f32_e32 v20, v20, v21
	v_add_f32_e32 v18, v18, v19
	v_add_f32_e32 v21, v22, v33
	v_add_f32_e32 v18, v18, v20
	v_add_f32_e32 v19, v27, v26
	v_add_f32_e32 v18, v18, v21
	v_add_f32_e32 v18, v19, v18
	v_mov_b32_e32 v19, v18
	s_nop 1
	v_permlane16_swap_b32_e32 v18, v19
	v_cvt_pk_f16_f32 v21, v16, v17
	v_cvt_pk_f16_f32 v23, v30, v31
	v_cvt_pk_f16_f32 v22, v28, v29
	v_cvt_pk_f16_f32 v20, v48, v49
	s_waitcnt lgkmcnt(0)
	v_add_f32_e32 v16, v18, v19
	v_mov_b32_e32 v17, v16
	s_nop 1
	v_permlane32_swap_b32_e32 v16, v17
	v_cvt_pk_f16_f32 v19, v50, v51
	v_cvt_pk_f16_f32 v18, v40, v41
	global_store_dwordx4 v[42:43], v[22:25], off
	global_store_dwordx4 v[44:45], v[18:21], off
	s_and_saveexec_b64 s[20:21], s[6:7]
	s_cbranch_execz .LBB0_1539
	v_lshl_add_u32 v136, v32, 4, s13
	s_waitcnt lgkmcnt(0)
	v_add_f32_e32 v18, v16, v17
	v_lshl_add_u64 v[16:17], v[136:137], 2, s[42:43]
	global_store_dword v[16:17], v18, off
.LBB0_1539:
	s_or_b64 exec, exec, s[20:21]
	v_add_u32_e32 v16, 0xb0, v167
	v_lshl_add_u32 v136, v16, 10, v168
	v_lshl_add_u64 v[26:27], v[136:137], 1, s[40:41]
	v_add_u32_e32 v136, 0x80, v136
	global_load_dwordx4 v[18:21], v[26:27], off
	v_lshl_add_u64 v[28:29], v[136:137], 1, s[40:41]
	global_load_dwordx4 v[22:25], v[28:29], off
	s_waitcnt vmcnt(1)
	v_cvt_f32_f16_e32 v30, v21
	v_cvt_f32_f16_sdwa v31, v21 dst_sel:DWORD dst_unused:UNUSED_PAD src0_sel:WORD_1
	v_cvt_f32_f16_e32 v32, v19
	v_cvt_f32_f16_sdwa v33, v19 dst_sel:DWORD dst_unused:UNUSED_PAD src0_sel:WORD_1
	v_cvt_f32_f16_e32 v34, v20
	v_cvt_f32_f16_sdwa v35, v20 dst_sel:DWORD dst_unused:UNUSED_PAD src0_sel:WORD_1
	v_cvt_f32_f16_e32 v20, v18
	v_cvt_f32_f16_sdwa v21, v18 dst_sel:DWORD dst_unused:UNUSED_PAD src0_sel:WORD_1
	s_waitcnt vmcnt(0)
	v_cvt_f32_f16_e32 v18, v25
	v_cvt_f32_f16_sdwa v19, v25 dst_sel:DWORD dst_unused:UNUSED_PAD src0_sel:WORD_1
	v_cvt_f32_f16_e32 v36, v23
	v_cvt_f32_f16_sdwa v37, v23 dst_sel:DWORD dst_unused:UNUSED_PAD src0_sel:WORD_1
	v_cvt_f32_f16_e32 v38, v24
	v_cvt_f32_f16_sdwa v39, v24 dst_sel:DWORD dst_unused:UNUSED_PAD src0_sel:WORD_1
	v_cvt_f32_f16_e32 v24, v22
	v_cvt_f32_f16_sdwa v25, v22 dst_sel:DWORD dst_unused:UNUSED_PAD src0_sel:WORD_1
	v_pk_add_f32 v[12:13], v[12:13], v[20:21]
	v_pk_add_f32 v[20:21], v[8:9], v[34:35]
	v_pk_add_f32 v[14:15], v[14:15], v[32:33]
	v_pk_add_f32 v[10:11], v[10:11], v[30:31]
	v_cvt_pk_f16_f32 v8, v20, v21
	v_cvt_pk_f16_f32 v9, v10, v11
	v_pk_mul_f32 v[22:23], v[12:13], v[12:13]
	v_pk_mul_f32 v[30:31], v[14:15], v[14:15]
	v_pk_mul_f32 v[20:21], v[20:21], v[20:21]
	v_pk_mul_f32 v[10:11], v[10:11], v[10:11]
	v_pk_add_f32 v[24:25], v[4:5], v[24:25]
	v_pk_add_f32 v[32:33], v[0:1], v[38:39]
	v_pk_add_f32 v[34:35], v[6:7], v[36:37]
	v_pk_add_f32 v[0:1], v[2:3], v[18:19]
	v_pk_mul_f32 v[2:3], v[24:25], v[24:25]
	v_pk_mul_f32 v[4:5], v[34:35], v[34:35]
	v_pk_mul_f32 v[6:7], v[32:33], v[32:33]
	v_pk_mul_f32 v[18:19], v[0:1], v[0:1]
	v_add_f32_e32 v10, v10, v11
	v_add_f32_e32 v11, v20, v21
	s_waitcnt lgkmcnt(0)
	v_add_f32_e32 v17, v30, v31
	v_add_f32_e32 v20, v22, v23
	v_add_f32_e32 v10, v11, v10
	v_add_f32_e32 v11, v20, v17
	v_add_f32_e32 v17, v18, v19
	v_add_f32_e32 v6, v6, v7
	v_add_f32_e32 v4, v4, v5
	v_add_f32_e32 v2, v2, v3
	v_add_f32_e32 v5, v6, v17
	v_add_f32_e32 v2, v2, v4
	v_add_f32_e32 v3, v11, v10
	v_add_f32_e32 v2, v2, v5
	v_add_f32_e32 v2, v3, v2
	v_mov_b32_e32 v3, v2
	s_nop 1
	v_permlane16_swap_b32_e32 v2, v3
	v_cvt_pk_f16_f32 v5, v0, v1
	v_cvt_pk_f16_f32 v7, v14, v15
	v_cvt_pk_f16_f32 v6, v12, v13
	v_cvt_pk_f16_f32 v4, v32, v33
	s_waitcnt lgkmcnt(0)
	v_add_f32_e32 v0, v2, v3
	v_mov_b32_e32 v1, v0
	s_nop 1
	v_permlane32_swap_b32_e32 v0, v1
	v_cvt_pk_f16_f32 v3, v34, v35
	v_cvt_pk_f16_f32 v2, v24, v25
	global_store_dwordx4 v[26:27], v[6:9], off
	global_store_dwordx4 v[28:29], v[2:5], off
	s_and_saveexec_b64 s[20:21], s[6:7]
	s_cbranch_execz .LBB0_1516
	v_lshl_add_u32 v136, v16, 4, s13
	s_waitcnt lgkmcnt(0)
	v_add_f32_e32 v2, v0, v1
	v_lshl_add_u64 v[0:1], v[136:137], 2, s[42:43]
	global_store_dword v[0:1], v2, off
	s_branch .LBB0_1516
